# DMA split 3+5+3+5 (3 pieces in the 16-read segments, 5 in the 8-read ones) + DMA-first load segments
# baseline (speedup 1.0000x reference)
.Lbal_first_21:
	s_add_u32 s26, s24, 0xfffc0080
	s_addc_u32 s27, s25, -1
	s_cmp_eq_u32 s55, 12
	s_cselect_b32 s29, s19, s27
	s_cselect_b32 s28, s51, s26
	s_cselect_b32 s27, s17, s54
	s_cselect_b32 s26, s52, s53
	s_add_i32 m0, s38, 0xc000
	s_nop 0
	global_load_lds_dwordx4 v138, s[24:25]
	s_add_i32 m0, s38, 0xe000
	s_nop 0
	global_load_lds_dwordx4 v136, s[24:25]
	ds_read_b128 v[144:147], v151
	ds_read_b128 v[156:159], v151 offset:1024
	ds_read_b128 v[160:163], v151 offset:2048
	ds_read_b128 v[164:167], v151 offset:3072
	ds_read_b128 v[168:171], v152
	ds_read_b128 v[172:175], v152 offset:1024
	ds_read_b128 v[176:179], v152 offset:2048
	ds_read_b128 v[180:183], v152 offset:3072
	ds_read_b128 v[184:187], v153
	ds_read_b128 v[188:191], v153 offset:1024
	ds_read_b128 v[192:195], v153 offset:2048
	ds_read_b128 v[196:199], v153 offset:3072
	ds_read_b128 v[200:203], v153 offset:4096
	ds_read_b128 v[208:211], v153 offset:5120
	ds_read_b128 v[212:215], v153 offset:6144
	ds_read_b128 v[216:219], v153 offset:7168
	s_waitcnt vmcnt(8)
	s_waitcnt lgkmcnt(0)
	s_barrier
	s_waitcnt lgkmcnt(0)
	v_mfma_f32_16x16x32_bf16 v[124:127], v[144:147], v[184:187], v[124:127]
	v_mfma_f32_16x16x32_bf16 v[120:123], v[160:163], v[184:187], v[120:123]
	v_mfma_f32_16x16x32_bf16 v[108:111], v[144:147], v[192:195], v[108:111]
	v_mfma_f32_16x16x32_bf16 v[104:107], v[160:163], v[192:195], v[104:107]
	v_mfma_f32_16x16x32_bf16 v[92:95], v[144:147], v[200:203], v[92:95]
	v_mfma_f32_16x16x32_bf16 v[88:91], v[160:163], v[200:203], v[88:91]
	v_mfma_f32_16x16x32_bf16 v[76:79], v[144:147], v[212:215], v[76:79]
	v_mfma_f32_16x16x32_bf16 v[72:75], v[160:163], v[212:215], v[72:75]
	v_mfma_f32_16x16x32_bf16 v[124:127], v[156:159], v[188:191], v[124:127]
	v_mfma_f32_16x16x32_bf16 v[120:123], v[164:167], v[188:191], v[120:123]
	v_mfma_f32_16x16x32_bf16 v[108:111], v[156:159], v[196:199], v[108:111]
	v_mfma_f32_16x16x32_bf16 v[104:107], v[164:167], v[196:199], v[104:107]
	v_mfma_f32_16x16x32_bf16 v[92:95], v[156:159], v[208:211], v[92:95]
	v_mfma_f32_16x16x32_bf16 v[88:91], v[164:167], v[208:211], v[88:91]
	v_mfma_f32_16x16x32_bf16 v[76:79], v[156:159], v[216:219], v[76:79]
	v_mfma_f32_16x16x32_bf16 v[72:75], v[164:167], v[216:219], v[72:75]
	v_mfma_f32_16x16x32_bf16 v[116:119], v[168:171], v[184:187], v[116:119]
	v_mfma_f32_16x16x32_bf16 v[112:115], v[176:179], v[184:187], v[112:115]
	v_mfma_f32_16x16x32_bf16 v[100:103], v[168:171], v[192:195], v[100:103]
	v_mfma_f32_16x16x32_bf16 v[96:99], v[176:179], v[192:195], v[96:99]
	v_mfma_f32_16x16x32_bf16 v[84:87], v[168:171], v[200:203], v[84:87]
	v_mfma_f32_16x16x32_bf16 v[80:83], v[176:179], v[200:203], v[80:83]
	v_mfma_f32_16x16x32_bf16 v[68:71], v[168:171], v[212:215], v[68:71]
	v_mfma_f32_16x16x32_bf16 v[64:67], v[176:179], v[212:215], v[64:67]
	v_mfma_f32_16x16x32_bf16 v[116:119], v[172:175], v[188:191], v[116:119]
	v_mfma_f32_16x16x32_bf16 v[112:115], v[180:183], v[188:191], v[112:115]
	v_mfma_f32_16x16x32_bf16 v[100:103], v[172:175], v[196:199], v[100:103]
	v_mfma_f32_16x16x32_bf16 v[96:99], v[180:183], v[196:199], v[96:99]
	v_mfma_f32_16x16x32_bf16 v[84:87], v[172:175], v[208:211], v[84:87]
	v_mfma_f32_16x16x32_bf16 v[80:83], v[180:183], v[208:211], v[80:83]
	v_mfma_f32_16x16x32_bf16 v[68:71], v[172:175], v[216:219], v[68:71]
	v_mfma_f32_16x16x32_bf16 v[64:67], v[180:183], v[216:219], v[64:67]
	s_barrier
	s_add_i32 s56, s48, s35
	s_mov_b32 m0, s56
	s_nop 0
	global_load_lds_dwordx4 v132, s[26:27]
	s_add_i32 m0, s56, 0x2000
	s_add_u32 s56, s26, 0x40000
	s_mov_b64 s[98:99], s[26:27]
	s_addc_u32 s57, s27, 0
	s_add_i32 s58, s49, s35
	global_load_lds_dwordx4 v128, s[26:27]
	s_mov_b32 m0, s58
	s_mov_b64 s[100:101], s[28:29]
	global_load_lds_dwordx4 v132, s[56:57]
	s_add_i32 m0, s58, 0x2000
	s_nop 0
	global_load_lds_dwordx4 v128, s[56:57]
	s_mov_b32 m0, s38
	s_nop 0
	global_load_lds_dwordx4 v134, s[28:29]
	ds_read_b128 v[184:187], v153 offset:16384
	ds_read_b128 v[188:191], v153 offset:17408
	ds_read_b128 v[192:195], v153 offset:18432
	ds_read_b128 v[196:199], v153 offset:19456
	ds_read_b128 v[200:203], v153 offset:20480
	ds_read_b128 v[208:211], v153 offset:21504
	ds_read_b128 v[212:215], v153 offset:22528
	ds_read_b128 v[216:219], v153 offset:23552
	s_waitcnt vmcnt(7)
	s_waitcnt lgkmcnt(0)
	s_barrier
	s_waitcnt lgkmcnt(0)
	v_mfma_f32_16x16x32_bf16 v[60:63], v[144:147], v[184:187], v[60:63]
	v_mfma_f32_16x16x32_bf16 v[56:59], v[160:163], v[184:187], v[56:59]
	v_mfma_f32_16x16x32_bf16 v[44:47], v[144:147], v[192:195], v[44:47]
	v_mfma_f32_16x16x32_bf16 v[40:43], v[160:163], v[192:195], v[40:43]
	v_mfma_f32_16x16x32_bf16 v[28:31], v[144:147], v[200:203], v[28:31]
	v_mfma_f32_16x16x32_bf16 v[24:27], v[160:163], v[200:203], v[24:27]
	v_mfma_f32_16x16x32_bf16 v[12:15], v[144:147], v[212:215], v[12:15]
	v_mfma_f32_16x16x32_bf16 v[8:11], v[160:163], v[212:215], v[8:11]
	v_mfma_f32_16x16x32_bf16 v[60:63], v[156:159], v[188:191], v[60:63]
	v_mfma_f32_16x16x32_bf16 v[56:59], v[164:167], v[188:191], v[56:59]
	v_mfma_f32_16x16x32_bf16 v[44:47], v[156:159], v[196:199], v[44:47]
	v_mfma_f32_16x16x32_bf16 v[40:43], v[164:167], v[196:199], v[40:43]
	v_mfma_f32_16x16x32_bf16 v[28:31], v[156:159], v[208:211], v[28:31]
	v_mfma_f32_16x16x32_bf16 v[24:27], v[164:167], v[208:211], v[24:27]
	v_mfma_f32_16x16x32_bf16 v[12:15], v[156:159], v[216:219], v[12:15]
	v_mfma_f32_16x16x32_bf16 v[8:11], v[164:167], v[216:219], v[8:11]
	v_mfma_f32_16x16x32_bf16 v[52:55], v[168:171], v[184:187], v[52:55]
	v_mfma_f32_16x16x32_bf16 v[48:51], v[176:179], v[184:187], v[48:51]
	v_mfma_f32_16x16x32_bf16 v[36:39], v[168:171], v[192:195], v[36:39]
	v_mfma_f32_16x16x32_bf16 v[32:35], v[176:179], v[192:195], v[32:35]
	v_mfma_f32_16x16x32_bf16 v[20:23], v[168:171], v[200:203], v[20:23]
	v_mfma_f32_16x16x32_bf16 v[16:19], v[176:179], v[200:203], v[16:19]
	v_mfma_f32_16x16x32_bf16 v[4:7], v[168:171], v[212:215], v[4:7]
	v_mfma_f32_16x16x32_bf16 v[0:3], v[176:179], v[212:215], v[0:3]
	v_mfma_f32_16x16x32_bf16 v[52:55], v[172:175], v[188:191], v[52:55]
	v_mfma_f32_16x16x32_bf16 v[48:51], v[180:183], v[188:191], v[48:51]
	v_mfma_f32_16x16x32_bf16 v[36:39], v[172:175], v[196:199], v[36:39]
	v_mfma_f32_16x16x32_bf16 v[32:35], v[180:183], v[196:199], v[32:35]
	v_mfma_f32_16x16x32_bf16 v[20:23], v[172:175], v[208:211], v[20:23]
	v_mfma_f32_16x16x32_bf16 v[16:19], v[180:183], v[208:211], v[16:19]
	v_mfma_f32_16x16x32_bf16 v[4:7], v[172:175], v[216:219], v[4:7]
	v_mfma_f32_16x16x32_bf16 v[0:3], v[180:183], v[216:219], v[0:3]
	s_barrier
	s_mov_b32 m0, s39
	s_nop 0
	global_load_lds_dwordx4 v130, s[28:29]
	s_add_i32 s56, 0, 0x18000
	s_add_i32 s57, 0, 0x1c000
	s_add_u32 s28, s28, 0x40000
	s_addc_u32 s29, s29, 0
	s_mov_b32 m0, s40
	s_nop 0
	global_load_lds_dwordx4 v134, s[28:29]
	s_mov_b32 m0, s41
	s_nop 0
	global_load_lds_dwordx4 v130, s[28:29]
	v_add_u32_e32 v164, s56, v149
	v_add_u32_e32 v180, s57, v149
	ds_read_b128 v[144:147], v164
	ds_read_b128 v[156:159], v164 offset:1024
	ds_read_b128 v[160:163], v164 offset:2048
	ds_read_b128 v[164:167], v164 offset:3072
	ds_read_b128 v[168:171], v180
	ds_read_b128 v[172:175], v180 offset:1024
	ds_read_b128 v[176:179], v180 offset:2048
	ds_read_b128 v[180:183], v180 offset:3072
	ds_read_b128 v[184:187], v153 offset:32768
	ds_read_b128 v[188:191], v153 offset:33792
	ds_read_b128 v[192:195], v153 offset:34816
	ds_read_b128 v[196:199], v153 offset:35840
	ds_read_b128 v[200:203], v153 offset:36864
	ds_read_b128 v[208:211], v153 offset:37888
	ds_read_b128 v[212:215], v153 offset:38912
	ds_read_b128 v[216:219], v153 offset:39936
	s_waitcnt vmcnt(8)
	s_waitcnt lgkmcnt(0)
	s_barrier
	s_waitcnt lgkmcnt(0)
	v_mfma_f32_16x16x32_bf16 v[124:127], v[144:147], v[184:187], v[124:127]
	v_mfma_f32_16x16x32_bf16 v[120:123], v[160:163], v[184:187], v[120:123]
	v_mfma_f32_16x16x32_bf16 v[108:111], v[144:147], v[192:195], v[108:111]
	v_mfma_f32_16x16x32_bf16 v[104:107], v[160:163], v[192:195], v[104:107]
	v_mfma_f32_16x16x32_bf16 v[92:95], v[144:147], v[200:203], v[92:95]
	v_mfma_f32_16x16x32_bf16 v[88:91], v[160:163], v[200:203], v[88:91]
	v_mfma_f32_16x16x32_bf16 v[76:79], v[144:147], v[212:215], v[76:79]
	v_mfma_f32_16x16x32_bf16 v[72:75], v[160:163], v[212:215], v[72:75]
	v_mfma_f32_16x16x32_bf16 v[124:127], v[156:159], v[188:191], v[124:127]
	v_mfma_f32_16x16x32_bf16 v[120:123], v[164:167], v[188:191], v[120:123]
	v_mfma_f32_16x16x32_bf16 v[108:111], v[156:159], v[196:199], v[108:111]
	v_mfma_f32_16x16x32_bf16 v[104:107], v[164:167], v[196:199], v[104:107]
	v_mfma_f32_16x16x32_bf16 v[92:95], v[156:159], v[208:211], v[92:95]
	v_mfma_f32_16x16x32_bf16 v[88:91], v[164:167], v[208:211], v[88:91]
	v_mfma_f32_16x16x32_bf16 v[76:79], v[156:159], v[216:219], v[76:79]
	v_mfma_f32_16x16x32_bf16 v[72:75], v[164:167], v[216:219], v[72:75]
	v_mfma_f32_16x16x32_bf16 v[116:119], v[168:171], v[184:187], v[116:119]
	v_mfma_f32_16x16x32_bf16 v[112:115], v[176:179], v[184:187], v[112:115]
	v_mfma_f32_16x16x32_bf16 v[100:103], v[168:171], v[192:195], v[100:103]
	v_mfma_f32_16x16x32_bf16 v[96:99], v[176:179], v[192:195], v[96:99]
	v_mfma_f32_16x16x32_bf16 v[84:87], v[168:171], v[200:203], v[84:87]
	v_mfma_f32_16x16x32_bf16 v[80:83], v[176:179], v[200:203], v[80:83]
	v_mfma_f32_16x16x32_bf16 v[68:71], v[168:171], v[212:215], v[68:71]
	v_mfma_f32_16x16x32_bf16 v[64:67], v[176:179], v[212:215], v[64:67]
	v_mfma_f32_16x16x32_bf16 v[116:119], v[172:175], v[188:191], v[116:119]
	v_mfma_f32_16x16x32_bf16 v[112:115], v[180:183], v[188:191], v[112:115]
	v_mfma_f32_16x16x32_bf16 v[100:103], v[172:175], v[196:199], v[100:103]
	v_mfma_f32_16x16x32_bf16 v[96:99], v[180:183], v[196:199], v[96:99]
	v_mfma_f32_16x16x32_bf16 v[84:87], v[172:175], v[208:211], v[84:87]
	v_mfma_f32_16x16x32_bf16 v[80:83], v[180:183], v[208:211], v[80:83]
	v_mfma_f32_16x16x32_bf16 v[68:71], v[172:175], v[216:219], v[68:71]
	v_mfma_f32_16x16x32_bf16 v[64:67], v[180:183], v[216:219], v[64:67]
	s_barrier
	s_add_i32 s28, s56, s35
	s_mov_b32 m0, s28
	s_nop 0
	global_load_lds_dwordx4 v220, s[26:27]
	s_add_i32 m0, s28, 0x2000
	s_add_u32 s26, s26, 0x40080
	s_addc_u32 s27, s27, 0
	s_add_i32 s28, s57, s35
	global_load_lds_dwordx4 v204, s[98:99]
	s_mov_b32 m0, s28
	s_nop 0
	global_load_lds_dwordx4 v132, s[26:27]
	s_add_i32 m0, s28, 0x2000
	s_nop 0
	global_load_lds_dwordx4 v128, s[26:27]
	s_mov_b32 m0, s45
	s_nop 0
	global_load_lds_dwordx4 v221, s[100:101]
	s_cmp_lg_u32 s55, 12
	s_cbranch_scc1 .Lbal_last_21
	s_mov_b32 m0, s46
	s_nop 0
	global_load_lds_dwordx4 v205, s[100:101]
.Lbal_last_21:
	ds_read_b128 v[184:187], v153 offset:49152
	ds_read_b128 v[188:191], v153 offset:50176
	ds_read_b128 v[192:195], v153 offset:51200
	ds_read_b128 v[196:199], v153 offset:52224
	ds_read_b128 v[200:203], v153 offset:53248
	ds_read_b128 v[208:211], v153 offset:54272
	ds_read_b128 v[212:215], v153 offset:55296
	ds_read_b128 v[216:219], v153 offset:56320
	s_waitcnt vmcnt(7)
	s_waitcnt lgkmcnt(0)
	s_barrier
	s_waitcnt lgkmcnt(0)
	v_mfma_f32_16x16x32_bf16 v[60:63], v[144:147], v[184:187], v[60:63]
	v_mfma_f32_16x16x32_bf16 v[56:59], v[160:163], v[184:187], v[56:59]
	v_mfma_f32_16x16x32_bf16 v[44:47], v[144:147], v[192:195], v[44:47]
	v_mfma_f32_16x16x32_bf16 v[40:43], v[160:163], v[192:195], v[40:43]
	v_mfma_f32_16x16x32_bf16 v[28:31], v[144:147], v[200:203], v[28:31]
	v_mfma_f32_16x16x32_bf16 v[24:27], v[160:163], v[200:203], v[24:27]
	v_mfma_f32_16x16x32_bf16 v[12:15], v[144:147], v[212:215], v[12:15]
	v_mfma_f32_16x16x32_bf16 v[8:11], v[160:163], v[212:215], v[8:11]
	v_mfma_f32_16x16x32_bf16 v[60:63], v[156:159], v[188:191], v[60:63]
	v_mfma_f32_16x16x32_bf16 v[56:59], v[164:167], v[188:191], v[56:59]
	v_mfma_f32_16x16x32_bf16 v[44:47], v[156:159], v[196:199], v[44:47]
	v_mfma_f32_16x16x32_bf16 v[40:43], v[164:167], v[196:199], v[40:43]
	v_mfma_f32_16x16x32_bf16 v[28:31], v[156:159], v[208:211], v[28:31]
	v_mfma_f32_16x16x32_bf16 v[24:27], v[164:167], v[208:211], v[24:27]
	v_mfma_f32_16x16x32_bf16 v[12:15], v[156:159], v[216:219], v[12:15]
	v_mfma_f32_16x16x32_bf16 v[8:11], v[164:167], v[216:219], v[8:11]
	v_mfma_f32_16x16x32_bf16 v[52:55], v[168:171], v[184:187], v[52:55]
	v_mfma_f32_16x16x32_bf16 v[48:51], v[176:179], v[184:187], v[48:51]
	v_mfma_f32_16x16x32_bf16 v[36:39], v[168:171], v[192:195], v[36:39]
	v_mfma_f32_16x16x32_bf16 v[32:35], v[176:179], v[192:195], v[32:35]
	v_mfma_f32_16x16x32_bf16 v[20:23], v[168:171], v[200:203], v[20:23]
	v_mfma_f32_16x16x32_bf16 v[16:19], v[176:179], v[200:203], v[16:19]
	v_mfma_f32_16x16x32_bf16 v[4:7], v[168:171], v[212:215], v[4:7]
	v_mfma_f32_16x16x32_bf16 v[0:3], v[176:179], v[212:215], v[0:3]
	v_mfma_f32_16x16x32_bf16 v[52:55], v[172:175], v[188:191], v[52:55]
	v_mfma_f32_16x16x32_bf16 v[48:51], v[180:183], v[188:191], v[48:51]
	v_mfma_f32_16x16x32_bf16 v[36:39], v[172:175], v[196:199], v[36:39]
	v_mfma_f32_16x16x32_bf16 v[32:35], v[180:183], v[196:199], v[32:35]
	v_mfma_f32_16x16x32_bf16 v[20:23], v[172:175], v[208:211], v[20:23]
	v_mfma_f32_16x16x32_bf16 v[16:19], v[180:183], v[208:211], v[16:19]
	v_mfma_f32_16x16x32_bf16 v[4:7], v[172:175], v[216:219], v[4:7]
	v_mfma_f32_16x16x32_bf16 v[0:3], v[180:183], v[216:219], v[0:3]
	s_barrier
	s_add_i32 s55, s55, 2
	s_add_u32 s53, s53, 0x100
	s_addc_u32 s54, s54, 0
	s_add_u32 s24, s24, 0x100
	s_addc_u32 s25, s25, 0
	s_cmp_gt_u32 s55, 13
	s_cbranch_scc0 .LBB0_163
	s_setprio 0
	s_and_b64 vcc, exec, s[14:15]
	s_cbranch_vccz .LBB0_166
	s_barrier

.Lbal_first_20:
	s_add_u32 s30, s28, 0x100
	s_addc_u32 s31, s29, 0
	s_cmp_eq_u32 s58, 12
	s_cselect_b32 s37, s21, s31
	s_cselect_b32 s36, s27, s30
	s_cselect_b32 s35, s19, s57
	s_cselect_b32 s34, s55, s56
	s_add_i32 m0, s44, 0xc000
	s_nop 0
	global_load_lds_dwordx4 v134, s[28:29]
	s_add_i32 m0, s44, 0xe000
	s_nop 0
	global_load_lds_dwordx4 v132, s[28:29]
	ds_read_b128 v[140:143], v147
	ds_read_b128 v[150:153], v147 offset:1024
	ds_read_b128 v[154:157], v147 offset:2048
	ds_read_b128 v[158:161], v147 offset:3072
	ds_read_b128 v[162:165], v148
	ds_read_b128 v[166:169], v148 offset:1024
	ds_read_b128 v[170:173], v148 offset:2048
	ds_read_b128 v[174:177], v148 offset:3072
	ds_read_b128 v[178:181], v149
	ds_read_b128 v[182:185], v149 offset:1024
	ds_read_b128 v[186:189], v149 offset:2048
	ds_read_b128 v[190:193], v149 offset:3072
	ds_read_b128 v[194:197], v149 offset:4096
	ds_read_b128 v[198:201], v149 offset:5120
	ds_read_b128 v[202:205], v149 offset:6144
	ds_read_b128 v[208:211], v149 offset:7168
	s_waitcnt vmcnt(8)
	s_waitcnt lgkmcnt(0)
	s_barrier
	s_waitcnt lgkmcnt(0)
	v_mfma_f32_16x16x32_bf16 v[124:127], v[140:143], v[178:181], v[124:127]
	v_mfma_f32_16x16x32_bf16 v[120:123], v[154:157], v[178:181], v[120:123]
	v_mfma_f32_16x16x32_bf16 v[108:111], v[140:143], v[186:189], v[108:111]
	v_mfma_f32_16x16x32_bf16 v[104:107], v[154:157], v[186:189], v[104:107]
	v_mfma_f32_16x16x32_bf16 v[92:95], v[140:143], v[194:197], v[92:95]
	v_mfma_f32_16x16x32_bf16 v[88:91], v[154:157], v[194:197], v[88:91]
	v_mfma_f32_16x16x32_bf16 v[76:79], v[140:143], v[202:205], v[76:79]
	v_mfma_f32_16x16x32_bf16 v[72:75], v[154:157], v[202:205], v[72:75]
	v_mfma_f32_16x16x32_bf16 v[124:127], v[150:153], v[182:185], v[124:127]
	v_mfma_f32_16x16x32_bf16 v[120:123], v[158:161], v[182:185], v[120:123]
	v_mfma_f32_16x16x32_bf16 v[108:111], v[150:153], v[190:193], v[108:111]
	v_mfma_f32_16x16x32_bf16 v[104:107], v[158:161], v[190:193], v[104:107]
	v_mfma_f32_16x16x32_bf16 v[92:95], v[150:153], v[198:201], v[92:95]
	v_mfma_f32_16x16x32_bf16 v[88:91], v[158:161], v[198:201], v[88:91]
	v_mfma_f32_16x16x32_bf16 v[76:79], v[150:153], v[208:211], v[76:79]
	v_mfma_f32_16x16x32_bf16 v[72:75], v[158:161], v[208:211], v[72:75]
	v_mfma_f32_16x16x32_bf16 v[116:119], v[162:165], v[178:181], v[116:119]
	v_mfma_f32_16x16x32_bf16 v[112:115], v[170:173], v[178:181], v[112:115]
	v_mfma_f32_16x16x32_bf16 v[100:103], v[162:165], v[186:189], v[100:103]
	v_mfma_f32_16x16x32_bf16 v[96:99], v[170:173], v[186:189], v[96:99]
	v_mfma_f32_16x16x32_bf16 v[84:87], v[162:165], v[194:197], v[84:87]
	v_mfma_f32_16x16x32_bf16 v[80:83], v[170:173], v[194:197], v[80:83]
	v_mfma_f32_16x16x32_bf16 v[68:71], v[162:165], v[202:205], v[68:71]
	v_mfma_f32_16x16x32_bf16 v[64:67], v[170:173], v[202:205], v[64:67]
	v_mfma_f32_16x16x32_bf16 v[116:119], v[166:169], v[182:185], v[116:119]
	v_mfma_f32_16x16x32_bf16 v[112:115], v[174:177], v[182:185], v[112:115]
	v_mfma_f32_16x16x32_bf16 v[100:103], v[166:169], v[190:193], v[100:103]
	v_mfma_f32_16x16x32_bf16 v[96:99], v[174:177], v[190:193], v[96:99]
	v_mfma_f32_16x16x32_bf16 v[84:87], v[166:169], v[198:201], v[84:87]
	v_mfma_f32_16x16x32_bf16 v[80:83], v[174:177], v[198:201], v[80:83]
	v_mfma_f32_16x16x32_bf16 v[68:71], v[166:169], v[208:211], v[68:71]
	v_mfma_f32_16x16x32_bf16 v[64:67], v[174:177], v[208:211], v[64:67]
	s_barrier
	s_add_i32 s28, s52, s43
	s_mov_b32 m0, s28
	s_nop 0
	global_load_lds_dwordx4 v128, s[34:35]
	s_add_i32 m0, s28, 0x2000
	s_add_u32 s28, s34, 0x40000
	s_mov_b64 s[98:99], s[34:35]
	s_addc_u32 s29, s35, 0
	s_add_i32 s59, s53, s43
	global_load_lds_dwordx4 v130, s[34:35]
	s_mov_b32 m0, s59
	s_nop 0
	global_load_lds_dwordx4 v128, s[28:29]
	s_add_i32 m0, s59, 0x2000
	s_nop 0
	global_load_lds_dwordx4 v130, s[28:29]
	s_mov_b32 m0, s44
	s_nop 0
	global_load_lds_dwordx4 v128, s[36:37]
	ds_read_b128 v[178:181], v149 offset:16384
	ds_read_b128 v[182:185], v149 offset:17408
	ds_read_b128 v[186:189], v149 offset:18432
	ds_read_b128 v[190:193], v149 offset:19456
	ds_read_b128 v[194:197], v149 offset:20480
	ds_read_b128 v[198:201], v149 offset:21504
	ds_read_b128 v[202:205], v149 offset:22528
	ds_read_b128 v[208:211], v149 offset:23552
	s_waitcnt vmcnt(7)
	s_waitcnt lgkmcnt(0)
	s_barrier
	s_waitcnt lgkmcnt(0)
	v_mfma_f32_16x16x32_bf16 v[60:63], v[140:143], v[178:181], v[60:63]
	v_mfma_f32_16x16x32_bf16 v[56:59], v[154:157], v[178:181], v[56:59]
	v_mfma_f32_16x16x32_bf16 v[44:47], v[140:143], v[186:189], v[44:47]
	v_mfma_f32_16x16x32_bf16 v[40:43], v[154:157], v[186:189], v[40:43]
	v_mfma_f32_16x16x32_bf16 v[28:31], v[140:143], v[194:197], v[28:31]
	v_mfma_f32_16x16x32_bf16 v[24:27], v[154:157], v[194:197], v[24:27]
	v_mfma_f32_16x16x32_bf16 v[12:15], v[140:143], v[202:205], v[12:15]
	v_mfma_f32_16x16x32_bf16 v[8:11], v[154:157], v[202:205], v[8:11]
	v_mfma_f32_16x16x32_bf16 v[60:63], v[150:153], v[182:185], v[60:63]
	v_mfma_f32_16x16x32_bf16 v[56:59], v[158:161], v[182:185], v[56:59]
	v_mfma_f32_16x16x32_bf16 v[44:47], v[150:153], v[190:193], v[44:47]
	v_mfma_f32_16x16x32_bf16 v[40:43], v[158:161], v[190:193], v[40:43]
	v_mfma_f32_16x16x32_bf16 v[28:31], v[150:153], v[198:201], v[28:31]
	v_mfma_f32_16x16x32_bf16 v[24:27], v[158:161], v[198:201], v[24:27]
	v_mfma_f32_16x16x32_bf16 v[12:15], v[150:153], v[208:211], v[12:15]
	v_mfma_f32_16x16x32_bf16 v[8:11], v[158:161], v[208:211], v[8:11]
	v_mfma_f32_16x16x32_bf16 v[52:55], v[162:165], v[178:181], v[52:55]
	v_mfma_f32_16x16x32_bf16 v[48:51], v[170:173], v[178:181], v[48:51]
	v_mfma_f32_16x16x32_bf16 v[36:39], v[162:165], v[186:189], v[36:39]
	v_mfma_f32_16x16x32_bf16 v[32:35], v[170:173], v[186:189], v[32:35]
	v_mfma_f32_16x16x32_bf16 v[20:23], v[162:165], v[194:197], v[20:23]
	v_mfma_f32_16x16x32_bf16 v[16:19], v[170:173], v[194:197], v[16:19]
	v_mfma_f32_16x16x32_bf16 v[4:7], v[162:165], v[202:205], v[4:7]
	v_mfma_f32_16x16x32_bf16 v[0:3], v[170:173], v[202:205], v[0:3]
	v_mfma_f32_16x16x32_bf16 v[52:55], v[166:169], v[182:185], v[52:55]
	v_mfma_f32_16x16x32_bf16 v[48:51], v[174:177], v[182:185], v[48:51]
	v_mfma_f32_16x16x32_bf16 v[36:39], v[166:169], v[190:193], v[36:39]
	v_mfma_f32_16x16x32_bf16 v[32:35], v[174:177], v[190:193], v[32:35]
	v_mfma_f32_16x16x32_bf16 v[20:23], v[166:169], v[198:201], v[20:23]
	v_mfma_f32_16x16x32_bf16 v[16:19], v[174:177], v[198:201], v[16:19]
	v_mfma_f32_16x16x32_bf16 v[4:7], v[166:169], v[208:211], v[4:7]
	v_mfma_f32_16x16x32_bf16 v[0:3], v[174:177], v[208:211], v[0:3]
	s_barrier
	s_mov_b32 m0, s45
	s_nop 0
	global_load_lds_dwordx4 v130, s[36:37]
	s_add_i32 s59, 0, 0x18000
	s_add_i32 s60, 0, 0x1c000
	s_add_u32 s28, s36, 0x40000
	s_addc_u32 s29, s37, 0
	s_mov_b32 m0, s46
	s_nop 0
	global_load_lds_dwordx4 v128, s[28:29]
	s_mov_b32 m0, s47
	s_nop 0
	global_load_lds_dwordx4 v130, s[28:29]
	v_add_u32_e32 v158, s59, v145
	v_add_u32_e32 v174, s60, v145
	ds_read_b128 v[140:143], v158
	ds_read_b128 v[150:153], v158 offset:1024
	ds_read_b128 v[154:157], v158 offset:2048
	ds_read_b128 v[158:161], v158 offset:3072
	ds_read_b128 v[162:165], v174
	ds_read_b128 v[166:169], v174 offset:1024
	ds_read_b128 v[170:173], v174 offset:2048
	ds_read_b128 v[174:177], v174 offset:3072
	ds_read_b128 v[178:181], v149 offset:32768
	ds_read_b128 v[182:185], v149 offset:33792
	ds_read_b128 v[186:189], v149 offset:34816
	ds_read_b128 v[190:193], v149 offset:35840
	ds_read_b128 v[194:197], v149 offset:36864
	ds_read_b128 v[198:201], v149 offset:37888
	ds_read_b128 v[202:205], v149 offset:38912
	ds_read_b128 v[208:211], v149 offset:39936
	s_waitcnt vmcnt(8)
	s_waitcnt lgkmcnt(0)
	s_barrier
	s_waitcnt lgkmcnt(0)
	v_mfma_f32_16x16x32_bf16 v[124:127], v[140:143], v[178:181], v[124:127]
	v_mfma_f32_16x16x32_bf16 v[120:123], v[154:157], v[178:181], v[120:123]
	v_mfma_f32_16x16x32_bf16 v[108:111], v[140:143], v[186:189], v[108:111]
	v_mfma_f32_16x16x32_bf16 v[104:107], v[154:157], v[186:189], v[104:107]
	v_mfma_f32_16x16x32_bf16 v[92:95], v[140:143], v[194:197], v[92:95]
	v_mfma_f32_16x16x32_bf16 v[88:91], v[154:157], v[194:197], v[88:91]
	v_mfma_f32_16x16x32_bf16 v[76:79], v[140:143], v[202:205], v[76:79]
	v_mfma_f32_16x16x32_bf16 v[72:75], v[154:157], v[202:205], v[72:75]
	v_mfma_f32_16x16x32_bf16 v[124:127], v[150:153], v[182:185], v[124:127]
	v_mfma_f32_16x16x32_bf16 v[120:123], v[158:161], v[182:185], v[120:123]
	v_mfma_f32_16x16x32_bf16 v[108:111], v[150:153], v[190:193], v[108:111]
	v_mfma_f32_16x16x32_bf16 v[104:107], v[158:161], v[190:193], v[104:107]
	v_mfma_f32_16x16x32_bf16 v[92:95], v[150:153], v[198:201], v[92:95]
	v_mfma_f32_16x16x32_bf16 v[88:91], v[158:161], v[198:201], v[88:91]
	v_mfma_f32_16x16x32_bf16 v[76:79], v[150:153], v[208:211], v[76:79]
	v_mfma_f32_16x16x32_bf16 v[72:75], v[158:161], v[208:211], v[72:75]
	v_mfma_f32_16x16x32_bf16 v[116:119], v[162:165], v[178:181], v[116:119]
	v_mfma_f32_16x16x32_bf16 v[112:115], v[170:173], v[178:181], v[112:115]
	v_mfma_f32_16x16x32_bf16 v[100:103], v[162:165], v[186:189], v[100:103]
	v_mfma_f32_16x16x32_bf16 v[96:99], v[170:173], v[186:189], v[96:99]
	v_mfma_f32_16x16x32_bf16 v[84:87], v[162:165], v[194:197], v[84:87]
	v_mfma_f32_16x16x32_bf16 v[80:83], v[170:173], v[194:197], v[80:83]
	v_mfma_f32_16x16x32_bf16 v[68:71], v[162:165], v[202:205], v[68:71]
	v_mfma_f32_16x16x32_bf16 v[64:67], v[170:173], v[202:205], v[64:67]
	v_mfma_f32_16x16x32_bf16 v[116:119], v[166:169], v[182:185], v[116:119]
	v_mfma_f32_16x16x32_bf16 v[112:115], v[174:177], v[182:185], v[112:115]
	v_mfma_f32_16x16x32_bf16 v[100:103], v[166:169], v[190:193], v[100:103]
	v_mfma_f32_16x16x32_bf16 v[96:99], v[174:177], v[190:193], v[96:99]
	v_mfma_f32_16x16x32_bf16 v[84:87], v[166:169], v[198:201], v[84:87]
	v_mfma_f32_16x16x32_bf16 v[80:83], v[174:177], v[198:201], v[80:83]
	v_mfma_f32_16x16x32_bf16 v[68:71], v[166:169], v[208:211], v[68:71]
	v_mfma_f32_16x16x32_bf16 v[64:67], v[174:177], v[208:211], v[64:67]
	s_barrier
	s_add_i32 s28, s59, s43
	s_mov_b32 m0, s28
	s_nop 0
	global_load_lds_dwordx4 v212, s[34:35]
	s_add_i32 m0, s28, 0x2000
	s_add_u32 s28, s34, 0x40080
	s_addc_u32 s29, s35, 0
	s_add_i32 s34, s60, s43
	global_load_lds_dwordx4 v213, s[98:99]
	s_mov_b32 m0, s34
	s_nop 0
	global_load_lds_dwordx4 v128, s[28:29]
	s_add_i32 m0, s34, 0x2000
	s_nop 0
	global_load_lds_dwordx4 v130, s[28:29]
	s_mov_b32 m0, s49
	s_nop 0
	global_load_lds_dwordx4 v212, s[36:37]
	s_cmp_lg_u32 s58, 12
	s_cbranch_scc1 .Lbal_last_20
	s_mov_b32 m0, s50
	s_nop 0
	global_load_lds_dwordx4 v213, s[36:37]
.Lbal_last_20:
	ds_read_b128 v[178:181], v149 offset:49152
	ds_read_b128 v[182:185], v149 offset:50176
	ds_read_b128 v[186:189], v149 offset:51200
	ds_read_b128 v[190:193], v149 offset:52224
	ds_read_b128 v[194:197], v149 offset:53248
	ds_read_b128 v[198:201], v149 offset:54272
	ds_read_b128 v[202:205], v149 offset:55296
	ds_read_b128 v[208:211], v149 offset:56320
	s_waitcnt vmcnt(7)
	s_waitcnt lgkmcnt(0)
	s_barrier
	s_waitcnt lgkmcnt(0)
	v_mfma_f32_16x16x32_bf16 v[60:63], v[140:143], v[178:181], v[60:63]
	v_mfma_f32_16x16x32_bf16 v[56:59], v[154:157], v[178:181], v[56:59]
	v_mfma_f32_16x16x32_bf16 v[44:47], v[140:143], v[186:189], v[44:47]
	v_mfma_f32_16x16x32_bf16 v[40:43], v[154:157], v[186:189], v[40:43]
	v_mfma_f32_16x16x32_bf16 v[28:31], v[140:143], v[194:197], v[28:31]
	v_mfma_f32_16x16x32_bf16 v[24:27], v[154:157], v[194:197], v[24:27]
	v_mfma_f32_16x16x32_bf16 v[12:15], v[140:143], v[202:205], v[12:15]
	v_mfma_f32_16x16x32_bf16 v[8:11], v[154:157], v[202:205], v[8:11]
	v_mfma_f32_16x16x32_bf16 v[60:63], v[150:153], v[182:185], v[60:63]
	v_mfma_f32_16x16x32_bf16 v[56:59], v[158:161], v[182:185], v[56:59]
	v_mfma_f32_16x16x32_bf16 v[44:47], v[150:153], v[190:193], v[44:47]
	v_mfma_f32_16x16x32_bf16 v[40:43], v[158:161], v[190:193], v[40:43]
	v_mfma_f32_16x16x32_bf16 v[28:31], v[150:153], v[198:201], v[28:31]
	v_mfma_f32_16x16x32_bf16 v[24:27], v[158:161], v[198:201], v[24:27]
	v_mfma_f32_16x16x32_bf16 v[12:15], v[150:153], v[208:211], v[12:15]
	v_mfma_f32_16x16x32_bf16 v[8:11], v[158:161], v[208:211], v[8:11]
	v_mfma_f32_16x16x32_bf16 v[52:55], v[162:165], v[178:181], v[52:55]
	v_mfma_f32_16x16x32_bf16 v[48:51], v[170:173], v[178:181], v[48:51]
	v_mfma_f32_16x16x32_bf16 v[36:39], v[162:165], v[186:189], v[36:39]
	v_mfma_f32_16x16x32_bf16 v[32:35], v[170:173], v[186:189], v[32:35]
	v_mfma_f32_16x16x32_bf16 v[20:23], v[162:165], v[194:197], v[20:23]
	v_mfma_f32_16x16x32_bf16 v[16:19], v[170:173], v[194:197], v[16:19]
	v_mfma_f32_16x16x32_bf16 v[4:7], v[162:165], v[202:205], v[4:7]
	v_mfma_f32_16x16x32_bf16 v[0:3], v[170:173], v[202:205], v[0:3]
	v_mfma_f32_16x16x32_bf16 v[52:55], v[166:169], v[182:185], v[52:55]
	v_mfma_f32_16x16x32_bf16 v[48:51], v[174:177], v[182:185], v[48:51]
	v_mfma_f32_16x16x32_bf16 v[36:39], v[166:169], v[190:193], v[36:39]
	v_mfma_f32_16x16x32_bf16 v[32:35], v[174:177], v[190:193], v[32:35]
	v_mfma_f32_16x16x32_bf16 v[20:23], v[166:169], v[198:201], v[20:23]
	v_mfma_f32_16x16x32_bf16 v[16:19], v[174:177], v[198:201], v[16:19]
	v_mfma_f32_16x16x32_bf16 v[4:7], v[166:169], v[208:211], v[4:7]
	v_mfma_f32_16x16x32_bf16 v[0:3], v[174:177], v[208:211], v[0:3]
	s_barrier
	s_add_i32 s58, s58, 2
	s_add_u32 s56, s56, 0x100
	s_addc_u32 s57, s57, 0
	s_cmp_gt_u32 s58, 13
	s_mov_b64 s[28:29], s[30:31]
	s_cbranch_scc0 .LBB0_606
	s_setprio 0
	s_and_b64 vcc, exec, s[16:17]
	s_cbranch_vccz .LBB0_609
	s_barrier

.Lbal_first_19:
	s_add_u32 s28, s26, 0xfffc0080
	s_addc_u32 s29, s27, -1
	s_cmp_eq_u32 s53, 12
	s_cselect_b32 s31, s21, s29
	s_cselect_b32 s30, s49, s28
	s_cselect_b32 s29, s19, s52
	s_cselect_b32 s28, s50, s51
	s_add_i32 m0, s39, 0xc000
	s_nop 0
	global_load_lds_dwordx4 v138, s[26:27]
	s_add_i32 m0, s39, 0xe000
	s_nop 0
	global_load_lds_dwordx4 v136, s[26:27]
	ds_read_b128 v[144:147], v151
	ds_read_b128 v[156:159], v151 offset:1024
	ds_read_b128 v[160:163], v151 offset:2048
	ds_read_b128 v[164:167], v151 offset:3072
	ds_read_b128 v[168:171], v152
	ds_read_b128 v[172:175], v152 offset:1024
	ds_read_b128 v[176:179], v152 offset:2048
	ds_read_b128 v[180:183], v152 offset:3072
	ds_read_b128 v[184:187], v153
	ds_read_b128 v[188:191], v153 offset:1024
	ds_read_b128 v[192:195], v153 offset:2048
	ds_read_b128 v[196:199], v153 offset:3072
	ds_read_b128 v[200:203], v153 offset:4096
	ds_read_b128 v[208:211], v153 offset:5120
	ds_read_b128 v[212:215], v153 offset:6144
	ds_read_b128 v[216:219], v153 offset:7168
	s_waitcnt vmcnt(8)
	s_waitcnt lgkmcnt(0)
	s_barrier
	s_waitcnt lgkmcnt(0)
	v_mfma_f32_16x16x32_bf16 v[124:127], v[144:147], v[184:187], v[124:127]
	v_mfma_f32_16x16x32_bf16 v[120:123], v[160:163], v[184:187], v[120:123]
	v_mfma_f32_16x16x32_bf16 v[108:111], v[144:147], v[192:195], v[108:111]
	v_mfma_f32_16x16x32_bf16 v[104:107], v[160:163], v[192:195], v[104:107]
	v_mfma_f32_16x16x32_bf16 v[92:95], v[144:147], v[200:203], v[92:95]
	v_mfma_f32_16x16x32_bf16 v[88:91], v[160:163], v[200:203], v[88:91]
	v_mfma_f32_16x16x32_bf16 v[76:79], v[144:147], v[212:215], v[76:79]
	v_mfma_f32_16x16x32_bf16 v[72:75], v[160:163], v[212:215], v[72:75]
	v_mfma_f32_16x16x32_bf16 v[124:127], v[156:159], v[188:191], v[124:127]
	v_mfma_f32_16x16x32_bf16 v[120:123], v[164:167], v[188:191], v[120:123]
	v_mfma_f32_16x16x32_bf16 v[108:111], v[156:159], v[196:199], v[108:111]
	v_mfma_f32_16x16x32_bf16 v[104:107], v[164:167], v[196:199], v[104:107]
	v_mfma_f32_16x16x32_bf16 v[92:95], v[156:159], v[208:211], v[92:95]
	v_mfma_f32_16x16x32_bf16 v[88:91], v[164:167], v[208:211], v[88:91]
	v_mfma_f32_16x16x32_bf16 v[76:79], v[156:159], v[216:219], v[76:79]
	v_mfma_f32_16x16x32_bf16 v[72:75], v[164:167], v[216:219], v[72:75]
	v_mfma_f32_16x16x32_bf16 v[116:119], v[168:171], v[184:187], v[116:119]
	v_mfma_f32_16x16x32_bf16 v[112:115], v[176:179], v[184:187], v[112:115]
	v_mfma_f32_16x16x32_bf16 v[100:103], v[168:171], v[192:195], v[100:103]
	v_mfma_f32_16x16x32_bf16 v[96:99], v[176:179], v[192:195], v[96:99]
	v_mfma_f32_16x16x32_bf16 v[84:87], v[168:171], v[200:203], v[84:87]
	v_mfma_f32_16x16x32_bf16 v[80:83], v[176:179], v[200:203], v[80:83]
	v_mfma_f32_16x16x32_bf16 v[68:71], v[168:171], v[212:215], v[68:71]
	v_mfma_f32_16x16x32_bf16 v[64:67], v[176:179], v[212:215], v[64:67]
	v_mfma_f32_16x16x32_bf16 v[116:119], v[172:175], v[188:191], v[116:119]
	v_mfma_f32_16x16x32_bf16 v[112:115], v[180:183], v[188:191], v[112:115]
	v_mfma_f32_16x16x32_bf16 v[100:103], v[172:175], v[196:199], v[100:103]
	v_mfma_f32_16x16x32_bf16 v[96:99], v[180:183], v[196:199], v[96:99]
	v_mfma_f32_16x16x32_bf16 v[84:87], v[172:175], v[208:211], v[84:87]
	v_mfma_f32_16x16x32_bf16 v[80:83], v[180:183], v[208:211], v[80:83]
	v_mfma_f32_16x16x32_bf16 v[68:71], v[172:175], v[216:219], v[68:71]
	v_mfma_f32_16x16x32_bf16 v[64:67], v[180:183], v[216:219], v[64:67]
	s_barrier
	s_add_i32 s54, s46, s38
	s_mov_b32 m0, s54
	s_nop 0
	global_load_lds_dwordx4 v130, s[28:29]
	s_add_i32 m0, s54, 0x2000
	s_add_u32 s54, s28, 0x40000
	s_mov_b64 s[98:99], s[28:29]
	s_addc_u32 s55, s29, 0
	s_add_i32 s56, s47, s38
	global_load_lds_dwordx4 v134, s[28:29]
	s_mov_b32 m0, s56
	s_mov_b64 s[100:101], s[30:31]
	global_load_lds_dwordx4 v130, s[54:55]
	s_add_i32 m0, s56, 0x2000
	s_nop 0
	global_load_lds_dwordx4 v134, s[54:55]
	s_mov_b32 m0, s39
	s_nop 0
	global_load_lds_dwordx4 v128, s[30:31]
	ds_read_b128 v[184:187], v153 offset:16384
	ds_read_b128 v[188:191], v153 offset:17408
	ds_read_b128 v[192:195], v153 offset:18432
	ds_read_b128 v[196:199], v153 offset:19456
	ds_read_b128 v[200:203], v153 offset:20480
	ds_read_b128 v[208:211], v153 offset:21504
	ds_read_b128 v[212:215], v153 offset:22528
	ds_read_b128 v[216:219], v153 offset:23552
	s_waitcnt vmcnt(7)
	s_waitcnt lgkmcnt(0)
	s_barrier
	s_waitcnt lgkmcnt(0)
	v_mfma_f32_16x16x32_bf16 v[60:63], v[144:147], v[184:187], v[60:63]
	v_mfma_f32_16x16x32_bf16 v[56:59], v[160:163], v[184:187], v[56:59]
	v_mfma_f32_16x16x32_bf16 v[44:47], v[144:147], v[192:195], v[44:47]
	v_mfma_f32_16x16x32_bf16 v[40:43], v[160:163], v[192:195], v[40:43]
	v_mfma_f32_16x16x32_bf16 v[28:31], v[144:147], v[200:203], v[28:31]
	v_mfma_f32_16x16x32_bf16 v[24:27], v[160:163], v[200:203], v[24:27]
	v_mfma_f32_16x16x32_bf16 v[12:15], v[144:147], v[212:215], v[12:15]
	v_mfma_f32_16x16x32_bf16 v[8:11], v[160:163], v[212:215], v[8:11]
	v_mfma_f32_16x16x32_bf16 v[60:63], v[156:159], v[188:191], v[60:63]
	v_mfma_f32_16x16x32_bf16 v[56:59], v[164:167], v[188:191], v[56:59]
	v_mfma_f32_16x16x32_bf16 v[44:47], v[156:159], v[196:199], v[44:47]
	v_mfma_f32_16x16x32_bf16 v[40:43], v[164:167], v[196:199], v[40:43]
	v_mfma_f32_16x16x32_bf16 v[28:31], v[156:159], v[208:211], v[28:31]
	v_mfma_f32_16x16x32_bf16 v[24:27], v[164:167], v[208:211], v[24:27]
	v_mfma_f32_16x16x32_bf16 v[12:15], v[156:159], v[216:219], v[12:15]
	v_mfma_f32_16x16x32_bf16 v[8:11], v[164:167], v[216:219], v[8:11]
	v_mfma_f32_16x16x32_bf16 v[52:55], v[168:171], v[184:187], v[52:55]
	v_mfma_f32_16x16x32_bf16 v[48:51], v[176:179], v[184:187], v[48:51]
	v_mfma_f32_16x16x32_bf16 v[36:39], v[168:171], v[192:195], v[36:39]
	v_mfma_f32_16x16x32_bf16 v[32:35], v[176:179], v[192:195], v[32:35]
	v_mfma_f32_16x16x32_bf16 v[20:23], v[168:171], v[200:203], v[20:23]
	v_mfma_f32_16x16x32_bf16 v[16:19], v[176:179], v[200:203], v[16:19]
	v_mfma_f32_16x16x32_bf16 v[4:7], v[168:171], v[212:215], v[4:7]
	v_mfma_f32_16x16x32_bf16 v[0:3], v[176:179], v[212:215], v[0:3]
	v_mfma_f32_16x16x32_bf16 v[52:55], v[172:175], v[188:191], v[52:55]
	v_mfma_f32_16x16x32_bf16 v[48:51], v[180:183], v[188:191], v[48:51]
	v_mfma_f32_16x16x32_bf16 v[36:39], v[172:175], v[196:199], v[36:39]
	v_mfma_f32_16x16x32_bf16 v[32:35], v[180:183], v[196:199], v[32:35]
	v_mfma_f32_16x16x32_bf16 v[20:23], v[172:175], v[208:211], v[20:23]
	v_mfma_f32_16x16x32_bf16 v[16:19], v[180:183], v[208:211], v[16:19]
	v_mfma_f32_16x16x32_bf16 v[4:7], v[172:175], v[216:219], v[4:7]
	v_mfma_f32_16x16x32_bf16 v[0:3], v[180:183], v[216:219], v[0:3]
	s_barrier
	s_mov_b32 m0, s40
	s_nop 0
	global_load_lds_dwordx4 v132, s[30:31]
	s_add_i32 s54, 0, 0x18000
	s_add_i32 s55, 0, 0x1c000
	s_add_u32 s30, s30, 0x40000
	s_addc_u32 s31, s31, 0
	s_mov_b32 m0, s41
	s_nop 0
	global_load_lds_dwordx4 v128, s[30:31]
	s_mov_b32 m0, s42
	s_nop 0
	global_load_lds_dwordx4 v132, s[30:31]
	v_add_u32_e32 v155, s54, v149
	ds_read_b128 v[144:147], v155
	ds_read_b128 v[156:159], v155 offset:1024
	ds_read_b128 v[160:163], v155 offset:2048
	ds_read_b128 v[164:167], v155 offset:3072
	v_add_u32_e32 v155, s55, v149
	ds_read_b128 v[168:171], v155
	ds_read_b128 v[172:175], v155 offset:1024
	ds_read_b128 v[176:179], v155 offset:2048
	ds_read_b128 v[180:183], v155 offset:3072
	ds_read_b128 v[184:187], v153 offset:32768
	ds_read_b128 v[188:191], v153 offset:33792
	ds_read_b128 v[192:195], v153 offset:34816
	ds_read_b128 v[196:199], v153 offset:35840
	ds_read_b128 v[200:203], v153 offset:36864
	ds_read_b128 v[208:211], v153 offset:37888
	ds_read_b128 v[212:215], v153 offset:38912
	ds_read_b128 v[216:219], v153 offset:39936
	s_waitcnt vmcnt(8)
	s_waitcnt lgkmcnt(0)
	s_barrier
	s_waitcnt lgkmcnt(0)
	v_mfma_f32_16x16x32_bf16 v[124:127], v[144:147], v[184:187], v[124:127]
	v_mfma_f32_16x16x32_bf16 v[120:123], v[160:163], v[184:187], v[120:123]
	v_mfma_f32_16x16x32_bf16 v[108:111], v[144:147], v[192:195], v[108:111]
	v_mfma_f32_16x16x32_bf16 v[104:107], v[160:163], v[192:195], v[104:107]
	v_mfma_f32_16x16x32_bf16 v[92:95], v[144:147], v[200:203], v[92:95]
	v_mfma_f32_16x16x32_bf16 v[88:91], v[160:163], v[200:203], v[88:91]
	v_mfma_f32_16x16x32_bf16 v[76:79], v[144:147], v[212:215], v[76:79]
	v_mfma_f32_16x16x32_bf16 v[72:75], v[160:163], v[212:215], v[72:75]
	v_mfma_f32_16x16x32_bf16 v[124:127], v[156:159], v[188:191], v[124:127]
	v_mfma_f32_16x16x32_bf16 v[120:123], v[164:167], v[188:191], v[120:123]
	v_mfma_f32_16x16x32_bf16 v[108:111], v[156:159], v[196:199], v[108:111]
	v_mfma_f32_16x16x32_bf16 v[104:107], v[164:167], v[196:199], v[104:107]
	v_mfma_f32_16x16x32_bf16 v[92:95], v[156:159], v[208:211], v[92:95]
	v_mfma_f32_16x16x32_bf16 v[88:91], v[164:167], v[208:211], v[88:91]
	v_mfma_f32_16x16x32_bf16 v[76:79], v[156:159], v[216:219], v[76:79]
	v_mfma_f32_16x16x32_bf16 v[72:75], v[164:167], v[216:219], v[72:75]
	v_mfma_f32_16x16x32_bf16 v[116:119], v[168:171], v[184:187], v[116:119]
	v_mfma_f32_16x16x32_bf16 v[112:115], v[176:179], v[184:187], v[112:115]
	v_mfma_f32_16x16x32_bf16 v[100:103], v[168:171], v[192:195], v[100:103]
	v_mfma_f32_16x16x32_bf16 v[96:99], v[176:179], v[192:195], v[96:99]
	v_mfma_f32_16x16x32_bf16 v[84:87], v[168:171], v[200:203], v[84:87]
	v_mfma_f32_16x16x32_bf16 v[80:83], v[176:179], v[200:203], v[80:83]
	v_mfma_f32_16x16x32_bf16 v[68:71], v[168:171], v[212:215], v[68:71]
	v_mfma_f32_16x16x32_bf16 v[64:67], v[176:179], v[212:215], v[64:67]
	v_mfma_f32_16x16x32_bf16 v[116:119], v[172:175], v[188:191], v[116:119]
	v_mfma_f32_16x16x32_bf16 v[112:115], v[180:183], v[188:191], v[112:115]
	v_mfma_f32_16x16x32_bf16 v[100:103], v[172:175], v[196:199], v[100:103]
	v_mfma_f32_16x16x32_bf16 v[96:99], v[180:183], v[196:199], v[96:99]
	v_mfma_f32_16x16x32_bf16 v[84:87], v[172:175], v[208:211], v[84:87]
	v_mfma_f32_16x16x32_bf16 v[80:83], v[180:183], v[208:211], v[80:83]
	v_mfma_f32_16x16x32_bf16 v[68:71], v[172:175], v[216:219], v[68:71]
	v_mfma_f32_16x16x32_bf16 v[64:67], v[180:183], v[216:219], v[64:67]
	s_barrier
	s_add_i32 s30, s54, s38
	s_mov_b32 m0, s30
	s_nop 0
	global_load_lds_dwordx4 v205, s[28:29]
	s_add_i32 m0, s30, 0x2000
	s_add_u32 s28, s28, 0x40080
	s_addc_u32 s29, s29, 0
	s_add_i32 s30, s55, s38
	global_load_lds_dwordx4 v221, s[98:99]
	s_mov_b32 m0, s30
	s_nop 0
	global_load_lds_dwordx4 v130, s[28:29]
	s_add_i32 m0, s30, 0x2000
	s_nop 0
	global_load_lds_dwordx4 v134, s[28:29]
	s_mov_b32 m0, s44
	s_nop 0
	global_load_lds_dwordx4 v204, s[100:101]
	s_cmp_lg_u32 s53, 12
	s_cbranch_scc1 .Lbal_last_19
	s_mov_b32 m0, s45
	s_nop 0
	global_load_lds_dwordx4 v220, s[100:101]
.Lbal_last_19:
	ds_read_b128 v[184:187], v153 offset:49152
	ds_read_b128 v[188:191], v153 offset:50176
	ds_read_b128 v[192:195], v153 offset:51200
	ds_read_b128 v[196:199], v153 offset:52224
	ds_read_b128 v[200:203], v153 offset:53248
	ds_read_b128 v[208:211], v153 offset:54272
	ds_read_b128 v[212:215], v153 offset:55296
	ds_read_b128 v[216:219], v153 offset:56320
	s_waitcnt vmcnt(7)
	s_waitcnt lgkmcnt(0)
	s_barrier
	s_waitcnt lgkmcnt(0)
	v_mfma_f32_16x16x32_bf16 v[60:63], v[144:147], v[184:187], v[60:63]
	v_mfma_f32_16x16x32_bf16 v[56:59], v[160:163], v[184:187], v[56:59]
	v_mfma_f32_16x16x32_bf16 v[44:47], v[144:147], v[192:195], v[44:47]
	v_mfma_f32_16x16x32_bf16 v[40:43], v[160:163], v[192:195], v[40:43]
	v_mfma_f32_16x16x32_bf16 v[28:31], v[144:147], v[200:203], v[28:31]
	v_mfma_f32_16x16x32_bf16 v[24:27], v[160:163], v[200:203], v[24:27]
	v_mfma_f32_16x16x32_bf16 v[12:15], v[144:147], v[212:215], v[12:15]
	v_mfma_f32_16x16x32_bf16 v[8:11], v[160:163], v[212:215], v[8:11]
	v_mfma_f32_16x16x32_bf16 v[60:63], v[156:159], v[188:191], v[60:63]
	v_mfma_f32_16x16x32_bf16 v[56:59], v[164:167], v[188:191], v[56:59]
	v_mfma_f32_16x16x32_bf16 v[44:47], v[156:159], v[196:199], v[44:47]
	v_mfma_f32_16x16x32_bf16 v[40:43], v[164:167], v[196:199], v[40:43]
	v_mfma_f32_16x16x32_bf16 v[28:31], v[156:159], v[208:211], v[28:31]
	v_mfma_f32_16x16x32_bf16 v[24:27], v[164:167], v[208:211], v[24:27]
	v_mfma_f32_16x16x32_bf16 v[12:15], v[156:159], v[216:219], v[12:15]
	v_mfma_f32_16x16x32_bf16 v[8:11], v[164:167], v[216:219], v[8:11]
	v_mfma_f32_16x16x32_bf16 v[52:55], v[168:171], v[184:187], v[52:55]
	v_mfma_f32_16x16x32_bf16 v[48:51], v[176:179], v[184:187], v[48:51]
	v_mfma_f32_16x16x32_bf16 v[36:39], v[168:171], v[192:195], v[36:39]
	v_mfma_f32_16x16x32_bf16 v[32:35], v[176:179], v[192:195], v[32:35]
	v_mfma_f32_16x16x32_bf16 v[20:23], v[168:171], v[200:203], v[20:23]
	v_mfma_f32_16x16x32_bf16 v[16:19], v[176:179], v[200:203], v[16:19]
	v_mfma_f32_16x16x32_bf16 v[4:7], v[168:171], v[212:215], v[4:7]
	v_mfma_f32_16x16x32_bf16 v[0:3], v[176:179], v[212:215], v[0:3]
	v_mfma_f32_16x16x32_bf16 v[52:55], v[172:175], v[188:191], v[52:55]
	v_mfma_f32_16x16x32_bf16 v[48:51], v[180:183], v[188:191], v[48:51]
	v_mfma_f32_16x16x32_bf16 v[36:39], v[172:175], v[196:199], v[36:39]
	v_mfma_f32_16x16x32_bf16 v[32:35], v[180:183], v[196:199], v[32:35]
	v_mfma_f32_16x16x32_bf16 v[20:23], v[172:175], v[208:211], v[20:23]
	v_mfma_f32_16x16x32_bf16 v[16:19], v[180:183], v[208:211], v[16:19]
	v_mfma_f32_16x16x32_bf16 v[4:7], v[172:175], v[216:219], v[4:7]
	v_mfma_f32_16x16x32_bf16 v[0:3], v[180:183], v[216:219], v[0:3]
	s_barrier
	s_add_i32 s53, s53, 2
	s_add_u32 s51, s51, 0x100
	s_addc_u32 s52, s52, 0
	s_add_u32 s26, s26, 0x100
	s_addc_u32 s27, s27, 0
	s_cmp_gt_u32 s53, 13
	s_cbranch_scc0 .LBB0_699
	s_setprio 0
	s_and_b64 vcc, exec, s[16:17]
	s_cbranch_vccz .LBB0_702
	s_barrier

.Lbal_first_18:
	s_add_u32 s30, s28, 0x100
	s_addc_u32 s31, s29, 0
	s_cmp_eq_u32 s58, 60
	s_cselect_b32 s37, s21, s31
	s_cselect_b32 s36, s27, s30
	s_cselect_b32 s35, s19, s57
	s_cselect_b32 s34, s55, s56
	s_add_i32 m0, s44, 0xc000
	s_nop 0
	global_load_lds_dwordx4 v134, s[28:29]
	s_add_i32 m0, s44, 0xe000
	s_nop 0
	global_load_lds_dwordx4 v132, s[28:29]
	ds_read_b128 v[140:143], v147
	ds_read_b128 v[150:153], v147 offset:1024
	ds_read_b128 v[154:157], v147 offset:2048
	ds_read_b128 v[158:161], v147 offset:3072
	ds_read_b128 v[162:165], v148
	ds_read_b128 v[166:169], v148 offset:1024
	ds_read_b128 v[170:173], v148 offset:2048
	ds_read_b128 v[174:177], v148 offset:3072
	ds_read_b128 v[178:181], v149
	ds_read_b128 v[182:185], v149 offset:1024
	ds_read_b128 v[186:189], v149 offset:2048
	ds_read_b128 v[190:193], v149 offset:3072
	ds_read_b128 v[194:197], v149 offset:4096
	ds_read_b128 v[198:201], v149 offset:5120
	ds_read_b128 v[202:205], v149 offset:6144
	ds_read_b128 v[208:211], v149 offset:7168
	s_waitcnt vmcnt(8)
	s_waitcnt lgkmcnt(0)
	s_barrier
	s_waitcnt lgkmcnt(0)
	v_mfma_f32_16x16x32_bf16 v[124:127], v[140:143], v[178:181], v[124:127]
	v_mfma_f32_16x16x32_bf16 v[120:123], v[154:157], v[178:181], v[120:123]
	v_mfma_f32_16x16x32_bf16 v[108:111], v[140:143], v[186:189], v[108:111]
	v_mfma_f32_16x16x32_bf16 v[104:107], v[154:157], v[186:189], v[104:107]
	v_mfma_f32_16x16x32_bf16 v[92:95], v[140:143], v[194:197], v[92:95]
	v_mfma_f32_16x16x32_bf16 v[88:91], v[154:157], v[194:197], v[88:91]
	v_mfma_f32_16x16x32_bf16 v[76:79], v[140:143], v[202:205], v[76:79]
	v_mfma_f32_16x16x32_bf16 v[72:75], v[154:157], v[202:205], v[72:75]
	v_mfma_f32_16x16x32_bf16 v[124:127], v[150:153], v[182:185], v[124:127]
	v_mfma_f32_16x16x32_bf16 v[120:123], v[158:161], v[182:185], v[120:123]
	v_mfma_f32_16x16x32_bf16 v[108:111], v[150:153], v[190:193], v[108:111]
	v_mfma_f32_16x16x32_bf16 v[104:107], v[158:161], v[190:193], v[104:107]
	v_mfma_f32_16x16x32_bf16 v[92:95], v[150:153], v[198:201], v[92:95]
	v_mfma_f32_16x16x32_bf16 v[88:91], v[158:161], v[198:201], v[88:91]
	v_mfma_f32_16x16x32_bf16 v[76:79], v[150:153], v[208:211], v[76:79]
	v_mfma_f32_16x16x32_bf16 v[72:75], v[158:161], v[208:211], v[72:75]
	v_mfma_f32_16x16x32_bf16 v[116:119], v[162:165], v[178:181], v[116:119]
	v_mfma_f32_16x16x32_bf16 v[112:115], v[170:173], v[178:181], v[112:115]
	v_mfma_f32_16x16x32_bf16 v[100:103], v[162:165], v[186:189], v[100:103]
	v_mfma_f32_16x16x32_bf16 v[96:99], v[170:173], v[186:189], v[96:99]
	v_mfma_f32_16x16x32_bf16 v[84:87], v[162:165], v[194:197], v[84:87]
	v_mfma_f32_16x16x32_bf16 v[80:83], v[170:173], v[194:197], v[80:83]
	v_mfma_f32_16x16x32_bf16 v[68:71], v[162:165], v[202:205], v[68:71]
	v_mfma_f32_16x16x32_bf16 v[64:67], v[170:173], v[202:205], v[64:67]
	v_mfma_f32_16x16x32_bf16 v[116:119], v[166:169], v[182:185], v[116:119]
	v_mfma_f32_16x16x32_bf16 v[112:115], v[174:177], v[182:185], v[112:115]
	v_mfma_f32_16x16x32_bf16 v[100:103], v[166:169], v[190:193], v[100:103]
	v_mfma_f32_16x16x32_bf16 v[96:99], v[174:177], v[190:193], v[96:99]
	v_mfma_f32_16x16x32_bf16 v[84:87], v[166:169], v[198:201], v[84:87]
	v_mfma_f32_16x16x32_bf16 v[80:83], v[174:177], v[198:201], v[80:83]
	v_mfma_f32_16x16x32_bf16 v[68:71], v[166:169], v[208:211], v[68:71]
	v_mfma_f32_16x16x32_bf16 v[64:67], v[174:177], v[208:211], v[64:67]
	s_barrier
	s_add_i32 s28, s52, s43
	s_mov_b32 m0, s28
	s_nop 0
	global_load_lds_dwordx4 v128, s[34:35]
	s_add_i32 m0, s28, 0x2000
	s_add_u32 s28, s34, 0x100000
	s_mov_b64 s[98:99], s[34:35]
	s_addc_u32 s29, s35, 0
	s_add_i32 s59, s53, s43
	global_load_lds_dwordx4 v130, s[34:35]
	s_mov_b32 m0, s59
	s_nop 0
	global_load_lds_dwordx4 v128, s[28:29]
	s_add_i32 m0, s59, 0x2000
	s_nop 0
	global_load_lds_dwordx4 v130, s[28:29]
	s_mov_b32 m0, s44
	s_nop 0
	global_load_lds_dwordx4 v128, s[36:37]
	ds_read_b128 v[178:181], v149 offset:16384
	ds_read_b128 v[182:185], v149 offset:17408
	ds_read_b128 v[186:189], v149 offset:18432
	ds_read_b128 v[190:193], v149 offset:19456
	ds_read_b128 v[194:197], v149 offset:20480
	ds_read_b128 v[198:201], v149 offset:21504
	ds_read_b128 v[202:205], v149 offset:22528
	ds_read_b128 v[208:211], v149 offset:23552
	s_waitcnt vmcnt(7)
	s_waitcnt lgkmcnt(0)
	s_barrier
	s_waitcnt lgkmcnt(0)
	v_mfma_f32_16x16x32_bf16 v[60:63], v[140:143], v[178:181], v[60:63]
	v_mfma_f32_16x16x32_bf16 v[56:59], v[154:157], v[178:181], v[56:59]
	v_mfma_f32_16x16x32_bf16 v[44:47], v[140:143], v[186:189], v[44:47]
	v_mfma_f32_16x16x32_bf16 v[40:43], v[154:157], v[186:189], v[40:43]
	v_mfma_f32_16x16x32_bf16 v[28:31], v[140:143], v[194:197], v[28:31]
	v_mfma_f32_16x16x32_bf16 v[24:27], v[154:157], v[194:197], v[24:27]
	v_mfma_f32_16x16x32_bf16 v[12:15], v[140:143], v[202:205], v[12:15]
	v_mfma_f32_16x16x32_bf16 v[8:11], v[154:157], v[202:205], v[8:11]
	v_mfma_f32_16x16x32_bf16 v[60:63], v[150:153], v[182:185], v[60:63]
	v_mfma_f32_16x16x32_bf16 v[56:59], v[158:161], v[182:185], v[56:59]
	v_mfma_f32_16x16x32_bf16 v[44:47], v[150:153], v[190:193], v[44:47]
	v_mfma_f32_16x16x32_bf16 v[40:43], v[158:161], v[190:193], v[40:43]
	v_mfma_f32_16x16x32_bf16 v[28:31], v[150:153], v[198:201], v[28:31]
	v_mfma_f32_16x16x32_bf16 v[24:27], v[158:161], v[198:201], v[24:27]
	v_mfma_f32_16x16x32_bf16 v[12:15], v[150:153], v[208:211], v[12:15]
	v_mfma_f32_16x16x32_bf16 v[8:11], v[158:161], v[208:211], v[8:11]
	v_mfma_f32_16x16x32_bf16 v[52:55], v[162:165], v[178:181], v[52:55]
	v_mfma_f32_16x16x32_bf16 v[48:51], v[170:173], v[178:181], v[48:51]
	v_mfma_f32_16x16x32_bf16 v[36:39], v[162:165], v[186:189], v[36:39]
	v_mfma_f32_16x16x32_bf16 v[32:35], v[170:173], v[186:189], v[32:35]
	v_mfma_f32_16x16x32_bf16 v[20:23], v[162:165], v[194:197], v[20:23]
	v_mfma_f32_16x16x32_bf16 v[16:19], v[170:173], v[194:197], v[16:19]
	v_mfma_f32_16x16x32_bf16 v[4:7], v[162:165], v[202:205], v[4:7]
	v_mfma_f32_16x16x32_bf16 v[0:3], v[170:173], v[202:205], v[0:3]
	v_mfma_f32_16x16x32_bf16 v[52:55], v[166:169], v[182:185], v[52:55]
	v_mfma_f32_16x16x32_bf16 v[48:51], v[174:177], v[182:185], v[48:51]
	v_mfma_f32_16x16x32_bf16 v[36:39], v[166:169], v[190:193], v[36:39]
	v_mfma_f32_16x16x32_bf16 v[32:35], v[174:177], v[190:193], v[32:35]
	v_mfma_f32_16x16x32_bf16 v[20:23], v[166:169], v[198:201], v[20:23]
	v_mfma_f32_16x16x32_bf16 v[16:19], v[174:177], v[198:201], v[16:19]
	v_mfma_f32_16x16x32_bf16 v[4:7], v[166:169], v[208:211], v[4:7]
	v_mfma_f32_16x16x32_bf16 v[0:3], v[174:177], v[208:211], v[0:3]
	s_barrier
	s_mov_b32 m0, s45
	s_nop 0
	global_load_lds_dwordx4 v130, s[36:37]
	s_add_i32 s59, 0, 0x18000
	s_add_i32 s60, 0, 0x1c000
	s_add_u32 s28, s36, 0x100000
	s_addc_u32 s29, s37, 0
	s_mov_b32 m0, s46
	s_nop 0
	global_load_lds_dwordx4 v128, s[28:29]
	s_mov_b32 m0, s47
	s_nop 0
	global_load_lds_dwordx4 v130, s[28:29]
	v_add_u32_e32 v158, s59, v145
	v_add_u32_e32 v174, s60, v145
	ds_read_b128 v[140:143], v158
	ds_read_b128 v[150:153], v158 offset:1024
	ds_read_b128 v[154:157], v158 offset:2048
	ds_read_b128 v[158:161], v158 offset:3072
	ds_read_b128 v[162:165], v174
	ds_read_b128 v[166:169], v174 offset:1024
	ds_read_b128 v[170:173], v174 offset:2048
	ds_read_b128 v[174:177], v174 offset:3072
	ds_read_b128 v[178:181], v149 offset:32768
	ds_read_b128 v[182:185], v149 offset:33792
	ds_read_b128 v[186:189], v149 offset:34816
	ds_read_b128 v[190:193], v149 offset:35840
	ds_read_b128 v[194:197], v149 offset:36864
	ds_read_b128 v[198:201], v149 offset:37888
	ds_read_b128 v[202:205], v149 offset:38912
	ds_read_b128 v[208:211], v149 offset:39936
	s_waitcnt vmcnt(8)
	s_waitcnt lgkmcnt(0)
	s_barrier
	s_waitcnt lgkmcnt(0)
	v_mfma_f32_16x16x32_bf16 v[124:127], v[140:143], v[178:181], v[124:127]
	v_mfma_f32_16x16x32_bf16 v[120:123], v[154:157], v[178:181], v[120:123]
	v_mfma_f32_16x16x32_bf16 v[108:111], v[140:143], v[186:189], v[108:111]
	v_mfma_f32_16x16x32_bf16 v[104:107], v[154:157], v[186:189], v[104:107]
	v_mfma_f32_16x16x32_bf16 v[92:95], v[140:143], v[194:197], v[92:95]
	v_mfma_f32_16x16x32_bf16 v[88:91], v[154:157], v[194:197], v[88:91]
	v_mfma_f32_16x16x32_bf16 v[76:79], v[140:143], v[202:205], v[76:79]
	v_mfma_f32_16x16x32_bf16 v[72:75], v[154:157], v[202:205], v[72:75]
	v_mfma_f32_16x16x32_bf16 v[124:127], v[150:153], v[182:185], v[124:127]
	v_mfma_f32_16x16x32_bf16 v[120:123], v[158:161], v[182:185], v[120:123]
	v_mfma_f32_16x16x32_bf16 v[108:111], v[150:153], v[190:193], v[108:111]
	v_mfma_f32_16x16x32_bf16 v[104:107], v[158:161], v[190:193], v[104:107]
	v_mfma_f32_16x16x32_bf16 v[92:95], v[150:153], v[198:201], v[92:95]
	v_mfma_f32_16x16x32_bf16 v[88:91], v[158:161], v[198:201], v[88:91]
	v_mfma_f32_16x16x32_bf16 v[76:79], v[150:153], v[208:211], v[76:79]
	v_mfma_f32_16x16x32_bf16 v[72:75], v[158:161], v[208:211], v[72:75]
	v_mfma_f32_16x16x32_bf16 v[116:119], v[162:165], v[178:181], v[116:119]
	v_mfma_f32_16x16x32_bf16 v[112:115], v[170:173], v[178:181], v[112:115]
	v_mfma_f32_16x16x32_bf16 v[100:103], v[162:165], v[186:189], v[100:103]
	v_mfma_f32_16x16x32_bf16 v[96:99], v[170:173], v[186:189], v[96:99]
	v_mfma_f32_16x16x32_bf16 v[84:87], v[162:165], v[194:197], v[84:87]
	v_mfma_f32_16x16x32_bf16 v[80:83], v[170:173], v[194:197], v[80:83]
	v_mfma_f32_16x16x32_bf16 v[68:71], v[162:165], v[202:205], v[68:71]
	v_mfma_f32_16x16x32_bf16 v[64:67], v[170:173], v[202:205], v[64:67]
	v_mfma_f32_16x16x32_bf16 v[116:119], v[166:169], v[182:185], v[116:119]
	v_mfma_f32_16x16x32_bf16 v[112:115], v[174:177], v[182:185], v[112:115]
	v_mfma_f32_16x16x32_bf16 v[100:103], v[166:169], v[190:193], v[100:103]
	v_mfma_f32_16x16x32_bf16 v[96:99], v[174:177], v[190:193], v[96:99]
	v_mfma_f32_16x16x32_bf16 v[84:87], v[166:169], v[198:201], v[84:87]
	v_mfma_f32_16x16x32_bf16 v[80:83], v[174:177], v[198:201], v[80:83]
	v_mfma_f32_16x16x32_bf16 v[68:71], v[166:169], v[208:211], v[68:71]
	v_mfma_f32_16x16x32_bf16 v[64:67], v[174:177], v[208:211], v[64:67]
	s_barrier
	s_add_i32 s28, s59, s43
	s_mov_b32 m0, s28
	s_nop 0
	global_load_lds_dwordx4 v212, s[34:35]
	s_add_i32 m0, s28, 0x2000
	s_add_u32 s28, s34, 0x100080
	s_addc_u32 s29, s35, 0
	s_add_i32 s34, s60, s43
	global_load_lds_dwordx4 v213, s[98:99]
	s_mov_b32 m0, s34
	s_nop 0
	global_load_lds_dwordx4 v128, s[28:29]
	s_add_i32 m0, s34, 0x2000
	s_nop 0
	global_load_lds_dwordx4 v130, s[28:29]
	s_mov_b32 m0, s49
	s_nop 0
	global_load_lds_dwordx4 v212, s[36:37]
	s_cmp_lg_u32 s58, 60
	s_cbranch_scc1 .Lbal_last_18
	s_mov_b32 m0, s50
	s_nop 0
	global_load_lds_dwordx4 v213, s[36:37]
.Lbal_last_18:
	ds_read_b128 v[178:181], v149 offset:49152
	ds_read_b128 v[182:185], v149 offset:50176
	ds_read_b128 v[186:189], v149 offset:51200
	ds_read_b128 v[190:193], v149 offset:52224
	ds_read_b128 v[194:197], v149 offset:53248
	ds_read_b128 v[198:201], v149 offset:54272
	ds_read_b128 v[202:205], v149 offset:55296
	ds_read_b128 v[208:211], v149 offset:56320
	s_waitcnt vmcnt(7)
	s_waitcnt lgkmcnt(0)
	s_barrier
	s_waitcnt lgkmcnt(0)
	v_mfma_f32_16x16x32_bf16 v[60:63], v[140:143], v[178:181], v[60:63]
	v_mfma_f32_16x16x32_bf16 v[56:59], v[154:157], v[178:181], v[56:59]
	v_mfma_f32_16x16x32_bf16 v[44:47], v[140:143], v[186:189], v[44:47]
	v_mfma_f32_16x16x32_bf16 v[40:43], v[154:157], v[186:189], v[40:43]
	v_mfma_f32_16x16x32_bf16 v[28:31], v[140:143], v[194:197], v[28:31]
	v_mfma_f32_16x16x32_bf16 v[24:27], v[154:157], v[194:197], v[24:27]
	v_mfma_f32_16x16x32_bf16 v[12:15], v[140:143], v[202:205], v[12:15]
	v_mfma_f32_16x16x32_bf16 v[8:11], v[154:157], v[202:205], v[8:11]
	v_mfma_f32_16x16x32_bf16 v[60:63], v[150:153], v[182:185], v[60:63]
	v_mfma_f32_16x16x32_bf16 v[56:59], v[158:161], v[182:185], v[56:59]
	v_mfma_f32_16x16x32_bf16 v[44:47], v[150:153], v[190:193], v[44:47]
	v_mfma_f32_16x16x32_bf16 v[40:43], v[158:161], v[190:193], v[40:43]
	v_mfma_f32_16x16x32_bf16 v[28:31], v[150:153], v[198:201], v[28:31]
	v_mfma_f32_16x16x32_bf16 v[24:27], v[158:161], v[198:201], v[24:27]
	v_mfma_f32_16x16x32_bf16 v[12:15], v[150:153], v[208:211], v[12:15]
	v_mfma_f32_16x16x32_bf16 v[8:11], v[158:161], v[208:211], v[8:11]
	v_mfma_f32_16x16x32_bf16 v[52:55], v[162:165], v[178:181], v[52:55]
	v_mfma_f32_16x16x32_bf16 v[48:51], v[170:173], v[178:181], v[48:51]
	v_mfma_f32_16x16x32_bf16 v[36:39], v[162:165], v[186:189], v[36:39]
	v_mfma_f32_16x16x32_bf16 v[32:35], v[170:173], v[186:189], v[32:35]
	v_mfma_f32_16x16x32_bf16 v[20:23], v[162:165], v[194:197], v[20:23]
	v_mfma_f32_16x16x32_bf16 v[16:19], v[170:173], v[194:197], v[16:19]
	v_mfma_f32_16x16x32_bf16 v[4:7], v[162:165], v[202:205], v[4:7]
	v_mfma_f32_16x16x32_bf16 v[0:3], v[170:173], v[202:205], v[0:3]
	v_mfma_f32_16x16x32_bf16 v[52:55], v[166:169], v[182:185], v[52:55]
	v_mfma_f32_16x16x32_bf16 v[48:51], v[174:177], v[182:185], v[48:51]
	v_mfma_f32_16x16x32_bf16 v[36:39], v[166:169], v[190:193], v[36:39]
	v_mfma_f32_16x16x32_bf16 v[32:35], v[174:177], v[190:193], v[32:35]
	v_mfma_f32_16x16x32_bf16 v[20:23], v[166:169], v[198:201], v[20:23]
	v_mfma_f32_16x16x32_bf16 v[16:19], v[174:177], v[198:201], v[16:19]
	v_mfma_f32_16x16x32_bf16 v[4:7], v[166:169], v[208:211], v[4:7]
	v_mfma_f32_16x16x32_bf16 v[0:3], v[174:177], v[208:211], v[0:3]
	s_barrier
	s_add_i32 s58, s58, 2
	s_add_u32 s56, s56, 0x100
	s_addc_u32 s57, s57, 0
	s_cmp_gt_u32 s58, 61
	s_mov_b64 s[28:29], s[30:31]
	s_cbranch_scc0 .LBB0_778
	s_setprio 0
	s_and_b64 vcc, exec, s[16:17]
	s_cbranch_vccz .LBB0_781
	s_barrier

.Lbal_first_17:
	s_add_u32 s38, s36, 0xfffc0080
	s_addc_u32 s39, s37, -1
	s_cmp_eq_u32 s61, 12
	s_cselect_b32 s41, s3, s39
	s_cselect_b32 s40, s29, s38
	s_cselect_b32 s39, s27, s60
	s_cselect_b32 s38, s58, s59
	s_add_i32 m0, s46, 0xc000
	s_nop 0
	global_load_lds_dwordx4 v134, s[36:37]
	s_add_i32 m0, s46, 0xe000
	s_nop 0
	global_load_lds_dwordx4 v132, s[36:37]
	ds_read_b128 v[140:143], v153
	ds_read_b128 v[144:147], v153 offset:1024
	ds_read_b128 v[158:161], v153 offset:2048
	ds_read_b128 v[162:165], v153 offset:3072
	ds_read_b128 v[166:169], v154
	ds_read_b128 v[170:173], v154 offset:1024
	ds_read_b128 v[174:177], v154 offset:2048
	ds_read_b128 v[178:181], v154 offset:3072
	ds_read_b128 v[182:185], v155
	ds_read_b128 v[186:189], v155 offset:1024
	ds_read_b128 v[190:193], v155 offset:2048
	ds_read_b128 v[194:197], v155 offset:3072
	ds_read_b128 v[198:201], v155 offset:4096
	ds_read_b128 v[202:205], v155 offset:5120
	ds_read_b128 v[208:211], v155 offset:6144
	ds_read_b128 v[212:215], v155 offset:7168
	s_waitcnt vmcnt(8)
	s_waitcnt lgkmcnt(0)
	s_barrier
	s_waitcnt lgkmcnt(0)
	v_mfma_f32_16x16x32_bf16 v[124:127], v[140:143], v[182:185], v[124:127]
	v_mfma_f32_16x16x32_bf16 v[120:123], v[158:161], v[182:185], v[120:123]
	v_mfma_f32_16x16x32_bf16 v[108:111], v[140:143], v[190:193], v[108:111]
	v_mfma_f32_16x16x32_bf16 v[104:107], v[158:161], v[190:193], v[104:107]
	v_mfma_f32_16x16x32_bf16 v[92:95], v[140:143], v[198:201], v[92:95]
	v_mfma_f32_16x16x32_bf16 v[88:91], v[158:161], v[198:201], v[88:91]
	v_mfma_f32_16x16x32_bf16 v[76:79], v[140:143], v[208:211], v[76:79]
	v_mfma_f32_16x16x32_bf16 v[72:75], v[158:161], v[208:211], v[72:75]
	v_mfma_f32_16x16x32_bf16 v[124:127], v[144:147], v[186:189], v[124:127]
	v_mfma_f32_16x16x32_bf16 v[120:123], v[162:165], v[186:189], v[120:123]
	v_mfma_f32_16x16x32_bf16 v[108:111], v[144:147], v[194:197], v[108:111]
	v_mfma_f32_16x16x32_bf16 v[104:107], v[162:165], v[194:197], v[104:107]
	v_mfma_f32_16x16x32_bf16 v[92:95], v[144:147], v[202:205], v[92:95]
	v_mfma_f32_16x16x32_bf16 v[88:91], v[162:165], v[202:205], v[88:91]
	v_mfma_f32_16x16x32_bf16 v[76:79], v[144:147], v[212:215], v[76:79]
	v_mfma_f32_16x16x32_bf16 v[72:75], v[162:165], v[212:215], v[72:75]
	v_mfma_f32_16x16x32_bf16 v[116:119], v[166:169], v[182:185], v[116:119]
	v_mfma_f32_16x16x32_bf16 v[112:115], v[174:177], v[182:185], v[112:115]
	v_mfma_f32_16x16x32_bf16 v[100:103], v[166:169], v[190:193], v[100:103]
	v_mfma_f32_16x16x32_bf16 v[96:99], v[174:177], v[190:193], v[96:99]
	v_mfma_f32_16x16x32_bf16 v[84:87], v[166:169], v[198:201], v[84:87]
	v_mfma_f32_16x16x32_bf16 v[80:83], v[174:177], v[198:201], v[80:83]
	v_mfma_f32_16x16x32_bf16 v[68:71], v[166:169], v[208:211], v[68:71]
	v_mfma_f32_16x16x32_bf16 v[64:67], v[174:177], v[208:211], v[64:67]
	v_mfma_f32_16x16x32_bf16 v[116:119], v[170:173], v[186:189], v[116:119]
	v_mfma_f32_16x16x32_bf16 v[112:115], v[178:181], v[186:189], v[112:115]
	v_mfma_f32_16x16x32_bf16 v[100:103], v[170:173], v[194:197], v[100:103]
	v_mfma_f32_16x16x32_bf16 v[96:99], v[178:181], v[194:197], v[96:99]
	v_mfma_f32_16x16x32_bf16 v[84:87], v[170:173], v[202:205], v[84:87]
	v_mfma_f32_16x16x32_bf16 v[80:83], v[178:181], v[202:205], v[80:83]
	v_mfma_f32_16x16x32_bf16 v[68:71], v[170:173], v[212:215], v[68:71]
	v_mfma_f32_16x16x32_bf16 v[64:67], v[178:181], v[212:215], v[64:67]
	s_barrier
	s_add_i32 s62, s54, s45
	s_mov_b32 m0, s62
	s_nop 0
	global_load_lds_dwordx4 v128, s[38:39]
	s_add_i32 m0, s62, 0x2000
	s_add_u32 s62, s38, 0x40000
	s_mov_b64 s[98:99], s[38:39]
	s_addc_u32 s63, s39, 0
	s_add_i32 s64, s55, s45
	global_load_lds_dwordx4 v130, s[38:39]
	s_mov_b32 m0, s64
	s_mov_b64 s[100:101], s[40:41]
	global_load_lds_dwordx4 v128, s[62:63]
	s_add_i32 m0, s64, 0x2000
	s_nop 0
	global_load_lds_dwordx4 v130, s[62:63]
	s_mov_b32 m0, s46
	s_nop 0
	global_load_lds_dwordx4 v128, s[40:41]
	ds_read_b128 v[182:185], v155 offset:16384
	ds_read_b128 v[186:189], v155 offset:17408
	ds_read_b128 v[190:193], v155 offset:18432
	ds_read_b128 v[194:197], v155 offset:19456
	ds_read_b128 v[198:201], v155 offset:20480
	ds_read_b128 v[202:205], v155 offset:21504
	ds_read_b128 v[208:211], v155 offset:22528
	ds_read_b128 v[212:215], v155 offset:23552
	s_waitcnt vmcnt(7)
	s_waitcnt lgkmcnt(0)
	s_barrier
	s_waitcnt lgkmcnt(0)
	v_mfma_f32_16x16x32_bf16 v[60:63], v[140:143], v[182:185], v[60:63]
	v_mfma_f32_16x16x32_bf16 v[56:59], v[158:161], v[182:185], v[56:59]
	v_mfma_f32_16x16x32_bf16 v[44:47], v[140:143], v[190:193], v[44:47]
	v_mfma_f32_16x16x32_bf16 v[40:43], v[158:161], v[190:193], v[40:43]
	v_mfma_f32_16x16x32_bf16 v[28:31], v[140:143], v[198:201], v[28:31]
	v_mfma_f32_16x16x32_bf16 v[24:27], v[158:161], v[198:201], v[24:27]
	v_mfma_f32_16x16x32_bf16 v[12:15], v[140:143], v[208:211], v[12:15]
	v_mfma_f32_16x16x32_bf16 v[8:11], v[158:161], v[208:211], v[8:11]
	v_mfma_f32_16x16x32_bf16 v[60:63], v[144:147], v[186:189], v[60:63]
	v_mfma_f32_16x16x32_bf16 v[56:59], v[162:165], v[186:189], v[56:59]
	v_mfma_f32_16x16x32_bf16 v[44:47], v[144:147], v[194:197], v[44:47]
	v_mfma_f32_16x16x32_bf16 v[40:43], v[162:165], v[194:197], v[40:43]
	v_mfma_f32_16x16x32_bf16 v[28:31], v[144:147], v[202:205], v[28:31]
	v_mfma_f32_16x16x32_bf16 v[24:27], v[162:165], v[202:205], v[24:27]
	v_mfma_f32_16x16x32_bf16 v[12:15], v[144:147], v[212:215], v[12:15]
	v_mfma_f32_16x16x32_bf16 v[8:11], v[162:165], v[212:215], v[8:11]
	v_mfma_f32_16x16x32_bf16 v[52:55], v[166:169], v[182:185], v[52:55]
	v_mfma_f32_16x16x32_bf16 v[48:51], v[174:177], v[182:185], v[48:51]
	v_mfma_f32_16x16x32_bf16 v[36:39], v[166:169], v[190:193], v[36:39]
	v_mfma_f32_16x16x32_bf16 v[32:35], v[174:177], v[190:193], v[32:35]
	v_mfma_f32_16x16x32_bf16 v[20:23], v[166:169], v[198:201], v[20:23]
	v_mfma_f32_16x16x32_bf16 v[16:19], v[174:177], v[198:201], v[16:19]
	v_mfma_f32_16x16x32_bf16 v[4:7], v[166:169], v[208:211], v[4:7]
	v_mfma_f32_16x16x32_bf16 v[0:3], v[174:177], v[208:211], v[0:3]
	v_mfma_f32_16x16x32_bf16 v[52:55], v[170:173], v[186:189], v[52:55]
	v_mfma_f32_16x16x32_bf16 v[48:51], v[178:181], v[186:189], v[48:51]
	v_mfma_f32_16x16x32_bf16 v[36:39], v[170:173], v[194:197], v[36:39]
	v_mfma_f32_16x16x32_bf16 v[32:35], v[178:181], v[194:197], v[32:35]
	v_mfma_f32_16x16x32_bf16 v[20:23], v[170:173], v[202:205], v[20:23]
	v_mfma_f32_16x16x32_bf16 v[16:19], v[178:181], v[202:205], v[16:19]
	v_mfma_f32_16x16x32_bf16 v[4:7], v[170:173], v[212:215], v[4:7]
	v_mfma_f32_16x16x32_bf16 v[0:3], v[178:181], v[212:215], v[0:3]
	s_barrier
	s_mov_b32 m0, s47
	s_nop 0
	global_load_lds_dwordx4 v130, s[40:41]
	s_add_i32 s62, 0, 0x18000
	s_add_i32 s63, 0, 0x1c000
	s_add_u32 s40, s40, 0x40000
	s_addc_u32 s41, s41, 0
	s_mov_b32 m0, s48
	s_nop 0
	global_load_lds_dwordx4 v128, s[40:41]
	s_mov_b32 m0, s49
	s_nop 0
	global_load_lds_dwordx4 v130, s[40:41]
	v_add_u32_e32 v157, s62, v151
	ds_read_b128 v[140:143], v157
	ds_read_b128 v[144:147], v157 offset:1024
	ds_read_b128 v[158:161], v157 offset:2048
	ds_read_b128 v[162:165], v157 offset:3072
	v_add_u32_e32 v157, s63, v151
	ds_read_b128 v[166:169], v157
	ds_read_b128 v[170:173], v157 offset:1024
	ds_read_b128 v[174:177], v157 offset:2048
	ds_read_b128 v[178:181], v157 offset:3072
	ds_read_b128 v[182:185], v155 offset:32768
	ds_read_b128 v[186:189], v155 offset:33792
	ds_read_b128 v[190:193], v155 offset:34816
	ds_read_b128 v[194:197], v155 offset:35840
	ds_read_b128 v[198:201], v155 offset:36864
	ds_read_b128 v[202:205], v155 offset:37888
	ds_read_b128 v[208:211], v155 offset:38912
	ds_read_b128 v[212:215], v155 offset:39936
	s_waitcnt vmcnt(8)
	s_waitcnt lgkmcnt(0)
	s_barrier
	s_waitcnt lgkmcnt(0)
	v_mfma_f32_16x16x32_bf16 v[124:127], v[140:143], v[182:185], v[124:127]
	v_mfma_f32_16x16x32_bf16 v[120:123], v[158:161], v[182:185], v[120:123]
	v_mfma_f32_16x16x32_bf16 v[108:111], v[140:143], v[190:193], v[108:111]
	v_mfma_f32_16x16x32_bf16 v[104:107], v[158:161], v[190:193], v[104:107]
	v_mfma_f32_16x16x32_bf16 v[92:95], v[140:143], v[198:201], v[92:95]
	v_mfma_f32_16x16x32_bf16 v[88:91], v[158:161], v[198:201], v[88:91]
	v_mfma_f32_16x16x32_bf16 v[76:79], v[140:143], v[208:211], v[76:79]
	v_mfma_f32_16x16x32_bf16 v[72:75], v[158:161], v[208:211], v[72:75]
	v_mfma_f32_16x16x32_bf16 v[124:127], v[144:147], v[186:189], v[124:127]
	v_mfma_f32_16x16x32_bf16 v[120:123], v[162:165], v[186:189], v[120:123]
	v_mfma_f32_16x16x32_bf16 v[108:111], v[144:147], v[194:197], v[108:111]
	v_mfma_f32_16x16x32_bf16 v[104:107], v[162:165], v[194:197], v[104:107]
	v_mfma_f32_16x16x32_bf16 v[92:95], v[144:147], v[202:205], v[92:95]
	v_mfma_f32_16x16x32_bf16 v[88:91], v[162:165], v[202:205], v[88:91]
	v_mfma_f32_16x16x32_bf16 v[76:79], v[144:147], v[212:215], v[76:79]
	v_mfma_f32_16x16x32_bf16 v[72:75], v[162:165], v[212:215], v[72:75]
	v_mfma_f32_16x16x32_bf16 v[116:119], v[166:169], v[182:185], v[116:119]
	v_mfma_f32_16x16x32_bf16 v[112:115], v[174:177], v[182:185], v[112:115]
	v_mfma_f32_16x16x32_bf16 v[100:103], v[166:169], v[190:193], v[100:103]
	v_mfma_f32_16x16x32_bf16 v[96:99], v[174:177], v[190:193], v[96:99]
	v_mfma_f32_16x16x32_bf16 v[84:87], v[166:169], v[198:201], v[84:87]
	v_mfma_f32_16x16x32_bf16 v[80:83], v[174:177], v[198:201], v[80:83]
	v_mfma_f32_16x16x32_bf16 v[68:71], v[166:169], v[208:211], v[68:71]
	v_mfma_f32_16x16x32_bf16 v[64:67], v[174:177], v[208:211], v[64:67]
	v_mfma_f32_16x16x32_bf16 v[116:119], v[170:173], v[186:189], v[116:119]
	v_mfma_f32_16x16x32_bf16 v[112:115], v[178:181], v[186:189], v[112:115]
	v_mfma_f32_16x16x32_bf16 v[100:103], v[170:173], v[194:197], v[100:103]
	v_mfma_f32_16x16x32_bf16 v[96:99], v[178:181], v[194:197], v[96:99]
	v_mfma_f32_16x16x32_bf16 v[84:87], v[170:173], v[202:205], v[84:87]
	v_mfma_f32_16x16x32_bf16 v[80:83], v[178:181], v[202:205], v[80:83]
	v_mfma_f32_16x16x32_bf16 v[68:71], v[170:173], v[212:215], v[68:71]
	v_mfma_f32_16x16x32_bf16 v[64:67], v[178:181], v[212:215], v[64:67]
	s_barrier
	s_add_i32 s40, s62, s45
	s_mov_b32 m0, s40
	s_nop 0
	global_load_lds_dwordx4 v148, s[38:39]
	s_add_i32 m0, s40, 0x2000
	s_add_u32 s38, s38, 0x40080
	s_addc_u32 s39, s39, 0
	s_add_i32 s40, s63, s45
	global_load_lds_dwordx4 v149, s[98:99]
	s_mov_b32 m0, s40
	s_nop 0
	global_load_lds_dwordx4 v128, s[38:39]
	s_add_i32 m0, s40, 0x2000
	s_nop 0
	global_load_lds_dwordx4 v130, s[38:39]
	s_mov_b32 m0, s51
	s_nop 0
	global_load_lds_dwordx4 v148, s[100:101]
	s_cmp_lg_u32 s61, 12
	s_cbranch_scc1 .Lbal_last_17
	s_mov_b32 m0, s52
	s_nop 0
	global_load_lds_dwordx4 v149, s[100:101]
.Lbal_last_17:
	ds_read_b128 v[182:185], v155 offset:49152
	ds_read_b128 v[186:189], v155 offset:50176
	ds_read_b128 v[190:193], v155 offset:51200
	ds_read_b128 v[194:197], v155 offset:52224
	ds_read_b128 v[198:201], v155 offset:53248
	ds_read_b128 v[202:205], v155 offset:54272
	ds_read_b128 v[208:211], v155 offset:55296
	ds_read_b128 v[212:215], v155 offset:56320
	s_waitcnt vmcnt(7)
	s_waitcnt lgkmcnt(0)
	s_barrier
	s_waitcnt lgkmcnt(0)
	v_mfma_f32_16x16x32_bf16 v[60:63], v[140:143], v[182:185], v[60:63]
	v_mfma_f32_16x16x32_bf16 v[56:59], v[158:161], v[182:185], v[56:59]
	v_mfma_f32_16x16x32_bf16 v[44:47], v[140:143], v[190:193], v[44:47]
	v_mfma_f32_16x16x32_bf16 v[40:43], v[158:161], v[190:193], v[40:43]
	v_mfma_f32_16x16x32_bf16 v[28:31], v[140:143], v[198:201], v[28:31]
	v_mfma_f32_16x16x32_bf16 v[24:27], v[158:161], v[198:201], v[24:27]
	v_mfma_f32_16x16x32_bf16 v[12:15], v[140:143], v[208:211], v[12:15]
	v_mfma_f32_16x16x32_bf16 v[8:11], v[158:161], v[208:211], v[8:11]
	v_mfma_f32_16x16x32_bf16 v[60:63], v[144:147], v[186:189], v[60:63]
	v_mfma_f32_16x16x32_bf16 v[56:59], v[162:165], v[186:189], v[56:59]
	v_mfma_f32_16x16x32_bf16 v[44:47], v[144:147], v[194:197], v[44:47]
	v_mfma_f32_16x16x32_bf16 v[40:43], v[162:165], v[194:197], v[40:43]
	v_mfma_f32_16x16x32_bf16 v[28:31], v[144:147], v[202:205], v[28:31]
	v_mfma_f32_16x16x32_bf16 v[24:27], v[162:165], v[202:205], v[24:27]
	v_mfma_f32_16x16x32_bf16 v[12:15], v[144:147], v[212:215], v[12:15]
	v_mfma_f32_16x16x32_bf16 v[8:11], v[162:165], v[212:215], v[8:11]
	v_mfma_f32_16x16x32_bf16 v[52:55], v[166:169], v[182:185], v[52:55]
	v_mfma_f32_16x16x32_bf16 v[48:51], v[174:177], v[182:185], v[48:51]
	v_mfma_f32_16x16x32_bf16 v[36:39], v[166:169], v[190:193], v[36:39]
	v_mfma_f32_16x16x32_bf16 v[32:35], v[174:177], v[190:193], v[32:35]
	v_mfma_f32_16x16x32_bf16 v[20:23], v[166:169], v[198:201], v[20:23]
	v_mfma_f32_16x16x32_bf16 v[16:19], v[174:177], v[198:201], v[16:19]
	v_mfma_f32_16x16x32_bf16 v[4:7], v[166:169], v[208:211], v[4:7]
	v_mfma_f32_16x16x32_bf16 v[0:3], v[174:177], v[208:211], v[0:3]
	v_mfma_f32_16x16x32_bf16 v[52:55], v[170:173], v[186:189], v[52:55]
	v_mfma_f32_16x16x32_bf16 v[48:51], v[178:181], v[186:189], v[48:51]
	v_mfma_f32_16x16x32_bf16 v[36:39], v[170:173], v[194:197], v[36:39]
	v_mfma_f32_16x16x32_bf16 v[32:35], v[178:181], v[194:197], v[32:35]
	v_mfma_f32_16x16x32_bf16 v[20:23], v[170:173], v[202:205], v[20:23]
	v_mfma_f32_16x16x32_bf16 v[16:19], v[178:181], v[202:205], v[16:19]
	v_mfma_f32_16x16x32_bf16 v[4:7], v[170:173], v[212:215], v[4:7]
	v_mfma_f32_16x16x32_bf16 v[0:3], v[178:181], v[212:215], v[0:3]
	s_barrier
	s_add_i32 s61, s61, 2
	s_add_u32 s59, s59, 0x100
	s_addc_u32 s60, s60, 0
	s_add_u32 s36, s36, 0x100
	s_addc_u32 s37, s37, 0
	s_cmp_gt_u32 s61, 13
	s_cbranch_scc0 .LBB0_895
	s_setprio 0
	s_and_b64 vcc, exec, s[24:25]
	s_cbranch_vccz .LBB0_898
	s_barrier

.Lbal_first_16:
	s_add_u32 s26, s6, 0xfffc0080
	s_addc_u32 s27, s7, -1
	s_cmp_eq_u32 s53, 12
	s_cselect_b32 s29, s19, s27
	s_cselect_b32 s28, s49, s26
	s_cselect_b32 s27, s17, s52
	s_cselect_b32 s26, s50, s51
	s_add_i32 m0, s25, 0xc000
	s_nop 0
	global_load_lds_dwordx4 v138, s[6:7]
	s_add_i32 m0, s25, 0xe000
	s_nop 0
	global_load_lds_dwordx4 v136, s[6:7]
	ds_read_b128 v[144:147], v151
	ds_read_b128 v[156:159], v151 offset:1024
	ds_read_b128 v[160:163], v151 offset:2048
	ds_read_b128 v[164:167], v151 offset:3072
	ds_read_b128 v[168:171], v152
	ds_read_b128 v[172:175], v152 offset:1024
	ds_read_b128 v[176:179], v152 offset:2048
	ds_read_b128 v[180:183], v152 offset:3072
	ds_read_b128 v[184:187], v153
	ds_read_b128 v[188:191], v153 offset:1024
	ds_read_b128 v[192:195], v153 offset:2048
	ds_read_b128 v[196:199], v153 offset:3072
	ds_read_b128 v[200:203], v153 offset:4096
	ds_read_b128 v[208:211], v153 offset:5120
	ds_read_b128 v[212:215], v153 offset:6144
	ds_read_b128 v[216:219], v153 offset:7168
	s_waitcnt vmcnt(8)
	s_waitcnt lgkmcnt(0)
	s_barrier
	s_waitcnt lgkmcnt(0)
	v_mfma_f32_16x16x32_bf16 v[124:127], v[144:147], v[184:187], v[124:127]
	v_mfma_f32_16x16x32_bf16 v[120:123], v[160:163], v[184:187], v[120:123]
	v_mfma_f32_16x16x32_bf16 v[108:111], v[144:147], v[192:195], v[108:111]
	v_mfma_f32_16x16x32_bf16 v[104:107], v[160:163], v[192:195], v[104:107]
	v_mfma_f32_16x16x32_bf16 v[92:95], v[144:147], v[200:203], v[92:95]
	v_mfma_f32_16x16x32_bf16 v[88:91], v[160:163], v[200:203], v[88:91]
	v_mfma_f32_16x16x32_bf16 v[76:79], v[144:147], v[212:215], v[76:79]
	v_mfma_f32_16x16x32_bf16 v[72:75], v[160:163], v[212:215], v[72:75]
	v_mfma_f32_16x16x32_bf16 v[124:127], v[156:159], v[188:191], v[124:127]
	v_mfma_f32_16x16x32_bf16 v[120:123], v[164:167], v[188:191], v[120:123]
	v_mfma_f32_16x16x32_bf16 v[108:111], v[156:159], v[196:199], v[108:111]
	v_mfma_f32_16x16x32_bf16 v[104:107], v[164:167], v[196:199], v[104:107]
	v_mfma_f32_16x16x32_bf16 v[92:95], v[156:159], v[208:211], v[92:95]
	v_mfma_f32_16x16x32_bf16 v[88:91], v[164:167], v[208:211], v[88:91]
	v_mfma_f32_16x16x32_bf16 v[76:79], v[156:159], v[216:219], v[76:79]
	v_mfma_f32_16x16x32_bf16 v[72:75], v[164:167], v[216:219], v[72:75]
	v_mfma_f32_16x16x32_bf16 v[116:119], v[168:171], v[184:187], v[116:119]
	v_mfma_f32_16x16x32_bf16 v[112:115], v[176:179], v[184:187], v[112:115]
	v_mfma_f32_16x16x32_bf16 v[100:103], v[168:171], v[192:195], v[100:103]
	v_mfma_f32_16x16x32_bf16 v[96:99], v[176:179], v[192:195], v[96:99]
	v_mfma_f32_16x16x32_bf16 v[84:87], v[168:171], v[200:203], v[84:87]
	v_mfma_f32_16x16x32_bf16 v[80:83], v[176:179], v[200:203], v[80:83]
	v_mfma_f32_16x16x32_bf16 v[68:71], v[168:171], v[212:215], v[68:71]
	v_mfma_f32_16x16x32_bf16 v[64:67], v[176:179], v[212:215], v[64:67]
	v_mfma_f32_16x16x32_bf16 v[116:119], v[172:175], v[188:191], v[116:119]
	v_mfma_f32_16x16x32_bf16 v[112:115], v[180:183], v[188:191], v[112:115]
	v_mfma_f32_16x16x32_bf16 v[100:103], v[172:175], v[196:199], v[100:103]
	v_mfma_f32_16x16x32_bf16 v[96:99], v[180:183], v[196:199], v[96:99]
	v_mfma_f32_16x16x32_bf16 v[84:87], v[172:175], v[208:211], v[84:87]
	v_mfma_f32_16x16x32_bf16 v[80:83], v[180:183], v[208:211], v[80:83]
	v_mfma_f32_16x16x32_bf16 v[68:71], v[172:175], v[216:219], v[68:71]
	v_mfma_f32_16x16x32_bf16 v[64:67], v[180:183], v[216:219], v[64:67]
	s_barrier
	s_add_i32 s54, s45, s38
	s_mov_b32 m0, s54
	s_nop 0
	global_load_lds_dwordx4 v130, s[26:27]
	s_add_i32 m0, s54, 0x2000
	s_add_u32 s54, s26, 0x40000
	s_mov_b64 s[98:99], s[26:27]
	s_addc_u32 s55, s27, 0
	s_add_i32 s56, s46, s38
	global_load_lds_dwordx4 v134, s[26:27]
	s_mov_b32 m0, s56
	s_mov_b64 s[100:101], s[28:29]
	global_load_lds_dwordx4 v130, s[54:55]
	s_add_i32 m0, s56, 0x2000
	s_nop 0
	global_load_lds_dwordx4 v134, s[54:55]
	s_mov_b32 m0, s25
	s_nop 0
	global_load_lds_dwordx4 v128, s[28:29]
	ds_read_b128 v[184:187], v153 offset:16384
	ds_read_b128 v[188:191], v153 offset:17408
	ds_read_b128 v[192:195], v153 offset:18432
	ds_read_b128 v[196:199], v153 offset:19456
	ds_read_b128 v[200:203], v153 offset:20480
	ds_read_b128 v[208:211], v153 offset:21504
	ds_read_b128 v[212:215], v153 offset:22528
	ds_read_b128 v[216:219], v153 offset:23552
	s_waitcnt vmcnt(7)
	s_waitcnt lgkmcnt(0)
	s_barrier
	s_waitcnt lgkmcnt(0)
	v_mfma_f32_16x16x32_bf16 v[60:63], v[144:147], v[184:187], v[60:63]
	v_mfma_f32_16x16x32_bf16 v[56:59], v[160:163], v[184:187], v[56:59]
	v_mfma_f32_16x16x32_bf16 v[44:47], v[144:147], v[192:195], v[44:47]
	v_mfma_f32_16x16x32_bf16 v[40:43], v[160:163], v[192:195], v[40:43]
	v_mfma_f32_16x16x32_bf16 v[28:31], v[144:147], v[200:203], v[28:31]
	v_mfma_f32_16x16x32_bf16 v[24:27], v[160:163], v[200:203], v[24:27]
	v_mfma_f32_16x16x32_bf16 v[12:15], v[144:147], v[212:215], v[12:15]
	v_mfma_f32_16x16x32_bf16 v[8:11], v[160:163], v[212:215], v[8:11]
	v_mfma_f32_16x16x32_bf16 v[60:63], v[156:159], v[188:191], v[60:63]
	v_mfma_f32_16x16x32_bf16 v[56:59], v[164:167], v[188:191], v[56:59]
	v_mfma_f32_16x16x32_bf16 v[44:47], v[156:159], v[196:199], v[44:47]
	v_mfma_f32_16x16x32_bf16 v[40:43], v[164:167], v[196:199], v[40:43]
	v_mfma_f32_16x16x32_bf16 v[28:31], v[156:159], v[208:211], v[28:31]
	v_mfma_f32_16x16x32_bf16 v[24:27], v[164:167], v[208:211], v[24:27]
	v_mfma_f32_16x16x32_bf16 v[12:15], v[156:159], v[216:219], v[12:15]
	v_mfma_f32_16x16x32_bf16 v[8:11], v[164:167], v[216:219], v[8:11]
	v_mfma_f32_16x16x32_bf16 v[52:55], v[168:171], v[184:187], v[52:55]
	v_mfma_f32_16x16x32_bf16 v[48:51], v[176:179], v[184:187], v[48:51]
	v_mfma_f32_16x16x32_bf16 v[36:39], v[168:171], v[192:195], v[36:39]
	v_mfma_f32_16x16x32_bf16 v[32:35], v[176:179], v[192:195], v[32:35]
	v_mfma_f32_16x16x32_bf16 v[20:23], v[168:171], v[200:203], v[20:23]
	v_mfma_f32_16x16x32_bf16 v[16:19], v[176:179], v[200:203], v[16:19]
	v_mfma_f32_16x16x32_bf16 v[4:7], v[168:171], v[212:215], v[4:7]
	v_mfma_f32_16x16x32_bf16 v[0:3], v[176:179], v[212:215], v[0:3]
	v_mfma_f32_16x16x32_bf16 v[52:55], v[172:175], v[188:191], v[52:55]
	v_mfma_f32_16x16x32_bf16 v[48:51], v[180:183], v[188:191], v[48:51]
	v_mfma_f32_16x16x32_bf16 v[36:39], v[172:175], v[196:199], v[36:39]
	v_mfma_f32_16x16x32_bf16 v[32:35], v[180:183], v[196:199], v[32:35]
	v_mfma_f32_16x16x32_bf16 v[20:23], v[172:175], v[208:211], v[20:23]
	v_mfma_f32_16x16x32_bf16 v[16:19], v[180:183], v[208:211], v[16:19]
	v_mfma_f32_16x16x32_bf16 v[4:7], v[172:175], v[216:219], v[4:7]
	v_mfma_f32_16x16x32_bf16 v[0:3], v[180:183], v[216:219], v[0:3]
	s_barrier
	s_mov_b32 m0, s39
	s_nop 0
	global_load_lds_dwordx4 v132, s[28:29]
	s_add_i32 s54, 0, 0x18000
	s_add_i32 s55, 0, 0x1c000
	s_add_u32 s28, s28, 0x40000
	s_addc_u32 s29, s29, 0
	s_mov_b32 m0, s40
	s_nop 0
	global_load_lds_dwordx4 v128, s[28:29]
	s_mov_b32 m0, s41
	s_nop 0
	global_load_lds_dwordx4 v132, s[28:29]
	v_add_u32_e32 v155, s54, v149
	ds_read_b128 v[144:147], v155
	ds_read_b128 v[156:159], v155 offset:1024
	ds_read_b128 v[160:163], v155 offset:2048
	ds_read_b128 v[164:167], v155 offset:3072
	v_add_u32_e32 v155, s55, v149
	ds_read_b128 v[168:171], v155
	ds_read_b128 v[172:175], v155 offset:1024
	ds_read_b128 v[176:179], v155 offset:2048
	ds_read_b128 v[180:183], v155 offset:3072
	ds_read_b128 v[184:187], v153 offset:32768
	ds_read_b128 v[188:191], v153 offset:33792
	ds_read_b128 v[192:195], v153 offset:34816
	ds_read_b128 v[196:199], v153 offset:35840
	ds_read_b128 v[200:203], v153 offset:36864
	ds_read_b128 v[208:211], v153 offset:37888
	ds_read_b128 v[212:215], v153 offset:38912
	ds_read_b128 v[216:219], v153 offset:39936
	s_waitcnt vmcnt(8)
	s_waitcnt lgkmcnt(0)
	s_barrier
	s_waitcnt lgkmcnt(0)
	v_mfma_f32_16x16x32_bf16 v[124:127], v[144:147], v[184:187], v[124:127]
	v_mfma_f32_16x16x32_bf16 v[120:123], v[160:163], v[184:187], v[120:123]
	v_mfma_f32_16x16x32_bf16 v[108:111], v[144:147], v[192:195], v[108:111]
	v_mfma_f32_16x16x32_bf16 v[104:107], v[160:163], v[192:195], v[104:107]
	v_mfma_f32_16x16x32_bf16 v[92:95], v[144:147], v[200:203], v[92:95]
	v_mfma_f32_16x16x32_bf16 v[88:91], v[160:163], v[200:203], v[88:91]
	v_mfma_f32_16x16x32_bf16 v[76:79], v[144:147], v[212:215], v[76:79]
	v_mfma_f32_16x16x32_bf16 v[72:75], v[160:163], v[212:215], v[72:75]
	v_mfma_f32_16x16x32_bf16 v[124:127], v[156:159], v[188:191], v[124:127]
	v_mfma_f32_16x16x32_bf16 v[120:123], v[164:167], v[188:191], v[120:123]
	v_mfma_f32_16x16x32_bf16 v[108:111], v[156:159], v[196:199], v[108:111]
	v_mfma_f32_16x16x32_bf16 v[104:107], v[164:167], v[196:199], v[104:107]
	v_mfma_f32_16x16x32_bf16 v[92:95], v[156:159], v[208:211], v[92:95]
	v_mfma_f32_16x16x32_bf16 v[88:91], v[164:167], v[208:211], v[88:91]
	v_mfma_f32_16x16x32_bf16 v[76:79], v[156:159], v[216:219], v[76:79]
	v_mfma_f32_16x16x32_bf16 v[72:75], v[164:167], v[216:219], v[72:75]
	v_mfma_f32_16x16x32_bf16 v[116:119], v[168:171], v[184:187], v[116:119]
	v_mfma_f32_16x16x32_bf16 v[112:115], v[176:179], v[184:187], v[112:115]
	v_mfma_f32_16x16x32_bf16 v[100:103], v[168:171], v[192:195], v[100:103]
	v_mfma_f32_16x16x32_bf16 v[96:99], v[176:179], v[192:195], v[96:99]
	v_mfma_f32_16x16x32_bf16 v[84:87], v[168:171], v[200:203], v[84:87]
	v_mfma_f32_16x16x32_bf16 v[80:83], v[176:179], v[200:203], v[80:83]
	v_mfma_f32_16x16x32_bf16 v[68:71], v[168:171], v[212:215], v[68:71]
	v_mfma_f32_16x16x32_bf16 v[64:67], v[176:179], v[212:215], v[64:67]
	v_mfma_f32_16x16x32_bf16 v[116:119], v[172:175], v[188:191], v[116:119]
	v_mfma_f32_16x16x32_bf16 v[112:115], v[180:183], v[188:191], v[112:115]
	v_mfma_f32_16x16x32_bf16 v[100:103], v[172:175], v[196:199], v[100:103]
	v_mfma_f32_16x16x32_bf16 v[96:99], v[180:183], v[196:199], v[96:99]
	v_mfma_f32_16x16x32_bf16 v[84:87], v[172:175], v[208:211], v[84:87]
	v_mfma_f32_16x16x32_bf16 v[80:83], v[180:183], v[208:211], v[80:83]
	v_mfma_f32_16x16x32_bf16 v[68:71], v[172:175], v[216:219], v[68:71]
	v_mfma_f32_16x16x32_bf16 v[64:67], v[180:183], v[216:219], v[64:67]
	s_barrier
	s_add_i32 s28, s54, s38
	s_mov_b32 m0, s28
	s_nop 0
	global_load_lds_dwordx4 v205, s[26:27]
	s_add_i32 m0, s28, 0x2000
	s_add_u32 s26, s26, 0x40080
	s_addc_u32 s27, s27, 0
	s_add_i32 s28, s55, s38
	global_load_lds_dwordx4 v221, s[98:99]
	s_mov_b32 m0, s28
	s_nop 0
	global_load_lds_dwordx4 v130, s[26:27]
	s_add_i32 m0, s28, 0x2000
	s_nop 0
	global_load_lds_dwordx4 v134, s[26:27]
	s_mov_b32 m0, s43
	s_nop 0
	global_load_lds_dwordx4 v204, s[100:101]
	s_cmp_lg_u32 s53, 12
	s_cbranch_scc1 .Lbal_last_16
	s_mov_b32 m0, s44
	s_nop 0
	global_load_lds_dwordx4 v220, s[100:101]
.Lbal_last_16:
	ds_read_b128 v[184:187], v153 offset:49152
	ds_read_b128 v[188:191], v153 offset:50176
	ds_read_b128 v[192:195], v153 offset:51200
	ds_read_b128 v[196:199], v153 offset:52224
	ds_read_b128 v[200:203], v153 offset:53248
	ds_read_b128 v[208:211], v153 offset:54272
	ds_read_b128 v[212:215], v153 offset:55296
	ds_read_b128 v[216:219], v153 offset:56320
	s_waitcnt vmcnt(7)
	s_waitcnt lgkmcnt(0)
	s_barrier
	s_waitcnt lgkmcnt(0)
	v_mfma_f32_16x16x32_bf16 v[60:63], v[144:147], v[184:187], v[60:63]
	v_mfma_f32_16x16x32_bf16 v[56:59], v[160:163], v[184:187], v[56:59]
	v_mfma_f32_16x16x32_bf16 v[44:47], v[144:147], v[192:195], v[44:47]
	v_mfma_f32_16x16x32_bf16 v[40:43], v[160:163], v[192:195], v[40:43]
	v_mfma_f32_16x16x32_bf16 v[28:31], v[144:147], v[200:203], v[28:31]
	v_mfma_f32_16x16x32_bf16 v[24:27], v[160:163], v[200:203], v[24:27]
	v_mfma_f32_16x16x32_bf16 v[12:15], v[144:147], v[212:215], v[12:15]
	v_mfma_f32_16x16x32_bf16 v[8:11], v[160:163], v[212:215], v[8:11]
	v_mfma_f32_16x16x32_bf16 v[60:63], v[156:159], v[188:191], v[60:63]
	v_mfma_f32_16x16x32_bf16 v[56:59], v[164:167], v[188:191], v[56:59]
	v_mfma_f32_16x16x32_bf16 v[44:47], v[156:159], v[196:199], v[44:47]
	v_mfma_f32_16x16x32_bf16 v[40:43], v[164:167], v[196:199], v[40:43]
	v_mfma_f32_16x16x32_bf16 v[28:31], v[156:159], v[208:211], v[28:31]
	v_mfma_f32_16x16x32_bf16 v[24:27], v[164:167], v[208:211], v[24:27]
	v_mfma_f32_16x16x32_bf16 v[12:15], v[156:159], v[216:219], v[12:15]
	v_mfma_f32_16x16x32_bf16 v[8:11], v[164:167], v[216:219], v[8:11]
	v_mfma_f32_16x16x32_bf16 v[52:55], v[168:171], v[184:187], v[52:55]
	v_mfma_f32_16x16x32_bf16 v[48:51], v[176:179], v[184:187], v[48:51]
	v_mfma_f32_16x16x32_bf16 v[36:39], v[168:171], v[192:195], v[36:39]
	v_mfma_f32_16x16x32_bf16 v[32:35], v[176:179], v[192:195], v[32:35]
	v_mfma_f32_16x16x32_bf16 v[20:23], v[168:171], v[200:203], v[20:23]
	v_mfma_f32_16x16x32_bf16 v[16:19], v[176:179], v[200:203], v[16:19]
	v_mfma_f32_16x16x32_bf16 v[4:7], v[168:171], v[212:215], v[4:7]
	v_mfma_f32_16x16x32_bf16 v[0:3], v[176:179], v[212:215], v[0:3]
	v_mfma_f32_16x16x32_bf16 v[52:55], v[172:175], v[188:191], v[52:55]
	v_mfma_f32_16x16x32_bf16 v[48:51], v[180:183], v[188:191], v[48:51]
	v_mfma_f32_16x16x32_bf16 v[36:39], v[172:175], v[196:199], v[36:39]
	v_mfma_f32_16x16x32_bf16 v[32:35], v[180:183], v[196:199], v[32:35]
	v_mfma_f32_16x16x32_bf16 v[20:23], v[172:175], v[208:211], v[20:23]
	v_mfma_f32_16x16x32_bf16 v[16:19], v[180:183], v[208:211], v[16:19]
	v_mfma_f32_16x16x32_bf16 v[4:7], v[172:175], v[216:219], v[4:7]
	v_mfma_f32_16x16x32_bf16 v[0:3], v[180:183], v[216:219], v[0:3]
	s_barrier
	s_add_i32 s53, s53, 2
	s_add_u32 s51, s51, 0x100
	s_addc_u32 s52, s52, 0
	s_add_u32 s6, s6, 0x100
	s_addc_u32 s7, s7, 0
	s_cmp_gt_u32 s53, 13
	s_cbranch_scc0 .LBB0_988
	s_setprio 0
	s_and_b64 vcc, exec, s[14:15]
	s_cbranch_vccz .LBB0_991
	s_barrier

.Lbal_first_15:
	s_add_u32 s26, s24, 0xfffe0080
	s_addc_u32 s27, s25, -1
	s_cmp_eq_u32 s50, 4
	s_cselect_b32 s29, s17, s27
	s_cselect_b32 s28, s46, s26
	s_cselect_b32 s27, s15, s49
	s_cselect_b32 s26, s47, s48
	s_add_i32 m0, s23, 0xc000
	s_nop 0
	global_load_lds_dwordx4 v138, s[24:25]
	s_add_i32 m0, s23, 0xe000
	s_nop 0
	global_load_lds_dwordx4 v136, s[24:25]
	ds_read_b128 v[144:147], v151
	ds_read_b128 v[154:157], v151 offset:1024
	ds_read_b128 v[158:161], v151 offset:2048
	ds_read_b128 v[162:165], v151 offset:3072
	ds_read_b128 v[166:169], v152
	ds_read_b128 v[170:173], v152 offset:1024
	ds_read_b128 v[174:177], v152 offset:2048
	ds_read_b128 v[178:181], v152 offset:3072
	ds_read_b128 v[182:185], v153
	ds_read_b128 v[186:189], v153 offset:1024
	ds_read_b128 v[190:193], v153 offset:2048
	ds_read_b128 v[194:197], v153 offset:3072
	ds_read_b128 v[198:201], v153 offset:4096
	ds_read_b128 v[202:205], v153 offset:5120
	ds_read_b128 v[208:211], v153 offset:6144
	ds_read_b128 v[212:215], v153 offset:7168
	s_waitcnt vmcnt(8)
	s_waitcnt lgkmcnt(0)
	s_barrier
	s_waitcnt lgkmcnt(0)
	v_mfma_f32_16x16x32_bf16 v[124:127], v[144:147], v[182:185], v[124:127]
	v_mfma_f32_16x16x32_bf16 v[120:123], v[158:161], v[182:185], v[120:123]
	v_mfma_f32_16x16x32_bf16 v[108:111], v[144:147], v[190:193], v[108:111]
	v_mfma_f32_16x16x32_bf16 v[104:107], v[158:161], v[190:193], v[104:107]
	v_mfma_f32_16x16x32_bf16 v[92:95], v[144:147], v[198:201], v[92:95]
	v_mfma_f32_16x16x32_bf16 v[88:91], v[158:161], v[198:201], v[88:91]
	v_mfma_f32_16x16x32_bf16 v[76:79], v[144:147], v[208:211], v[76:79]
	v_mfma_f32_16x16x32_bf16 v[72:75], v[158:161], v[208:211], v[72:75]
	v_mfma_f32_16x16x32_bf16 v[124:127], v[154:157], v[186:189], v[124:127]
	v_mfma_f32_16x16x32_bf16 v[120:123], v[162:165], v[186:189], v[120:123]
	v_mfma_f32_16x16x32_bf16 v[108:111], v[154:157], v[194:197], v[108:111]
	v_mfma_f32_16x16x32_bf16 v[104:107], v[162:165], v[194:197], v[104:107]
	v_mfma_f32_16x16x32_bf16 v[92:95], v[154:157], v[202:205], v[92:95]
	v_mfma_f32_16x16x32_bf16 v[88:91], v[162:165], v[202:205], v[88:91]
	v_mfma_f32_16x16x32_bf16 v[76:79], v[154:157], v[212:215], v[76:79]
	v_mfma_f32_16x16x32_bf16 v[72:75], v[162:165], v[212:215], v[72:75]
	v_mfma_f32_16x16x32_bf16 v[116:119], v[166:169], v[182:185], v[116:119]
	v_mfma_f32_16x16x32_bf16 v[112:115], v[174:177], v[182:185], v[112:115]
	v_mfma_f32_16x16x32_bf16 v[100:103], v[166:169], v[190:193], v[100:103]
	v_mfma_f32_16x16x32_bf16 v[96:99], v[174:177], v[190:193], v[96:99]
	v_mfma_f32_16x16x32_bf16 v[84:87], v[166:169], v[198:201], v[84:87]
	v_mfma_f32_16x16x32_bf16 v[80:83], v[174:177], v[198:201], v[80:83]
	v_mfma_f32_16x16x32_bf16 v[68:71], v[166:169], v[208:211], v[68:71]
	v_mfma_f32_16x16x32_bf16 v[64:67], v[174:177], v[208:211], v[64:67]
	v_mfma_f32_16x16x32_bf16 v[116:119], v[170:173], v[186:189], v[116:119]
	v_mfma_f32_16x16x32_bf16 v[112:115], v[178:181], v[186:189], v[112:115]
	v_mfma_f32_16x16x32_bf16 v[100:103], v[170:173], v[194:197], v[100:103]
	v_mfma_f32_16x16x32_bf16 v[96:99], v[178:181], v[194:197], v[96:99]
	v_mfma_f32_16x16x32_bf16 v[84:87], v[170:173], v[202:205], v[84:87]
	v_mfma_f32_16x16x32_bf16 v[80:83], v[178:181], v[202:205], v[80:83]
	v_mfma_f32_16x16x32_bf16 v[68:71], v[170:173], v[212:215], v[68:71]
	v_mfma_f32_16x16x32_bf16 v[64:67], v[178:181], v[212:215], v[64:67]
	s_barrier
	s_add_i32 s51, s43, s36
	s_mov_b32 m0, s51
	s_nop 0
	global_load_lds_dwordx4 v130, s[26:27]
	s_add_i32 m0, s51, 0x2000
	s_add_u32 s52, s26, 0x20000
	s_mov_b64 s[98:99], s[26:27]
	s_addc_u32 s53, s27, 0
	s_add_i32 s51, s44, s36
	global_load_lds_dwordx4 v134, s[26:27]
	s_mov_b32 m0, s51
	s_mov_b64 s[100:101], s[28:29]
	global_load_lds_dwordx4 v130, s[52:53]
	s_add_i32 m0, s51, 0x2000
	s_nop 0
	global_load_lds_dwordx4 v134, s[52:53]
	s_mov_b32 m0, s23
	s_nop 0
	global_load_lds_dwordx4 v128, s[28:29]
	ds_read_b128 v[182:185], v153 offset:16384
	ds_read_b128 v[186:189], v153 offset:17408
	ds_read_b128 v[190:193], v153 offset:18432
	ds_read_b128 v[194:197], v153 offset:19456
	ds_read_b128 v[198:201], v153 offset:20480
	ds_read_b128 v[202:205], v153 offset:21504
	ds_read_b128 v[208:211], v153 offset:22528
	ds_read_b128 v[212:215], v153 offset:23552
	s_waitcnt vmcnt(7)
	s_waitcnt lgkmcnt(0)
	s_barrier
	s_waitcnt lgkmcnt(0)
	v_mfma_f32_16x16x32_bf16 v[60:63], v[144:147], v[182:185], v[60:63]
	v_mfma_f32_16x16x32_bf16 v[56:59], v[158:161], v[182:185], v[56:59]
	v_mfma_f32_16x16x32_bf16 v[44:47], v[144:147], v[190:193], v[44:47]
	v_mfma_f32_16x16x32_bf16 v[40:43], v[158:161], v[190:193], v[40:43]
	v_mfma_f32_16x16x32_bf16 v[28:31], v[144:147], v[198:201], v[28:31]
	v_mfma_f32_16x16x32_bf16 v[24:27], v[158:161], v[198:201], v[24:27]
	v_mfma_f32_16x16x32_bf16 v[12:15], v[144:147], v[208:211], v[12:15]
	v_mfma_f32_16x16x32_bf16 v[8:11], v[158:161], v[208:211], v[8:11]
	v_mfma_f32_16x16x32_bf16 v[60:63], v[154:157], v[186:189], v[60:63]
	v_mfma_f32_16x16x32_bf16 v[56:59], v[162:165], v[186:189], v[56:59]
	v_mfma_f32_16x16x32_bf16 v[44:47], v[154:157], v[194:197], v[44:47]
	v_mfma_f32_16x16x32_bf16 v[40:43], v[162:165], v[194:197], v[40:43]
	v_mfma_f32_16x16x32_bf16 v[28:31], v[154:157], v[202:205], v[28:31]
	v_mfma_f32_16x16x32_bf16 v[24:27], v[162:165], v[202:205], v[24:27]
	v_mfma_f32_16x16x32_bf16 v[12:15], v[154:157], v[212:215], v[12:15]
	v_mfma_f32_16x16x32_bf16 v[8:11], v[162:165], v[212:215], v[8:11]
	v_mfma_f32_16x16x32_bf16 v[52:55], v[166:169], v[182:185], v[52:55]
	v_mfma_f32_16x16x32_bf16 v[48:51], v[174:177], v[182:185], v[48:51]
	v_mfma_f32_16x16x32_bf16 v[36:39], v[166:169], v[190:193], v[36:39]
	v_mfma_f32_16x16x32_bf16 v[32:35], v[174:177], v[190:193], v[32:35]
	v_mfma_f32_16x16x32_bf16 v[20:23], v[166:169], v[198:201], v[20:23]
	v_mfma_f32_16x16x32_bf16 v[16:19], v[174:177], v[198:201], v[16:19]
	v_mfma_f32_16x16x32_bf16 v[4:7], v[166:169], v[208:211], v[4:7]
	v_mfma_f32_16x16x32_bf16 v[0:3], v[174:177], v[208:211], v[0:3]
	v_mfma_f32_16x16x32_bf16 v[52:55], v[170:173], v[186:189], v[52:55]
	v_mfma_f32_16x16x32_bf16 v[48:51], v[178:181], v[186:189], v[48:51]
	v_mfma_f32_16x16x32_bf16 v[36:39], v[170:173], v[194:197], v[36:39]
	v_mfma_f32_16x16x32_bf16 v[32:35], v[178:181], v[194:197], v[32:35]
	v_mfma_f32_16x16x32_bf16 v[20:23], v[170:173], v[202:205], v[20:23]
	v_mfma_f32_16x16x32_bf16 v[16:19], v[178:181], v[202:205], v[16:19]
	v_mfma_f32_16x16x32_bf16 v[4:7], v[170:173], v[212:215], v[4:7]
	v_mfma_f32_16x16x32_bf16 v[0:3], v[178:181], v[212:215], v[0:3]
	s_barrier
	s_mov_b32 m0, s37
	s_nop 0
	global_load_lds_dwordx4 v132, s[28:29]
	s_add_i32 s51, 0, 0x18000
	s_add_i32 s52, 0, 0x1c000
	s_add_u32 s28, s28, 0x20000
	s_addc_u32 s29, s29, 0
	s_mov_b32 m0, s38
	s_nop 0
	global_load_lds_dwordx4 v128, s[28:29]
	s_mov_b32 m0, s39
	s_nop 0
	global_load_lds_dwordx4 v132, s[28:29]
	v_add_u32_e32 v162, s51, v149
	v_add_u32_e32 v178, s52, v149
	ds_read_b128 v[144:147], v162
	ds_read_b128 v[154:157], v162 offset:1024
	ds_read_b128 v[158:161], v162 offset:2048
	ds_read_b128 v[162:165], v162 offset:3072
	ds_read_b128 v[166:169], v178
	ds_read_b128 v[170:173], v178 offset:1024
	ds_read_b128 v[174:177], v178 offset:2048
	ds_read_b128 v[178:181], v178 offset:3072
	ds_read_b128 v[182:185], v153 offset:32768
	ds_read_b128 v[186:189], v153 offset:33792
	ds_read_b128 v[190:193], v153 offset:34816
	ds_read_b128 v[194:197], v153 offset:35840
	ds_read_b128 v[198:201], v153 offset:36864
	ds_read_b128 v[202:205], v153 offset:37888
	ds_read_b128 v[208:211], v153 offset:38912
	ds_read_b128 v[212:215], v153 offset:39936
	s_waitcnt vmcnt(8)
	s_waitcnt lgkmcnt(0)
	s_barrier
	s_waitcnt lgkmcnt(0)
	v_mfma_f32_16x16x32_bf16 v[124:127], v[144:147], v[182:185], v[124:127]
	v_mfma_f32_16x16x32_bf16 v[120:123], v[158:161], v[182:185], v[120:123]
	v_mfma_f32_16x16x32_bf16 v[108:111], v[144:147], v[190:193], v[108:111]
	v_mfma_f32_16x16x32_bf16 v[104:107], v[158:161], v[190:193], v[104:107]
	v_mfma_f32_16x16x32_bf16 v[92:95], v[144:147], v[198:201], v[92:95]
	v_mfma_f32_16x16x32_bf16 v[88:91], v[158:161], v[198:201], v[88:91]
	v_mfma_f32_16x16x32_bf16 v[76:79], v[144:147], v[208:211], v[76:79]
	v_mfma_f32_16x16x32_bf16 v[72:75], v[158:161], v[208:211], v[72:75]
	v_mfma_f32_16x16x32_bf16 v[124:127], v[154:157], v[186:189], v[124:127]
	v_mfma_f32_16x16x32_bf16 v[120:123], v[162:165], v[186:189], v[120:123]
	v_mfma_f32_16x16x32_bf16 v[108:111], v[154:157], v[194:197], v[108:111]
	v_mfma_f32_16x16x32_bf16 v[104:107], v[162:165], v[194:197], v[104:107]
	v_mfma_f32_16x16x32_bf16 v[92:95], v[154:157], v[202:205], v[92:95]
	v_mfma_f32_16x16x32_bf16 v[88:91], v[162:165], v[202:205], v[88:91]
	v_mfma_f32_16x16x32_bf16 v[76:79], v[154:157], v[212:215], v[76:79]
	v_mfma_f32_16x16x32_bf16 v[72:75], v[162:165], v[212:215], v[72:75]
	v_mfma_f32_16x16x32_bf16 v[116:119], v[166:169], v[182:185], v[116:119]
	v_mfma_f32_16x16x32_bf16 v[112:115], v[174:177], v[182:185], v[112:115]
	v_mfma_f32_16x16x32_bf16 v[100:103], v[166:169], v[190:193], v[100:103]
	v_mfma_f32_16x16x32_bf16 v[96:99], v[174:177], v[190:193], v[96:99]
	v_mfma_f32_16x16x32_bf16 v[84:87], v[166:169], v[198:201], v[84:87]
	v_mfma_f32_16x16x32_bf16 v[80:83], v[174:177], v[198:201], v[80:83]
	v_mfma_f32_16x16x32_bf16 v[68:71], v[166:169], v[208:211], v[68:71]
	v_mfma_f32_16x16x32_bf16 v[64:67], v[174:177], v[208:211], v[64:67]
	v_mfma_f32_16x16x32_bf16 v[116:119], v[170:173], v[186:189], v[116:119]
	v_mfma_f32_16x16x32_bf16 v[112:115], v[178:181], v[186:189], v[112:115]
	v_mfma_f32_16x16x32_bf16 v[100:103], v[170:173], v[194:197], v[100:103]
	v_mfma_f32_16x16x32_bf16 v[96:99], v[178:181], v[194:197], v[96:99]
	v_mfma_f32_16x16x32_bf16 v[84:87], v[170:173], v[202:205], v[84:87]
	v_mfma_f32_16x16x32_bf16 v[80:83], v[178:181], v[202:205], v[80:83]
	v_mfma_f32_16x16x32_bf16 v[68:71], v[170:173], v[212:215], v[68:71]
	v_mfma_f32_16x16x32_bf16 v[64:67], v[178:181], v[212:215], v[64:67]
	s_barrier
	s_add_i32 s28, s51, s36
	s_mov_b32 m0, s28
	s_nop 0
	global_load_lds_dwordx4 v217, s[26:27]
	s_add_i32 m0, s28, 0x2000
	s_add_u32 s26, s26, 0x20080
	s_addc_u32 s27, s27, 0
	s_add_i32 s28, s52, s36
	global_load_lds_dwordx4 v219, s[98:99]
	s_mov_b32 m0, s28
	s_nop 0
	global_load_lds_dwordx4 v130, s[26:27]
	s_add_i32 m0, s28, 0x2000
	s_nop 0
	global_load_lds_dwordx4 v134, s[26:27]
	s_mov_b32 m0, s41
	s_nop 0
	global_load_lds_dwordx4 v216, s[100:101]
	s_cmp_lg_u32 s50, 4
	s_cbranch_scc1 .Lbal_last_15
	s_mov_b32 m0, s42
	s_nop 0
	global_load_lds_dwordx4 v218, s[100:101]
.Lbal_last_15:
	ds_read_b128 v[182:185], v153 offset:49152
	ds_read_b128 v[186:189], v153 offset:50176
	ds_read_b128 v[190:193], v153 offset:51200
	ds_read_b128 v[194:197], v153 offset:52224
	ds_read_b128 v[198:201], v153 offset:53248
	ds_read_b128 v[202:205], v153 offset:54272
	ds_read_b128 v[208:211], v153 offset:55296
	ds_read_b128 v[212:215], v153 offset:56320
	s_waitcnt vmcnt(7)
	s_waitcnt lgkmcnt(0)
	s_barrier
	s_waitcnt lgkmcnt(0)
	v_mfma_f32_16x16x32_bf16 v[60:63], v[144:147], v[182:185], v[60:63]
	v_mfma_f32_16x16x32_bf16 v[56:59], v[158:161], v[182:185], v[56:59]
	v_mfma_f32_16x16x32_bf16 v[44:47], v[144:147], v[190:193], v[44:47]
	v_mfma_f32_16x16x32_bf16 v[40:43], v[158:161], v[190:193], v[40:43]
	v_mfma_f32_16x16x32_bf16 v[28:31], v[144:147], v[198:201], v[28:31]
	v_mfma_f32_16x16x32_bf16 v[24:27], v[158:161], v[198:201], v[24:27]
	v_mfma_f32_16x16x32_bf16 v[12:15], v[144:147], v[208:211], v[12:15]
	v_mfma_f32_16x16x32_bf16 v[8:11], v[158:161], v[208:211], v[8:11]
	v_mfma_f32_16x16x32_bf16 v[60:63], v[154:157], v[186:189], v[60:63]
	v_mfma_f32_16x16x32_bf16 v[56:59], v[162:165], v[186:189], v[56:59]
	v_mfma_f32_16x16x32_bf16 v[44:47], v[154:157], v[194:197], v[44:47]
	v_mfma_f32_16x16x32_bf16 v[40:43], v[162:165], v[194:197], v[40:43]
	v_mfma_f32_16x16x32_bf16 v[28:31], v[154:157], v[202:205], v[28:31]
	v_mfma_f32_16x16x32_bf16 v[24:27], v[162:165], v[202:205], v[24:27]
	v_mfma_f32_16x16x32_bf16 v[12:15], v[154:157], v[212:215], v[12:15]
	v_mfma_f32_16x16x32_bf16 v[8:11], v[162:165], v[212:215], v[8:11]
	v_mfma_f32_16x16x32_bf16 v[52:55], v[166:169], v[182:185], v[52:55]
	v_mfma_f32_16x16x32_bf16 v[48:51], v[174:177], v[182:185], v[48:51]
	v_mfma_f32_16x16x32_bf16 v[36:39], v[166:169], v[190:193], v[36:39]
	v_mfma_f32_16x16x32_bf16 v[32:35], v[174:177], v[190:193], v[32:35]
	v_mfma_f32_16x16x32_bf16 v[20:23], v[166:169], v[198:201], v[20:23]
	v_mfma_f32_16x16x32_bf16 v[16:19], v[174:177], v[198:201], v[16:19]
	v_mfma_f32_16x16x32_bf16 v[4:7], v[166:169], v[208:211], v[4:7]
	v_mfma_f32_16x16x32_bf16 v[0:3], v[174:177], v[208:211], v[0:3]
	v_mfma_f32_16x16x32_bf16 v[52:55], v[170:173], v[186:189], v[52:55]
	v_mfma_f32_16x16x32_bf16 v[48:51], v[178:181], v[186:189], v[48:51]
	v_mfma_f32_16x16x32_bf16 v[36:39], v[170:173], v[194:197], v[36:39]
	v_mfma_f32_16x16x32_bf16 v[32:35], v[178:181], v[194:197], v[32:35]
	v_mfma_f32_16x16x32_bf16 v[20:23], v[170:173], v[202:205], v[20:23]
	v_mfma_f32_16x16x32_bf16 v[16:19], v[178:181], v[202:205], v[16:19]
	v_mfma_f32_16x16x32_bf16 v[4:7], v[170:173], v[212:215], v[4:7]
	v_mfma_f32_16x16x32_bf16 v[0:3], v[178:181], v[212:215], v[0:3]
	s_barrier
	s_add_i32 s50, s50, 2
	s_add_u32 s48, s48, 0x100
	s_addc_u32 s49, s49, 0
	s_add_u32 s24, s24, 0x100
	s_addc_u32 s25, s25, 0
	s_cmp_gt_u32 s50, 5
	s_cbranch_scc0 .LBB0_1193
	s_setprio 0
	s_and_b64 vcc, exec, s[12:13]
	s_cbranch_vccz .LBB0_1196
	s_barrier

.Lbal_first_13:
	s_add_u32 s26, s24, 0xfffc0080
	s_addc_u32 s27, s25, -1
	s_cmp_eq_u32 s53, 12
	s_cselect_b32 s29, s19, s27
	s_cselect_b32 s28, s49, s26
	s_cselect_b32 s27, s17, s52
	s_cselect_b32 s26, s50, s51
	s_add_i32 m0, s39, 0xc000
	s_nop 0
	global_load_lds_dwordx4 v138, s[24:25]
	s_add_i32 m0, s39, 0xe000
	s_nop 0
	global_load_lds_dwordx4 v136, s[24:25]
	ds_read_b128 v[144:147], v151
	ds_read_b128 v[156:159], v151 offset:1024
	ds_read_b128 v[160:163], v151 offset:2048
	ds_read_b128 v[164:167], v151 offset:3072
	ds_read_b128 v[168:171], v152
	ds_read_b128 v[172:175], v152 offset:1024
	ds_read_b128 v[176:179], v152 offset:2048
	ds_read_b128 v[180:183], v152 offset:3072
	ds_read_b128 v[184:187], v153
	ds_read_b128 v[188:191], v153 offset:1024
	ds_read_b128 v[192:195], v153 offset:2048
	ds_read_b128 v[196:199], v153 offset:3072
	ds_read_b128 v[200:203], v153 offset:4096
	ds_read_b128 v[208:211], v153 offset:5120
	ds_read_b128 v[212:215], v153 offset:6144
	ds_read_b128 v[216:219], v153 offset:7168
	s_waitcnt vmcnt(8)
	s_waitcnt lgkmcnt(0)
	s_barrier
	s_waitcnt lgkmcnt(0)
	v_mfma_f32_16x16x32_bf16 v[124:127], v[144:147], v[184:187], v[124:127]
	v_mfma_f32_16x16x32_bf16 v[120:123], v[160:163], v[184:187], v[120:123]
	v_mfma_f32_16x16x32_bf16 v[108:111], v[144:147], v[192:195], v[108:111]
	v_mfma_f32_16x16x32_bf16 v[104:107], v[160:163], v[192:195], v[104:107]
	v_mfma_f32_16x16x32_bf16 v[92:95], v[144:147], v[200:203], v[92:95]
	v_mfma_f32_16x16x32_bf16 v[88:91], v[160:163], v[200:203], v[88:91]
	v_mfma_f32_16x16x32_bf16 v[76:79], v[144:147], v[212:215], v[76:79]
	v_mfma_f32_16x16x32_bf16 v[72:75], v[160:163], v[212:215], v[72:75]
	v_mfma_f32_16x16x32_bf16 v[124:127], v[156:159], v[188:191], v[124:127]
	v_mfma_f32_16x16x32_bf16 v[120:123], v[164:167], v[188:191], v[120:123]
	v_mfma_f32_16x16x32_bf16 v[108:111], v[156:159], v[196:199], v[108:111]
	v_mfma_f32_16x16x32_bf16 v[104:107], v[164:167], v[196:199], v[104:107]
	v_mfma_f32_16x16x32_bf16 v[92:95], v[156:159], v[208:211], v[92:95]
	v_mfma_f32_16x16x32_bf16 v[88:91], v[164:167], v[208:211], v[88:91]
	v_mfma_f32_16x16x32_bf16 v[76:79], v[156:159], v[216:219], v[76:79]
	v_mfma_f32_16x16x32_bf16 v[72:75], v[164:167], v[216:219], v[72:75]
	v_mfma_f32_16x16x32_bf16 v[116:119], v[168:171], v[184:187], v[116:119]
	v_mfma_f32_16x16x32_bf16 v[112:115], v[176:179], v[184:187], v[112:115]
	v_mfma_f32_16x16x32_bf16 v[100:103], v[168:171], v[192:195], v[100:103]
	v_mfma_f32_16x16x32_bf16 v[96:99], v[176:179], v[192:195], v[96:99]
	v_mfma_f32_16x16x32_bf16 v[84:87], v[168:171], v[200:203], v[84:87]
	v_mfma_f32_16x16x32_bf16 v[80:83], v[176:179], v[200:203], v[80:83]
	v_mfma_f32_16x16x32_bf16 v[68:71], v[168:171], v[212:215], v[68:71]
	v_mfma_f32_16x16x32_bf16 v[64:67], v[176:179], v[212:215], v[64:67]
	v_mfma_f32_16x16x32_bf16 v[116:119], v[172:175], v[188:191], v[116:119]
	v_mfma_f32_16x16x32_bf16 v[112:115], v[180:183], v[188:191], v[112:115]
	v_mfma_f32_16x16x32_bf16 v[100:103], v[172:175], v[196:199], v[100:103]
	v_mfma_f32_16x16x32_bf16 v[96:99], v[180:183], v[196:199], v[96:99]
	v_mfma_f32_16x16x32_bf16 v[84:87], v[172:175], v[208:211], v[84:87]
	v_mfma_f32_16x16x32_bf16 v[80:83], v[180:183], v[208:211], v[80:83]
	v_mfma_f32_16x16x32_bf16 v[68:71], v[172:175], v[216:219], v[68:71]
	v_mfma_f32_16x16x32_bf16 v[64:67], v[180:183], v[216:219], v[64:67]
	s_barrier
	s_add_i32 s54, s46, s38
	s_mov_b32 m0, s54
	s_nop 0
	global_load_lds_dwordx4 v130, s[26:27]
	s_add_i32 m0, s54, 0x2000
	s_add_u32 s54, s26, 0x40000
	s_mov_b64 s[98:99], s[26:27]
	s_addc_u32 s55, s27, 0
	s_add_i32 s56, s47, s38
	global_load_lds_dwordx4 v134, s[26:27]
	s_mov_b32 m0, s56
	s_mov_b64 s[100:101], s[28:29]
	global_load_lds_dwordx4 v130, s[54:55]
	s_add_i32 m0, s56, 0x2000
	s_nop 0
	global_load_lds_dwordx4 v134, s[54:55]
	s_mov_b32 m0, s39
	s_nop 0
	global_load_lds_dwordx4 v128, s[28:29]
	ds_read_b128 v[184:187], v153 offset:16384
	ds_read_b128 v[188:191], v153 offset:17408
	ds_read_b128 v[192:195], v153 offset:18432
	ds_read_b128 v[196:199], v153 offset:19456
	ds_read_b128 v[200:203], v153 offset:20480
	ds_read_b128 v[208:211], v153 offset:21504
	ds_read_b128 v[212:215], v153 offset:22528
	ds_read_b128 v[216:219], v153 offset:23552
	s_waitcnt vmcnt(7)
	s_waitcnt lgkmcnt(0)
	s_barrier
	s_waitcnt lgkmcnt(0)
	v_mfma_f32_16x16x32_bf16 v[60:63], v[144:147], v[184:187], v[60:63]
	v_mfma_f32_16x16x32_bf16 v[56:59], v[160:163], v[184:187], v[56:59]
	v_mfma_f32_16x16x32_bf16 v[44:47], v[144:147], v[192:195], v[44:47]
	v_mfma_f32_16x16x32_bf16 v[40:43], v[160:163], v[192:195], v[40:43]
	v_mfma_f32_16x16x32_bf16 v[28:31], v[144:147], v[200:203], v[28:31]
	v_mfma_f32_16x16x32_bf16 v[24:27], v[160:163], v[200:203], v[24:27]
	v_mfma_f32_16x16x32_bf16 v[12:15], v[144:147], v[212:215], v[12:15]
	v_mfma_f32_16x16x32_bf16 v[8:11], v[160:163], v[212:215], v[8:11]
	v_mfma_f32_16x16x32_bf16 v[60:63], v[156:159], v[188:191], v[60:63]
	v_mfma_f32_16x16x32_bf16 v[56:59], v[164:167], v[188:191], v[56:59]
	v_mfma_f32_16x16x32_bf16 v[44:47], v[156:159], v[196:199], v[44:47]
	v_mfma_f32_16x16x32_bf16 v[40:43], v[164:167], v[196:199], v[40:43]
	v_mfma_f32_16x16x32_bf16 v[28:31], v[156:159], v[208:211], v[28:31]
	v_mfma_f32_16x16x32_bf16 v[24:27], v[164:167], v[208:211], v[24:27]
	v_mfma_f32_16x16x32_bf16 v[12:15], v[156:159], v[216:219], v[12:15]
	v_mfma_f32_16x16x32_bf16 v[8:11], v[164:167], v[216:219], v[8:11]
	v_mfma_f32_16x16x32_bf16 v[52:55], v[168:171], v[184:187], v[52:55]
	v_mfma_f32_16x16x32_bf16 v[48:51], v[176:179], v[184:187], v[48:51]
	v_mfma_f32_16x16x32_bf16 v[36:39], v[168:171], v[192:195], v[36:39]
	v_mfma_f32_16x16x32_bf16 v[32:35], v[176:179], v[192:195], v[32:35]
	v_mfma_f32_16x16x32_bf16 v[20:23], v[168:171], v[200:203], v[20:23]
	v_mfma_f32_16x16x32_bf16 v[16:19], v[176:179], v[200:203], v[16:19]
	v_mfma_f32_16x16x32_bf16 v[4:7], v[168:171], v[212:215], v[4:7]
	v_mfma_f32_16x16x32_bf16 v[0:3], v[176:179], v[212:215], v[0:3]
	v_mfma_f32_16x16x32_bf16 v[52:55], v[172:175], v[188:191], v[52:55]
	v_mfma_f32_16x16x32_bf16 v[48:51], v[180:183], v[188:191], v[48:51]
	v_mfma_f32_16x16x32_bf16 v[36:39], v[172:175], v[196:199], v[36:39]
	v_mfma_f32_16x16x32_bf16 v[32:35], v[180:183], v[196:199], v[32:35]
	v_mfma_f32_16x16x32_bf16 v[20:23], v[172:175], v[208:211], v[20:23]
	v_mfma_f32_16x16x32_bf16 v[16:19], v[180:183], v[208:211], v[16:19]
	v_mfma_f32_16x16x32_bf16 v[4:7], v[172:175], v[216:219], v[4:7]
	v_mfma_f32_16x16x32_bf16 v[0:3], v[180:183], v[216:219], v[0:3]
	s_barrier
	s_mov_b32 m0, s40
	s_nop 0
	global_load_lds_dwordx4 v132, s[28:29]
	s_add_i32 s54, 0, 0x18000
	s_add_i32 s55, 0, 0x1c000
	s_add_u32 s28, s28, 0x40000
	s_addc_u32 s29, s29, 0
	s_mov_b32 m0, s41
	s_nop 0
	global_load_lds_dwordx4 v128, s[28:29]
	s_mov_b32 m0, s42
	s_nop 0
	global_load_lds_dwordx4 v132, s[28:29]
	v_add_u32_e32 v155, s54, v149
	ds_read_b128 v[144:147], v155
	ds_read_b128 v[156:159], v155 offset:1024
	ds_read_b128 v[160:163], v155 offset:2048
	ds_read_b128 v[164:167], v155 offset:3072
	v_add_u32_e32 v155, s55, v149
	ds_read_b128 v[168:171], v155
	ds_read_b128 v[172:175], v155 offset:1024
	ds_read_b128 v[176:179], v155 offset:2048
	ds_read_b128 v[180:183], v155 offset:3072
	ds_read_b128 v[184:187], v153 offset:32768
	ds_read_b128 v[188:191], v153 offset:33792
	ds_read_b128 v[192:195], v153 offset:34816
	ds_read_b128 v[196:199], v153 offset:35840
	ds_read_b128 v[200:203], v153 offset:36864
	ds_read_b128 v[208:211], v153 offset:37888
	ds_read_b128 v[212:215], v153 offset:38912
	ds_read_b128 v[216:219], v153 offset:39936
	s_waitcnt vmcnt(8)
	s_waitcnt lgkmcnt(0)
	s_barrier
	s_waitcnt lgkmcnt(0)
	v_mfma_f32_16x16x32_bf16 v[124:127], v[144:147], v[184:187], v[124:127]
	v_mfma_f32_16x16x32_bf16 v[120:123], v[160:163], v[184:187], v[120:123]
	v_mfma_f32_16x16x32_bf16 v[108:111], v[144:147], v[192:195], v[108:111]
	v_mfma_f32_16x16x32_bf16 v[104:107], v[160:163], v[192:195], v[104:107]
	v_mfma_f32_16x16x32_bf16 v[92:95], v[144:147], v[200:203], v[92:95]
	v_mfma_f32_16x16x32_bf16 v[88:91], v[160:163], v[200:203], v[88:91]
	v_mfma_f32_16x16x32_bf16 v[76:79], v[144:147], v[212:215], v[76:79]
	v_mfma_f32_16x16x32_bf16 v[72:75], v[160:163], v[212:215], v[72:75]
	v_mfma_f32_16x16x32_bf16 v[124:127], v[156:159], v[188:191], v[124:127]
	v_mfma_f32_16x16x32_bf16 v[120:123], v[164:167], v[188:191], v[120:123]
	v_mfma_f32_16x16x32_bf16 v[108:111], v[156:159], v[196:199], v[108:111]
	v_mfma_f32_16x16x32_bf16 v[104:107], v[164:167], v[196:199], v[104:107]
	v_mfma_f32_16x16x32_bf16 v[92:95], v[156:159], v[208:211], v[92:95]
	v_mfma_f32_16x16x32_bf16 v[88:91], v[164:167], v[208:211], v[88:91]
	v_mfma_f32_16x16x32_bf16 v[76:79], v[156:159], v[216:219], v[76:79]
	v_mfma_f32_16x16x32_bf16 v[72:75], v[164:167], v[216:219], v[72:75]
	v_mfma_f32_16x16x32_bf16 v[116:119], v[168:171], v[184:187], v[116:119]
	v_mfma_f32_16x16x32_bf16 v[112:115], v[176:179], v[184:187], v[112:115]
	v_mfma_f32_16x16x32_bf16 v[100:103], v[168:171], v[192:195], v[100:103]
	v_mfma_f32_16x16x32_bf16 v[96:99], v[176:179], v[192:195], v[96:99]
	v_mfma_f32_16x16x32_bf16 v[84:87], v[168:171], v[200:203], v[84:87]
	v_mfma_f32_16x16x32_bf16 v[80:83], v[176:179], v[200:203], v[80:83]
	v_mfma_f32_16x16x32_bf16 v[68:71], v[168:171], v[212:215], v[68:71]
	v_mfma_f32_16x16x32_bf16 v[64:67], v[176:179], v[212:215], v[64:67]
	v_mfma_f32_16x16x32_bf16 v[116:119], v[172:175], v[188:191], v[116:119]
	v_mfma_f32_16x16x32_bf16 v[112:115], v[180:183], v[188:191], v[112:115]
	v_mfma_f32_16x16x32_bf16 v[100:103], v[172:175], v[196:199], v[100:103]
	v_mfma_f32_16x16x32_bf16 v[96:99], v[180:183], v[196:199], v[96:99]
	v_mfma_f32_16x16x32_bf16 v[84:87], v[172:175], v[208:211], v[84:87]
	v_mfma_f32_16x16x32_bf16 v[80:83], v[180:183], v[208:211], v[80:83]
	v_mfma_f32_16x16x32_bf16 v[68:71], v[172:175], v[216:219], v[68:71]
	v_mfma_f32_16x16x32_bf16 v[64:67], v[180:183], v[216:219], v[64:67]
	s_barrier
	s_add_i32 s28, s54, s38
	s_mov_b32 m0, s28
	s_nop 0
	global_load_lds_dwordx4 v205, s[26:27]
	s_add_i32 m0, s28, 0x2000
	s_add_u32 s26, s26, 0x40080
	s_addc_u32 s27, s27, 0
	s_add_i32 s28, s55, s38
	global_load_lds_dwordx4 v221, s[98:99]
	s_mov_b32 m0, s28
	s_nop 0
	global_load_lds_dwordx4 v130, s[26:27]
	s_add_i32 m0, s28, 0x2000
	s_nop 0
	global_load_lds_dwordx4 v134, s[26:27]
	s_mov_b32 m0, s44
	s_nop 0
	global_load_lds_dwordx4 v204, s[100:101]
	s_cmp_lg_u32 s53, 12
	s_cbranch_scc1 .Lbal_last_13
	s_mov_b32 m0, s45
	s_nop 0
	global_load_lds_dwordx4 v220, s[100:101]
.Lbal_last_13:
	ds_read_b128 v[184:187], v153 offset:49152
	ds_read_b128 v[188:191], v153 offset:50176
	ds_read_b128 v[192:195], v153 offset:51200
	ds_read_b128 v[196:199], v153 offset:52224
	ds_read_b128 v[200:203], v153 offset:53248
	ds_read_b128 v[208:211], v153 offset:54272
	ds_read_b128 v[212:215], v153 offset:55296
	ds_read_b128 v[216:219], v153 offset:56320
	s_waitcnt vmcnt(7)
	s_waitcnt lgkmcnt(0)
	s_barrier
	s_waitcnt lgkmcnt(0)
	v_mfma_f32_16x16x32_bf16 v[60:63], v[144:147], v[184:187], v[60:63]
	v_mfma_f32_16x16x32_bf16 v[56:59], v[160:163], v[184:187], v[56:59]
	v_mfma_f32_16x16x32_bf16 v[44:47], v[144:147], v[192:195], v[44:47]
	v_mfma_f32_16x16x32_bf16 v[40:43], v[160:163], v[192:195], v[40:43]
	v_mfma_f32_16x16x32_bf16 v[28:31], v[144:147], v[200:203], v[28:31]
	v_mfma_f32_16x16x32_bf16 v[24:27], v[160:163], v[200:203], v[24:27]
	v_mfma_f32_16x16x32_bf16 v[12:15], v[144:147], v[212:215], v[12:15]
	v_mfma_f32_16x16x32_bf16 v[8:11], v[160:163], v[212:215], v[8:11]
	v_mfma_f32_16x16x32_bf16 v[60:63], v[156:159], v[188:191], v[60:63]
	v_mfma_f32_16x16x32_bf16 v[56:59], v[164:167], v[188:191], v[56:59]
	v_mfma_f32_16x16x32_bf16 v[44:47], v[156:159], v[196:199], v[44:47]
	v_mfma_f32_16x16x32_bf16 v[40:43], v[164:167], v[196:199], v[40:43]
	v_mfma_f32_16x16x32_bf16 v[28:31], v[156:159], v[208:211], v[28:31]
	v_mfma_f32_16x16x32_bf16 v[24:27], v[164:167], v[208:211], v[24:27]
	v_mfma_f32_16x16x32_bf16 v[12:15], v[156:159], v[216:219], v[12:15]
	v_mfma_f32_16x16x32_bf16 v[8:11], v[164:167], v[216:219], v[8:11]
	v_mfma_f32_16x16x32_bf16 v[52:55], v[168:171], v[184:187], v[52:55]
	v_mfma_f32_16x16x32_bf16 v[48:51], v[176:179], v[184:187], v[48:51]
	v_mfma_f32_16x16x32_bf16 v[36:39], v[168:171], v[192:195], v[36:39]
	v_mfma_f32_16x16x32_bf16 v[32:35], v[176:179], v[192:195], v[32:35]
	v_mfma_f32_16x16x32_bf16 v[20:23], v[168:171], v[200:203], v[20:23]
	v_mfma_f32_16x16x32_bf16 v[16:19], v[176:179], v[200:203], v[16:19]
	v_mfma_f32_16x16x32_bf16 v[4:7], v[168:171], v[212:215], v[4:7]
	v_mfma_f32_16x16x32_bf16 v[0:3], v[176:179], v[212:215], v[0:3]
	v_mfma_f32_16x16x32_bf16 v[52:55], v[172:175], v[188:191], v[52:55]
	v_mfma_f32_16x16x32_bf16 v[48:51], v[180:183], v[188:191], v[48:51]
	v_mfma_f32_16x16x32_bf16 v[36:39], v[172:175], v[196:199], v[36:39]
	v_mfma_f32_16x16x32_bf16 v[32:35], v[180:183], v[196:199], v[32:35]
	v_mfma_f32_16x16x32_bf16 v[20:23], v[172:175], v[208:211], v[20:23]
	v_mfma_f32_16x16x32_bf16 v[16:19], v[180:183], v[208:211], v[16:19]
	v_mfma_f32_16x16x32_bf16 v[4:7], v[172:175], v[216:219], v[4:7]
	v_mfma_f32_16x16x32_bf16 v[0:3], v[180:183], v[216:219], v[0:3]
	s_barrier
	s_add_i32 s53, s53, 2
	s_add_u32 s51, s51, 0x100
	s_addc_u32 s52, s52, 0
	s_add_u32 s24, s24, 0x100
	s_addc_u32 s25, s25, 0
	s_cmp_gt_u32 s53, 13
	s_cbranch_scc0 .LBB0_1365
	s_setprio 0
	s_and_b64 vcc, exec, s[14:15]
	s_cbranch_vccz .LBB0_1368
	s_barrier

.Lbal_first_11:
	s_add_u32 s38, s36, 0xfffc0080
	s_addc_u32 s39, s37, -1
	s_cmp_eq_u32 s61, 12
	s_cselect_b32 s41, s3, s39
	s_cselect_b32 s40, s29, s38
	s_cselect_b32 s39, s27, s60
	s_cselect_b32 s38, s58, s59
	s_add_i32 m0, s46, 0xc000
	s_nop 0
	global_load_lds_dwordx4 v134, s[36:37]
	s_add_i32 m0, s46, 0xe000
	s_nop 0
	global_load_lds_dwordx4 v132, s[36:37]
	ds_read_b128 v[140:143], v151
	ds_read_b128 v[144:147], v151 offset:1024
	ds_read_b128 v[156:159], v151 offset:2048
	ds_read_b128 v[160:163], v151 offset:3072
	ds_read_b128 v[164:167], v152
	ds_read_b128 v[168:171], v152 offset:1024
	ds_read_b128 v[172:175], v152 offset:2048
	ds_read_b128 v[176:179], v152 offset:3072
	ds_read_b128 v[180:183], v153
	ds_read_b128 v[184:187], v153 offset:1024
	ds_read_b128 v[188:191], v153 offset:2048
	ds_read_b128 v[192:195], v153 offset:3072
	ds_read_b128 v[196:199], v153 offset:4096
	ds_read_b128 v[200:203], v153 offset:5120
	ds_read_b128 v[208:211], v153 offset:6144
	ds_read_b128 v[212:215], v153 offset:7168
	s_waitcnt vmcnt(8)
	s_waitcnt lgkmcnt(0)
	s_barrier
	s_waitcnt lgkmcnt(0)
	v_mfma_f32_16x16x32_bf16 v[124:127], v[140:143], v[180:183], v[124:127]
	v_mfma_f32_16x16x32_bf16 v[120:123], v[156:159], v[180:183], v[120:123]
	v_mfma_f32_16x16x32_bf16 v[108:111], v[140:143], v[188:191], v[108:111]
	v_mfma_f32_16x16x32_bf16 v[104:107], v[156:159], v[188:191], v[104:107]
	v_mfma_f32_16x16x32_bf16 v[92:95], v[140:143], v[196:199], v[92:95]
	v_mfma_f32_16x16x32_bf16 v[88:91], v[156:159], v[196:199], v[88:91]
	v_mfma_f32_16x16x32_bf16 v[76:79], v[140:143], v[208:211], v[76:79]
	v_mfma_f32_16x16x32_bf16 v[72:75], v[156:159], v[208:211], v[72:75]
	v_mfma_f32_16x16x32_bf16 v[124:127], v[144:147], v[184:187], v[124:127]
	v_mfma_f32_16x16x32_bf16 v[120:123], v[160:163], v[184:187], v[120:123]
	v_mfma_f32_16x16x32_bf16 v[108:111], v[144:147], v[192:195], v[108:111]
	v_mfma_f32_16x16x32_bf16 v[104:107], v[160:163], v[192:195], v[104:107]
	v_mfma_f32_16x16x32_bf16 v[92:95], v[144:147], v[200:203], v[92:95]
	v_mfma_f32_16x16x32_bf16 v[88:91], v[160:163], v[200:203], v[88:91]
	v_mfma_f32_16x16x32_bf16 v[76:79], v[144:147], v[212:215], v[76:79]
	v_mfma_f32_16x16x32_bf16 v[72:75], v[160:163], v[212:215], v[72:75]
	v_mfma_f32_16x16x32_bf16 v[116:119], v[164:167], v[180:183], v[116:119]
	v_mfma_f32_16x16x32_bf16 v[112:115], v[172:175], v[180:183], v[112:115]
	v_mfma_f32_16x16x32_bf16 v[100:103], v[164:167], v[188:191], v[100:103]
	v_mfma_f32_16x16x32_bf16 v[96:99], v[172:175], v[188:191], v[96:99]
	v_mfma_f32_16x16x32_bf16 v[84:87], v[164:167], v[196:199], v[84:87]
	v_mfma_f32_16x16x32_bf16 v[80:83], v[172:175], v[196:199], v[80:83]
	v_mfma_f32_16x16x32_bf16 v[68:71], v[164:167], v[208:211], v[68:71]
	v_mfma_f32_16x16x32_bf16 v[64:67], v[172:175], v[208:211], v[64:67]
	v_mfma_f32_16x16x32_bf16 v[116:119], v[168:171], v[184:187], v[116:119]
	v_mfma_f32_16x16x32_bf16 v[112:115], v[176:179], v[184:187], v[112:115]
	v_mfma_f32_16x16x32_bf16 v[100:103], v[168:171], v[192:195], v[100:103]
	v_mfma_f32_16x16x32_bf16 v[96:99], v[176:179], v[192:195], v[96:99]
	v_mfma_f32_16x16x32_bf16 v[84:87], v[168:171], v[200:203], v[84:87]
	v_mfma_f32_16x16x32_bf16 v[80:83], v[176:179], v[200:203], v[80:83]
	v_mfma_f32_16x16x32_bf16 v[68:71], v[168:171], v[212:215], v[68:71]
	v_mfma_f32_16x16x32_bf16 v[64:67], v[176:179], v[212:215], v[64:67]
	s_barrier
	s_add_i32 s62, s54, s45
	s_mov_b32 m0, s62
	s_nop 0
	global_load_lds_dwordx4 v128, s[38:39]
	s_add_i32 m0, s62, 0x2000
	s_add_u32 s62, s38, 0x40000
	s_mov_b64 s[98:99], s[38:39]
	s_addc_u32 s63, s39, 0
	s_add_i32 s64, s55, s45
	global_load_lds_dwordx4 v130, s[38:39]
	s_mov_b32 m0, s64
	s_mov_b64 s[100:101], s[40:41]
	global_load_lds_dwordx4 v128, s[62:63]
	s_add_i32 m0, s64, 0x2000
	s_nop 0
	global_load_lds_dwordx4 v130, s[62:63]
	s_mov_b32 m0, s46
	s_nop 0
	global_load_lds_dwordx4 v128, s[40:41]
	ds_read_b128 v[180:183], v153 offset:16384
	ds_read_b128 v[184:187], v153 offset:17408
	ds_read_b128 v[188:191], v153 offset:18432
	ds_read_b128 v[192:195], v153 offset:19456
	ds_read_b128 v[196:199], v153 offset:20480
	ds_read_b128 v[200:203], v153 offset:21504
	ds_read_b128 v[208:211], v153 offset:22528
	ds_read_b128 v[212:215], v153 offset:23552
	s_waitcnt vmcnt(7)
	s_waitcnt lgkmcnt(0)
	s_barrier
	s_waitcnt lgkmcnt(0)
	v_mfma_f32_16x16x32_bf16 v[60:63], v[140:143], v[180:183], v[60:63]
	v_mfma_f32_16x16x32_bf16 v[56:59], v[156:159], v[180:183], v[56:59]
	v_mfma_f32_16x16x32_bf16 v[44:47], v[140:143], v[188:191], v[44:47]
	v_mfma_f32_16x16x32_bf16 v[40:43], v[156:159], v[188:191], v[40:43]
	v_mfma_f32_16x16x32_bf16 v[28:31], v[140:143], v[196:199], v[28:31]
	v_mfma_f32_16x16x32_bf16 v[24:27], v[156:159], v[196:199], v[24:27]
	v_mfma_f32_16x16x32_bf16 v[12:15], v[140:143], v[208:211], v[12:15]
	v_mfma_f32_16x16x32_bf16 v[8:11], v[156:159], v[208:211], v[8:11]
	v_mfma_f32_16x16x32_bf16 v[60:63], v[144:147], v[184:187], v[60:63]
	v_mfma_f32_16x16x32_bf16 v[56:59], v[160:163], v[184:187], v[56:59]
	v_mfma_f32_16x16x32_bf16 v[44:47], v[144:147], v[192:195], v[44:47]
	v_mfma_f32_16x16x32_bf16 v[40:43], v[160:163], v[192:195], v[40:43]
	v_mfma_f32_16x16x32_bf16 v[28:31], v[144:147], v[200:203], v[28:31]
	v_mfma_f32_16x16x32_bf16 v[24:27], v[160:163], v[200:203], v[24:27]
	v_mfma_f32_16x16x32_bf16 v[12:15], v[144:147], v[212:215], v[12:15]
	v_mfma_f32_16x16x32_bf16 v[8:11], v[160:163], v[212:215], v[8:11]
	v_mfma_f32_16x16x32_bf16 v[52:55], v[164:167], v[180:183], v[52:55]
	v_mfma_f32_16x16x32_bf16 v[48:51], v[172:175], v[180:183], v[48:51]
	v_mfma_f32_16x16x32_bf16 v[36:39], v[164:167], v[188:191], v[36:39]
	v_mfma_f32_16x16x32_bf16 v[32:35], v[172:175], v[188:191], v[32:35]
	v_mfma_f32_16x16x32_bf16 v[20:23], v[164:167], v[196:199], v[20:23]
	v_mfma_f32_16x16x32_bf16 v[16:19], v[172:175], v[196:199], v[16:19]
	v_mfma_f32_16x16x32_bf16 v[4:7], v[164:167], v[208:211], v[4:7]
	v_mfma_f32_16x16x32_bf16 v[0:3], v[172:175], v[208:211], v[0:3]
	v_mfma_f32_16x16x32_bf16 v[52:55], v[168:171], v[184:187], v[52:55]
	v_mfma_f32_16x16x32_bf16 v[48:51], v[176:179], v[184:187], v[48:51]
	v_mfma_f32_16x16x32_bf16 v[36:39], v[168:171], v[192:195], v[36:39]
	v_mfma_f32_16x16x32_bf16 v[32:35], v[176:179], v[192:195], v[32:35]
	v_mfma_f32_16x16x32_bf16 v[20:23], v[168:171], v[200:203], v[20:23]
	v_mfma_f32_16x16x32_bf16 v[16:19], v[176:179], v[200:203], v[16:19]
	v_mfma_f32_16x16x32_bf16 v[4:7], v[168:171], v[212:215], v[4:7]
	v_mfma_f32_16x16x32_bf16 v[0:3], v[176:179], v[212:215], v[0:3]
	s_barrier
	s_mov_b32 m0, s47
	s_nop 0
	global_load_lds_dwordx4 v130, s[40:41]
	s_add_i32 s62, 0, 0x18000
	s_add_i32 s63, 0, 0x1c000
	s_add_u32 s40, s40, 0x40000
	s_addc_u32 s41, s41, 0
	s_mov_b32 m0, s48
	s_nop 0
	global_load_lds_dwordx4 v128, s[40:41]
	s_mov_b32 m0, s49
	s_nop 0
	global_load_lds_dwordx4 v130, s[40:41]
	v_add_u32_e32 v155, s62, v149
	ds_read_b128 v[140:143], v155
	ds_read_b128 v[144:147], v155 offset:1024
	ds_read_b128 v[156:159], v155 offset:2048
	ds_read_b128 v[160:163], v155 offset:3072
	v_add_u32_e32 v155, s63, v149
	ds_read_b128 v[164:167], v155
	ds_read_b128 v[168:171], v155 offset:1024
	ds_read_b128 v[172:175], v155 offset:2048
	ds_read_b128 v[176:179], v155 offset:3072
	ds_read_b128 v[180:183], v153 offset:32768
	ds_read_b128 v[184:187], v153 offset:33792
	ds_read_b128 v[188:191], v153 offset:34816
	ds_read_b128 v[192:195], v153 offset:35840
	ds_read_b128 v[196:199], v153 offset:36864
	ds_read_b128 v[200:203], v153 offset:37888
	ds_read_b128 v[208:211], v153 offset:38912
	ds_read_b128 v[212:215], v153 offset:39936
	s_waitcnt vmcnt(8)
	s_waitcnt lgkmcnt(0)
	s_barrier
	s_waitcnt lgkmcnt(0)
	v_mfma_f32_16x16x32_bf16 v[124:127], v[140:143], v[180:183], v[124:127]
	v_mfma_f32_16x16x32_bf16 v[120:123], v[156:159], v[180:183], v[120:123]
	v_mfma_f32_16x16x32_bf16 v[108:111], v[140:143], v[188:191], v[108:111]
	v_mfma_f32_16x16x32_bf16 v[104:107], v[156:159], v[188:191], v[104:107]
	v_mfma_f32_16x16x32_bf16 v[92:95], v[140:143], v[196:199], v[92:95]
	v_mfma_f32_16x16x32_bf16 v[88:91], v[156:159], v[196:199], v[88:91]
	v_mfma_f32_16x16x32_bf16 v[76:79], v[140:143], v[208:211], v[76:79]
	v_mfma_f32_16x16x32_bf16 v[72:75], v[156:159], v[208:211], v[72:75]
	v_mfma_f32_16x16x32_bf16 v[124:127], v[144:147], v[184:187], v[124:127]
	v_mfma_f32_16x16x32_bf16 v[120:123], v[160:163], v[184:187], v[120:123]
	v_mfma_f32_16x16x32_bf16 v[108:111], v[144:147], v[192:195], v[108:111]
	v_mfma_f32_16x16x32_bf16 v[104:107], v[160:163], v[192:195], v[104:107]
	v_mfma_f32_16x16x32_bf16 v[92:95], v[144:147], v[200:203], v[92:95]
	v_mfma_f32_16x16x32_bf16 v[88:91], v[160:163], v[200:203], v[88:91]
	v_mfma_f32_16x16x32_bf16 v[76:79], v[144:147], v[212:215], v[76:79]
	v_mfma_f32_16x16x32_bf16 v[72:75], v[160:163], v[212:215], v[72:75]
	v_mfma_f32_16x16x32_bf16 v[116:119], v[164:167], v[180:183], v[116:119]
	v_mfma_f32_16x16x32_bf16 v[112:115], v[172:175], v[180:183], v[112:115]
	v_mfma_f32_16x16x32_bf16 v[100:103], v[164:167], v[188:191], v[100:103]
	v_mfma_f32_16x16x32_bf16 v[96:99], v[172:175], v[188:191], v[96:99]
	v_mfma_f32_16x16x32_bf16 v[84:87], v[164:167], v[196:199], v[84:87]
	v_mfma_f32_16x16x32_bf16 v[80:83], v[172:175], v[196:199], v[80:83]
	v_mfma_f32_16x16x32_bf16 v[68:71], v[164:167], v[208:211], v[68:71]
	v_mfma_f32_16x16x32_bf16 v[64:67], v[172:175], v[208:211], v[64:67]
	v_mfma_f32_16x16x32_bf16 v[116:119], v[168:171], v[184:187], v[116:119]
	v_mfma_f32_16x16x32_bf16 v[112:115], v[176:179], v[184:187], v[112:115]
	v_mfma_f32_16x16x32_bf16 v[100:103], v[168:171], v[192:195], v[100:103]
	v_mfma_f32_16x16x32_bf16 v[96:99], v[176:179], v[192:195], v[96:99]
	v_mfma_f32_16x16x32_bf16 v[84:87], v[168:171], v[200:203], v[84:87]
	v_mfma_f32_16x16x32_bf16 v[80:83], v[176:179], v[200:203], v[80:83]
	v_mfma_f32_16x16x32_bf16 v[68:71], v[168:171], v[212:215], v[68:71]
	v_mfma_f32_16x16x32_bf16 v[64:67], v[176:179], v[212:215], v[64:67]
	s_barrier
	s_add_i32 s40, s62, s45
	s_mov_b32 m0, s40
	s_nop 0
	global_load_lds_dwordx4 v204, s[38:39]
	s_add_i32 m0, s40, 0x2000
	s_add_u32 s38, s38, 0x40080
	s_addc_u32 s39, s39, 0
	s_add_i32 s40, s63, s45
	global_load_lds_dwordx4 v205, s[98:99]
	s_mov_b32 m0, s40
	s_nop 0
	global_load_lds_dwordx4 v128, s[38:39]
	s_add_i32 m0, s40, 0x2000
	s_nop 0
	global_load_lds_dwordx4 v130, s[38:39]
	s_mov_b32 m0, s51
	s_nop 0
	global_load_lds_dwordx4 v204, s[100:101]
	s_cmp_lg_u32 s61, 12
	s_cbranch_scc1 .Lbal_last_11
	s_mov_b32 m0, s52
	s_nop 0
	global_load_lds_dwordx4 v205, s[100:101]
.Lbal_last_11:
	ds_read_b128 v[180:183], v153 offset:49152
	ds_read_b128 v[184:187], v153 offset:50176
	ds_read_b128 v[188:191], v153 offset:51200
	ds_read_b128 v[192:195], v153 offset:52224
	ds_read_b128 v[196:199], v153 offset:53248
	ds_read_b128 v[200:203], v153 offset:54272
	ds_read_b128 v[208:211], v153 offset:55296
	ds_read_b128 v[212:215], v153 offset:56320
	s_waitcnt vmcnt(7)
	s_waitcnt lgkmcnt(0)
	s_barrier
	s_waitcnt lgkmcnt(0)
	v_mfma_f32_16x16x32_bf16 v[60:63], v[140:143], v[180:183], v[60:63]
	v_mfma_f32_16x16x32_bf16 v[56:59], v[156:159], v[180:183], v[56:59]
	v_mfma_f32_16x16x32_bf16 v[44:47], v[140:143], v[188:191], v[44:47]
	v_mfma_f32_16x16x32_bf16 v[40:43], v[156:159], v[188:191], v[40:43]
	v_mfma_f32_16x16x32_bf16 v[28:31], v[140:143], v[196:199], v[28:31]
	v_mfma_f32_16x16x32_bf16 v[24:27], v[156:159], v[196:199], v[24:27]
	v_mfma_f32_16x16x32_bf16 v[12:15], v[140:143], v[208:211], v[12:15]
	v_mfma_f32_16x16x32_bf16 v[8:11], v[156:159], v[208:211], v[8:11]
	v_mfma_f32_16x16x32_bf16 v[60:63], v[144:147], v[184:187], v[60:63]
	v_mfma_f32_16x16x32_bf16 v[56:59], v[160:163], v[184:187], v[56:59]
	v_mfma_f32_16x16x32_bf16 v[44:47], v[144:147], v[192:195], v[44:47]
	v_mfma_f32_16x16x32_bf16 v[40:43], v[160:163], v[192:195], v[40:43]
	v_mfma_f32_16x16x32_bf16 v[28:31], v[144:147], v[200:203], v[28:31]
	v_mfma_f32_16x16x32_bf16 v[24:27], v[160:163], v[200:203], v[24:27]
	v_mfma_f32_16x16x32_bf16 v[12:15], v[144:147], v[212:215], v[12:15]
	v_mfma_f32_16x16x32_bf16 v[8:11], v[160:163], v[212:215], v[8:11]
	v_mfma_f32_16x16x32_bf16 v[52:55], v[164:167], v[180:183], v[52:55]
	v_mfma_f32_16x16x32_bf16 v[48:51], v[172:175], v[180:183], v[48:51]
	v_mfma_f32_16x16x32_bf16 v[36:39], v[164:167], v[188:191], v[36:39]
	v_mfma_f32_16x16x32_bf16 v[32:35], v[172:175], v[188:191], v[32:35]
	v_mfma_f32_16x16x32_bf16 v[20:23], v[164:167], v[196:199], v[20:23]
	v_mfma_f32_16x16x32_bf16 v[16:19], v[172:175], v[196:199], v[16:19]
	v_mfma_f32_16x16x32_bf16 v[4:7], v[164:167], v[208:211], v[4:7]
	v_mfma_f32_16x16x32_bf16 v[0:3], v[172:175], v[208:211], v[0:3]
	v_mfma_f32_16x16x32_bf16 v[52:55], v[168:171], v[184:187], v[52:55]
	v_mfma_f32_16x16x32_bf16 v[48:51], v[176:179], v[184:187], v[48:51]
	v_mfma_f32_16x16x32_bf16 v[36:39], v[168:171], v[192:195], v[36:39]
	v_mfma_f32_16x16x32_bf16 v[32:35], v[176:179], v[192:195], v[32:35]
	v_mfma_f32_16x16x32_bf16 v[20:23], v[168:171], v[200:203], v[20:23]
	v_mfma_f32_16x16x32_bf16 v[16:19], v[176:179], v[200:203], v[16:19]
	v_mfma_f32_16x16x32_bf16 v[4:7], v[168:171], v[212:215], v[4:7]
	v_mfma_f32_16x16x32_bf16 v[0:3], v[176:179], v[212:215], v[0:3]
	s_barrier
	s_add_i32 s61, s61, 2
	s_add_u32 s59, s59, 0x100
	s_addc_u32 s60, s60, 0
	s_add_u32 s36, s36, 0x100
	s_addc_u32 s37, s37, 0
	s_cmp_gt_u32 s61, 13
	s_cbranch_scc0 .LBB0_1561
	s_setprio 0
	s_and_b64 vcc, exec, s[24:25]
	s_cbranch_vccz .LBB0_1564
	s_barrier

.Lbal_first_10:
	s_add_u32 s26, s24, 0xfffc0080
	s_addc_u32 s27, s25, -1
	s_cmp_eq_u32 s54, 12
	s_cselect_b32 s29, s19, s27
	s_cselect_b32 s28, s50, s26
	s_cselect_b32 s27, s17, s53
	s_cselect_b32 s26, s51, s52
	s_add_i32 m0, s38, 0xc000
	s_nop 0
	global_load_lds_dwordx4 v138, s[24:25]
	s_add_i32 m0, s38, 0xe000
	s_nop 0
	global_load_lds_dwordx4 v136, s[24:25]
	ds_read_b128 v[144:147], v151
	ds_read_b128 v[156:159], v151 offset:1024
	ds_read_b128 v[160:163], v151 offset:2048
	ds_read_b128 v[164:167], v151 offset:3072
	ds_read_b128 v[168:171], v152
	ds_read_b128 v[172:175], v152 offset:1024
	ds_read_b128 v[176:179], v152 offset:2048
	ds_read_b128 v[180:183], v152 offset:3072
	ds_read_b128 v[184:187], v153
	ds_read_b128 v[188:191], v153 offset:1024
	ds_read_b128 v[192:195], v153 offset:2048
	ds_read_b128 v[196:199], v153 offset:3072
	ds_read_b128 v[200:203], v153 offset:4096
	ds_read_b128 v[208:211], v153 offset:5120
	ds_read_b128 v[212:215], v153 offset:6144
	ds_read_b128 v[216:219], v153 offset:7168
	s_waitcnt vmcnt(8)
	s_waitcnt lgkmcnt(0)
	s_barrier
	s_waitcnt lgkmcnt(0)
	v_mfma_f32_16x16x32_bf16 v[124:127], v[144:147], v[184:187], v[124:127]
	v_mfma_f32_16x16x32_bf16 v[120:123], v[160:163], v[184:187], v[120:123]
	v_mfma_f32_16x16x32_bf16 v[108:111], v[144:147], v[192:195], v[108:111]
	v_mfma_f32_16x16x32_bf16 v[104:107], v[160:163], v[192:195], v[104:107]
	v_mfma_f32_16x16x32_bf16 v[92:95], v[144:147], v[200:203], v[92:95]
	v_mfma_f32_16x16x32_bf16 v[88:91], v[160:163], v[200:203], v[88:91]
	v_mfma_f32_16x16x32_bf16 v[76:79], v[144:147], v[212:215], v[76:79]
	v_mfma_f32_16x16x32_bf16 v[72:75], v[160:163], v[212:215], v[72:75]
	v_mfma_f32_16x16x32_bf16 v[124:127], v[156:159], v[188:191], v[124:127]
	v_mfma_f32_16x16x32_bf16 v[120:123], v[164:167], v[188:191], v[120:123]
	v_mfma_f32_16x16x32_bf16 v[108:111], v[156:159], v[196:199], v[108:111]
	v_mfma_f32_16x16x32_bf16 v[104:107], v[164:167], v[196:199], v[104:107]
	v_mfma_f32_16x16x32_bf16 v[92:95], v[156:159], v[208:211], v[92:95]
	v_mfma_f32_16x16x32_bf16 v[88:91], v[164:167], v[208:211], v[88:91]
	v_mfma_f32_16x16x32_bf16 v[76:79], v[156:159], v[216:219], v[76:79]
	v_mfma_f32_16x16x32_bf16 v[72:75], v[164:167], v[216:219], v[72:75]
	v_mfma_f32_16x16x32_bf16 v[116:119], v[168:171], v[184:187], v[116:119]
	v_mfma_f32_16x16x32_bf16 v[112:115], v[176:179], v[184:187], v[112:115]
	v_mfma_f32_16x16x32_bf16 v[100:103], v[168:171], v[192:195], v[100:103]
	v_mfma_f32_16x16x32_bf16 v[96:99], v[176:179], v[192:195], v[96:99]
	v_mfma_f32_16x16x32_bf16 v[84:87], v[168:171], v[200:203], v[84:87]
	v_mfma_f32_16x16x32_bf16 v[80:83], v[176:179], v[200:203], v[80:83]
	v_mfma_f32_16x16x32_bf16 v[68:71], v[168:171], v[212:215], v[68:71]
	v_mfma_f32_16x16x32_bf16 v[64:67], v[176:179], v[212:215], v[64:67]
	v_mfma_f32_16x16x32_bf16 v[116:119], v[172:175], v[188:191], v[116:119]
	v_mfma_f32_16x16x32_bf16 v[112:115], v[180:183], v[188:191], v[112:115]
	v_mfma_f32_16x16x32_bf16 v[100:103], v[172:175], v[196:199], v[100:103]
	v_mfma_f32_16x16x32_bf16 v[96:99], v[180:183], v[196:199], v[96:99]
	v_mfma_f32_16x16x32_bf16 v[84:87], v[172:175], v[208:211], v[84:87]
	v_mfma_f32_16x16x32_bf16 v[80:83], v[180:183], v[208:211], v[80:83]
	v_mfma_f32_16x16x32_bf16 v[68:71], v[172:175], v[216:219], v[68:71]
	v_mfma_f32_16x16x32_bf16 v[64:67], v[180:183], v[216:219], v[64:67]
	s_barrier
	s_add_i32 s55, s47, s35
	s_mov_b32 m0, s55
	s_nop 0
	global_load_lds_dwordx4 v132, s[26:27]
	s_add_i32 m0, s55, 0x2000
	s_add_u32 s56, s26, 0x40000
	s_mov_b64 s[98:99], s[26:27]
	s_addc_u32 s57, s27, 0
	s_add_i32 s55, s48, s35
	global_load_lds_dwordx4 v128, s[26:27]
	s_mov_b32 m0, s55
	s_mov_b64 s[100:101], s[28:29]
	global_load_lds_dwordx4 v132, s[56:57]
	s_add_i32 m0, s55, 0x2000
	s_nop 0
	global_load_lds_dwordx4 v128, s[56:57]
	s_mov_b32 m0, s38
	s_nop 0
	global_load_lds_dwordx4 v134, s[28:29]
	ds_read_b128 v[184:187], v153 offset:16384
	ds_read_b128 v[188:191], v153 offset:17408
	ds_read_b128 v[192:195], v153 offset:18432
	ds_read_b128 v[196:199], v153 offset:19456
	ds_read_b128 v[200:203], v153 offset:20480
	ds_read_b128 v[208:211], v153 offset:21504
	ds_read_b128 v[212:215], v153 offset:22528
	ds_read_b128 v[216:219], v153 offset:23552
	s_waitcnt vmcnt(7)
	s_waitcnt lgkmcnt(0)
	s_barrier
	s_waitcnt lgkmcnt(0)
	v_mfma_f32_16x16x32_bf16 v[60:63], v[144:147], v[184:187], v[60:63]
	v_mfma_f32_16x16x32_bf16 v[56:59], v[160:163], v[184:187], v[56:59]
	v_mfma_f32_16x16x32_bf16 v[44:47], v[144:147], v[192:195], v[44:47]
	v_mfma_f32_16x16x32_bf16 v[40:43], v[160:163], v[192:195], v[40:43]
	v_mfma_f32_16x16x32_bf16 v[28:31], v[144:147], v[200:203], v[28:31]
	v_mfma_f32_16x16x32_bf16 v[24:27], v[160:163], v[200:203], v[24:27]
	v_mfma_f32_16x16x32_bf16 v[12:15], v[144:147], v[212:215], v[12:15]
	v_mfma_f32_16x16x32_bf16 v[8:11], v[160:163], v[212:215], v[8:11]
	v_mfma_f32_16x16x32_bf16 v[60:63], v[156:159], v[188:191], v[60:63]
	v_mfma_f32_16x16x32_bf16 v[56:59], v[164:167], v[188:191], v[56:59]
	v_mfma_f32_16x16x32_bf16 v[44:47], v[156:159], v[196:199], v[44:47]
	v_mfma_f32_16x16x32_bf16 v[40:43], v[164:167], v[196:199], v[40:43]
	v_mfma_f32_16x16x32_bf16 v[28:31], v[156:159], v[208:211], v[28:31]
	v_mfma_f32_16x16x32_bf16 v[24:27], v[164:167], v[208:211], v[24:27]
	v_mfma_f32_16x16x32_bf16 v[12:15], v[156:159], v[216:219], v[12:15]
	v_mfma_f32_16x16x32_bf16 v[8:11], v[164:167], v[216:219], v[8:11]
	v_mfma_f32_16x16x32_bf16 v[52:55], v[168:171], v[184:187], v[52:55]
	v_mfma_f32_16x16x32_bf16 v[48:51], v[176:179], v[184:187], v[48:51]
	v_mfma_f32_16x16x32_bf16 v[36:39], v[168:171], v[192:195], v[36:39]
	v_mfma_f32_16x16x32_bf16 v[32:35], v[176:179], v[192:195], v[32:35]
	v_mfma_f32_16x16x32_bf16 v[20:23], v[168:171], v[200:203], v[20:23]
	v_mfma_f32_16x16x32_bf16 v[16:19], v[176:179], v[200:203], v[16:19]
	v_mfma_f32_16x16x32_bf16 v[4:7], v[168:171], v[212:215], v[4:7]
	v_mfma_f32_16x16x32_bf16 v[0:3], v[176:179], v[212:215], v[0:3]
	v_mfma_f32_16x16x32_bf16 v[52:55], v[172:175], v[188:191], v[52:55]
	v_mfma_f32_16x16x32_bf16 v[48:51], v[180:183], v[188:191], v[48:51]
	v_mfma_f32_16x16x32_bf16 v[36:39], v[172:175], v[196:199], v[36:39]
	v_mfma_f32_16x16x32_bf16 v[32:35], v[180:183], v[196:199], v[32:35]
	v_mfma_f32_16x16x32_bf16 v[20:23], v[172:175], v[208:211], v[20:23]
	v_mfma_f32_16x16x32_bf16 v[16:19], v[180:183], v[208:211], v[16:19]
	v_mfma_f32_16x16x32_bf16 v[4:7], v[172:175], v[216:219], v[4:7]
	v_mfma_f32_16x16x32_bf16 v[0:3], v[180:183], v[216:219], v[0:3]
	s_barrier
	s_mov_b32 m0, s39
	s_nop 0
	global_load_lds_dwordx4 v130, s[28:29]
	s_add_i32 s55, 0, 0x18000
	s_add_i32 s56, 0, 0x1c000
	s_add_u32 s28, s28, 0x40000
	s_addc_u32 s29, s29, 0
	s_mov_b32 m0, s40
	s_nop 0
	global_load_lds_dwordx4 v134, s[28:29]
	s_mov_b32 m0, s41
	s_nop 0
	global_load_lds_dwordx4 v130, s[28:29]
	v_add_u32_e32 v164, s55, v149
	v_add_u32_e32 v180, s56, v149
	ds_read_b128 v[144:147], v164
	ds_read_b128 v[156:159], v164 offset:1024
	ds_read_b128 v[160:163], v164 offset:2048
	ds_read_b128 v[164:167], v164 offset:3072
	ds_read_b128 v[168:171], v180
	ds_read_b128 v[172:175], v180 offset:1024
	ds_read_b128 v[176:179], v180 offset:2048
	ds_read_b128 v[180:183], v180 offset:3072
	ds_read_b128 v[184:187], v153 offset:32768
	ds_read_b128 v[188:191], v153 offset:33792
	ds_read_b128 v[192:195], v153 offset:34816
	ds_read_b128 v[196:199], v153 offset:35840
	ds_read_b128 v[200:203], v153 offset:36864
	ds_read_b128 v[208:211], v153 offset:37888
	ds_read_b128 v[212:215], v153 offset:38912
	ds_read_b128 v[216:219], v153 offset:39936
	s_waitcnt vmcnt(8)
	s_waitcnt lgkmcnt(0)
	s_barrier
	s_waitcnt lgkmcnt(0)
	v_mfma_f32_16x16x32_bf16 v[124:127], v[144:147], v[184:187], v[124:127]
	v_mfma_f32_16x16x32_bf16 v[120:123], v[160:163], v[184:187], v[120:123]
	v_mfma_f32_16x16x32_bf16 v[108:111], v[144:147], v[192:195], v[108:111]
	v_mfma_f32_16x16x32_bf16 v[104:107], v[160:163], v[192:195], v[104:107]
	v_mfma_f32_16x16x32_bf16 v[92:95], v[144:147], v[200:203], v[92:95]
	v_mfma_f32_16x16x32_bf16 v[88:91], v[160:163], v[200:203], v[88:91]
	v_mfma_f32_16x16x32_bf16 v[76:79], v[144:147], v[212:215], v[76:79]
	v_mfma_f32_16x16x32_bf16 v[72:75], v[160:163], v[212:215], v[72:75]
	v_mfma_f32_16x16x32_bf16 v[124:127], v[156:159], v[188:191], v[124:127]
	v_mfma_f32_16x16x32_bf16 v[120:123], v[164:167], v[188:191], v[120:123]
	v_mfma_f32_16x16x32_bf16 v[108:111], v[156:159], v[196:199], v[108:111]
	v_mfma_f32_16x16x32_bf16 v[104:107], v[164:167], v[196:199], v[104:107]
	v_mfma_f32_16x16x32_bf16 v[92:95], v[156:159], v[208:211], v[92:95]
	v_mfma_f32_16x16x32_bf16 v[88:91], v[164:167], v[208:211], v[88:91]
	v_mfma_f32_16x16x32_bf16 v[76:79], v[156:159], v[216:219], v[76:79]
	v_mfma_f32_16x16x32_bf16 v[72:75], v[164:167], v[216:219], v[72:75]
	v_mfma_f32_16x16x32_bf16 v[116:119], v[168:171], v[184:187], v[116:119]
	v_mfma_f32_16x16x32_bf16 v[112:115], v[176:179], v[184:187], v[112:115]
	v_mfma_f32_16x16x32_bf16 v[100:103], v[168:171], v[192:195], v[100:103]
	v_mfma_f32_16x16x32_bf16 v[96:99], v[176:179], v[192:195], v[96:99]
	v_mfma_f32_16x16x32_bf16 v[84:87], v[168:171], v[200:203], v[84:87]
	v_mfma_f32_16x16x32_bf16 v[80:83], v[176:179], v[200:203], v[80:83]
	v_mfma_f32_16x16x32_bf16 v[68:71], v[168:171], v[212:215], v[68:71]
	v_mfma_f32_16x16x32_bf16 v[64:67], v[176:179], v[212:215], v[64:67]
	v_mfma_f32_16x16x32_bf16 v[116:119], v[172:175], v[188:191], v[116:119]
	v_mfma_f32_16x16x32_bf16 v[112:115], v[180:183], v[188:191], v[112:115]
	v_mfma_f32_16x16x32_bf16 v[100:103], v[172:175], v[196:199], v[100:103]
	v_mfma_f32_16x16x32_bf16 v[96:99], v[180:183], v[196:199], v[96:99]
	v_mfma_f32_16x16x32_bf16 v[84:87], v[172:175], v[208:211], v[84:87]
	v_mfma_f32_16x16x32_bf16 v[80:83], v[180:183], v[208:211], v[80:83]
	v_mfma_f32_16x16x32_bf16 v[68:71], v[172:175], v[216:219], v[68:71]
	v_mfma_f32_16x16x32_bf16 v[64:67], v[180:183], v[216:219], v[64:67]
	s_barrier
	s_add_i32 s28, s55, s35
	s_mov_b32 m0, s28
	s_nop 0
	global_load_lds_dwordx4 v220, s[26:27]
	s_add_i32 m0, s28, 0x2000
	s_add_u32 s26, s26, 0x40080
	s_addc_u32 s27, s27, 0
	s_add_i32 s28, s56, s35
	global_load_lds_dwordx4 v204, s[98:99]
	s_mov_b32 m0, s28
	s_nop 0
	global_load_lds_dwordx4 v132, s[26:27]
	s_add_i32 m0, s28, 0x2000
	s_nop 0
	global_load_lds_dwordx4 v128, s[26:27]
	s_mov_b32 m0, s45
	s_nop 0
	global_load_lds_dwordx4 v221, s[100:101]
	s_cmp_lg_u32 s54, 12
	s_cbranch_scc1 .Lbal_last_10
	s_mov_b32 m0, s46
	s_nop 0
	global_load_lds_dwordx4 v205, s[100:101]
.Lbal_last_10:
	ds_read_b128 v[184:187], v153 offset:49152
	ds_read_b128 v[188:191], v153 offset:50176
	ds_read_b128 v[192:195], v153 offset:51200
	ds_read_b128 v[196:199], v153 offset:52224
	ds_read_b128 v[200:203], v153 offset:53248
	ds_read_b128 v[208:211], v153 offset:54272
	ds_read_b128 v[212:215], v153 offset:55296
	ds_read_b128 v[216:219], v153 offset:56320
	s_waitcnt vmcnt(7)
	s_waitcnt lgkmcnt(0)
	s_barrier
	s_waitcnt lgkmcnt(0)
	v_mfma_f32_16x16x32_bf16 v[60:63], v[144:147], v[184:187], v[60:63]
	v_mfma_f32_16x16x32_bf16 v[56:59], v[160:163], v[184:187], v[56:59]
	v_mfma_f32_16x16x32_bf16 v[44:47], v[144:147], v[192:195], v[44:47]
	v_mfma_f32_16x16x32_bf16 v[40:43], v[160:163], v[192:195], v[40:43]
	v_mfma_f32_16x16x32_bf16 v[28:31], v[144:147], v[200:203], v[28:31]
	v_mfma_f32_16x16x32_bf16 v[24:27], v[160:163], v[200:203], v[24:27]
	v_mfma_f32_16x16x32_bf16 v[12:15], v[144:147], v[212:215], v[12:15]
	v_mfma_f32_16x16x32_bf16 v[8:11], v[160:163], v[212:215], v[8:11]
	v_mfma_f32_16x16x32_bf16 v[60:63], v[156:159], v[188:191], v[60:63]
	v_mfma_f32_16x16x32_bf16 v[56:59], v[164:167], v[188:191], v[56:59]
	v_mfma_f32_16x16x32_bf16 v[44:47], v[156:159], v[196:199], v[44:47]
	v_mfma_f32_16x16x32_bf16 v[40:43], v[164:167], v[196:199], v[40:43]
	v_mfma_f32_16x16x32_bf16 v[28:31], v[156:159], v[208:211], v[28:31]
	v_mfma_f32_16x16x32_bf16 v[24:27], v[164:167], v[208:211], v[24:27]
	v_mfma_f32_16x16x32_bf16 v[12:15], v[156:159], v[216:219], v[12:15]
	v_mfma_f32_16x16x32_bf16 v[8:11], v[164:167], v[216:219], v[8:11]
	v_mfma_f32_16x16x32_bf16 v[52:55], v[168:171], v[184:187], v[52:55]
	v_mfma_f32_16x16x32_bf16 v[48:51], v[176:179], v[184:187], v[48:51]
	v_mfma_f32_16x16x32_bf16 v[36:39], v[168:171], v[192:195], v[36:39]
	v_mfma_f32_16x16x32_bf16 v[32:35], v[176:179], v[192:195], v[32:35]
	v_mfma_f32_16x16x32_bf16 v[20:23], v[168:171], v[200:203], v[20:23]
	v_mfma_f32_16x16x32_bf16 v[16:19], v[176:179], v[200:203], v[16:19]
	v_mfma_f32_16x16x32_bf16 v[4:7], v[168:171], v[212:215], v[4:7]
	v_mfma_f32_16x16x32_bf16 v[0:3], v[176:179], v[212:215], v[0:3]
	v_mfma_f32_16x16x32_bf16 v[52:55], v[172:175], v[188:191], v[52:55]
	v_mfma_f32_16x16x32_bf16 v[48:51], v[180:183], v[188:191], v[48:51]
	v_mfma_f32_16x16x32_bf16 v[36:39], v[172:175], v[196:199], v[36:39]
	v_mfma_f32_16x16x32_bf16 v[32:35], v[180:183], v[196:199], v[32:35]
	v_mfma_f32_16x16x32_bf16 v[20:23], v[172:175], v[208:211], v[20:23]
	v_mfma_f32_16x16x32_bf16 v[16:19], v[180:183], v[208:211], v[16:19]
	v_mfma_f32_16x16x32_bf16 v[4:7], v[172:175], v[216:219], v[4:7]
	v_mfma_f32_16x16x32_bf16 v[0:3], v[180:183], v[216:219], v[0:3]
	s_barrier
	s_add_i32 s54, s54, 2
	s_add_u32 s52, s52, 0x100
	s_addc_u32 s53, s53, 0
	s_add_u32 s24, s24, 0x100
	s_addc_u32 s25, s25, 0
	s_cmp_gt_u32 s54, 13
	s_cbranch_scc0 .LBB0_1646
	s_setprio 0
	s_and_b64 vcc, exec, s[14:15]
	s_cbranch_vccz .LBB0_1649
	s_barrier
